# prompt attention loops: one static s_setprio 1 for waves 4-7 (the non-sleeping half) for the whole tile loop, reset at loop exit
# speedup vs baseline: 1.0051x; 1.0051x over previous
; __device__ __forceinline__ unsigned cvtpk(float lo, float hi) { unsigned r; asm volatile("v_cvt_pk_bf16_f32 %0, %1, %2" : "=v"(r) : "v"(lo), "v"(hi)); return r; }
; __device__ __forceinline__ float bf2f(short s) { return __uint_as_float(((unsigned)(unsigned short)s) << 16); }
; __device__ __forceinline__ float silu_fast(float g) { return g * __builtin_amdgcn_rcpf(1.f + __builtin_amdgcn_exp2f(-g * LOG2E)); }
; __device__ __forceinline__ int crow(int r, int hi) { return (r & 3) + 8 * (r >> 2) + 4 * hi; }
; __device__ __forceinline__ bf16x8 tobf8(f32x8 x) { u32x4 w = {cvtpk(x[0], x[1]), cvtpk(x[2], x[3]), cvtpk(x[4], x[5]), cvtpk(x[6], x[7])}; return *reinterpret_cast<bf16x8*>(&w); }
; template <int MODE, bool SAMPLE>
; __device__ __forceinline__ void attn_unit(const Params& p, char* lds, int b, int h, int qb) {
;     ...
;     if (wact && var < 1) {
;         bf16_t* MIX = (bf16_t*)(p.ws + (var == 0 ? WS_MIX : WS_ACT));
;         const size_t rbase = SAMPLE ? (size_t)(MP + b * TS) : (size_t)(b * SEQ + qb * 256 + wid * 32);
;         constexpr int NIT = SAMPLE ? 4 : 8; const int er = lane >> 4, ec = (lane & 15) * 8;
;         float rli[16];
;         if (MODE == 0) { if (hi == 0) wsc[32 + r32] = l_reg; asm volatile("s_waitcnt lgkmcnt(0)" ::: "memory");
; #pragma unroll
;             for (int r = 0; r < 16; ++r) rli[r] = __builtin_amdgcn_rcpf(wsc[32 + crow(r, hi)]); }
; #pragma unroll
;         for (int r = 0; r < 16; ++r) { const int orow = crow(r, hi);
;             if (!SAMPLE || orow < TS) {
; #pragma unroll
;                 for (int d0 = 0; d0 < 4; ++d0) { float ov = o[d0][r]; if (MODE == 0) ov *= rli[r];
;                     const unsigned pk = cvtpk(ov, 0.f); *(bf16_t*)(Qs + orow * 256 + (d0 * 32 + r32) * 2) = (bf16_t)(pk & 0xffffu); } } }
;         asm volatile("s_waitcnt lgkmcnt(0)" ::: "memory");
;         bf16x8 gt[NIT];
; #pragma unroll
;         for (int it = 0; it < NIT; ++it) gt[it] = __builtin_nontemporal_load((const bf16x8*)(P1q + 24 * HB + (rbase + it * 4 + er) * 128 + ec));
; #pragma unroll
;         for (int it = 0; it < NIT; ++it) { const int row = it * 4 + er; const bf16x8 mx = *(const bf16x8*)(Qs + row * 256 + ec * 2); f32x8 y;
; #pragma unroll
;             for (int i = 0; i < 8; ++i) y[i] = bf2f(mx[i]) * silu_fast(bf2f(gt[it][i]));
;             *(bf16x8*)(MIX + (rbase + row) * DM + MODE * 1024 + h * HD + ec) = tobf8(y); }
.LBB0_650:
	s_waitcnt vmcnt(0)
	s_setprio 0
	v_add3_u32 v64, s12, v193, v192
	v_cvt_pk_bf16_f32 v48, v48, v129
	ds_write_b16 v64, v48
	v_cvt_pk_bf16_f32 v32, v32, v129
	ds_write_b16 v64, v32 offset:64
	v_cvt_pk_bf16_f32 v16, v16, v129
	ds_write_b16 v64, v16 offset:128
	v_cvt_pk_bf16_f32 v0, v0, v129
	s_nop 2
	ds_write_b16 v64, v0 offset:192
	v_cvt_pk_bf16_f32 v0, v49, v129
	ds_write_b16 v64, v0 offset:256
	v_cvt_pk_bf16_f32 v0, v33, v129
	ds_write_b16 v64, v0 offset:320
	v_cvt_pk_bf16_f32 v0, v17, v129
	ds_write_b16 v64, v0 offset:384
	v_cvt_pk_bf16_f32 v0, v1, v129
	ds_write_b16 v64, v0 offset:448
	v_cvt_pk_bf16_f32 v0, v50, v129
	ds_write_b16 v64, v0 offset:512
	v_cvt_pk_bf16_f32 v0, v34, v129
	ds_write_b16 v64, v0 offset:576
	v_cvt_pk_bf16_f32 v0, v18, v129
	ds_write_b16 v64, v0 offset:640
	v_cvt_pk_bf16_f32 v0, v2, v129
	ds_write_b16 v64, v0 offset:704
	v_cvt_pk_bf16_f32 v0, v51, v129
	ds_write_b16 v64, v0 offset:768
	v_cvt_pk_bf16_f32 v0, v35, v129
	ds_write_b16 v64, v0 offset:832
	v_cvt_pk_bf16_f32 v0, v19, v129
	ds_write_b16 v64, v0 offset:896
	v_cvt_pk_bf16_f32 v0, v3, v129
	ds_write_b16 v64, v0 offset:960
	v_cvt_pk_bf16_f32 v0, v52, v129
	ds_write_b16 v64, v0 offset:2048
	v_cvt_pk_bf16_f32 v0, v36, v129
	ds_write_b16 v64, v0 offset:2112
	v_cvt_pk_bf16_f32 v0, v20, v129
	ds_write_b16 v64, v0 offset:2176
	v_cvt_pk_bf16_f32 v0, v4, v129
	ds_write_b16 v64, v0 offset:2240
	v_cvt_pk_bf16_f32 v0, v53, v129
	ds_write_b16 v64, v0 offset:2304
	v_cvt_pk_bf16_f32 v0, v37, v129
	ds_write_b16 v64, v0 offset:2368
	v_cvt_pk_bf16_f32 v0, v21, v129
	ds_write_b16 v64, v0 offset:2432
	v_cvt_pk_bf16_f32 v0, v5, v129
	ds_write_b16 v64, v0 offset:2496
	v_cvt_pk_bf16_f32 v0, v54, v129
	ds_write_b16 v64, v0 offset:2560
	v_cvt_pk_bf16_f32 v0, v38, v129
	ds_write_b16 v64, v0 offset:2624
	v_cvt_pk_bf16_f32 v0, v22, v129
	ds_write_b16 v64, v0 offset:2688
	v_cvt_pk_bf16_f32 v0, v6, v129
	ds_write_b16 v64, v0 offset:2752
	v_cvt_pk_bf16_f32 v0, v55, v129
	ds_write_b16 v64, v0 offset:2816
	v_cvt_pk_bf16_f32 v0, v39, v129
	ds_write_b16 v64, v0 offset:2880
	v_cvt_pk_bf16_f32 v0, v23, v129
	ds_write_b16 v64, v0 offset:2944
	v_cvt_pk_bf16_f32 v0, v7, v129
	ds_write_b16 v64, v0 offset:3008
	v_cvt_pk_bf16_f32 v0, v56, v129
	ds_write_b16 v64, v0 offset:4096
	v_cvt_pk_bf16_f32 v0, v40, v129
	ds_write_b16 v64, v0 offset:4160
	v_cvt_pk_bf16_f32 v0, v24, v129
	ds_write_b16 v64, v0 offset:4224
	v_cvt_pk_bf16_f32 v0, v8, v129
	ds_write_b16 v64, v0 offset:4288
	v_cvt_pk_bf16_f32 v0, v57, v129
	ds_write_b16 v64, v0 offset:4352
	v_cvt_pk_bf16_f32 v0, v41, v129
	ds_write_b16 v64, v0 offset:4416
	v_cvt_pk_bf16_f32 v0, v25, v129
	ds_write_b16 v64, v0 offset:4480
	v_cvt_pk_bf16_f32 v0, v9, v129
	ds_write_b16 v64, v0 offset:4544
	v_cvt_pk_bf16_f32 v0, v58, v129
	ds_write_b16 v64, v0 offset:4608
	v_cvt_pk_bf16_f32 v0, v42, v129
	ds_write_b16 v64, v0 offset:4672
	v_cvt_pk_bf16_f32 v0, v26, v129
	ds_write_b16 v64, v0 offset:4736
	v_cvt_pk_bf16_f32 v0, v10, v129
	ds_write_b16 v64, v0 offset:4800
	v_cvt_pk_bf16_f32 v0, v59, v129
	ds_write_b16 v64, v0 offset:4864
	v_cvt_pk_bf16_f32 v0, v43, v129
	ds_write_b16 v64, v0 offset:4928
	v_cvt_pk_bf16_f32 v0, v27, v129
	ds_write_b16 v64, v0 offset:4992
	v_cvt_pk_bf16_f32 v0, v11, v129
	ds_write_b16 v64, v0 offset:5056
	v_cvt_pk_bf16_f32 v0, v60, v129
	ds_write_b16 v64, v0 offset:6144
	v_cvt_pk_bf16_f32 v0, v44, v129
	ds_write_b16 v64, v0 offset:6208
	v_cvt_pk_bf16_f32 v0, v28, v129
	ds_write_b16 v64, v0 offset:6272
	v_cvt_pk_bf16_f32 v0, v12, v129
	ds_write_b16 v64, v0 offset:6336
	v_cvt_pk_bf16_f32 v0, v61, v129
	ds_write_b16 v64, v0 offset:6400
	v_cvt_pk_bf16_f32 v0, v45, v129
	ds_write_b16 v64, v0 offset:6464
	v_cvt_pk_bf16_f32 v0, v29, v129
	ds_write_b16 v64, v0 offset:6528
	v_cvt_pk_bf16_f32 v0, v13, v129
	ds_write_b16 v64, v0 offset:6592
	v_cvt_pk_bf16_f32 v0, v62, v129
	ds_write_b16 v64, v0 offset:6656
	v_cvt_pk_bf16_f32 v0, v46, v129
	ds_write_b16 v64, v0 offset:6720
	v_cvt_pk_bf16_f32 v0, v30, v129
	ds_write_b16 v64, v0 offset:6784
	v_cvt_pk_bf16_f32 v0, v14, v129
	ds_write_b16 v64, v0 offset:6848
	v_cvt_pk_bf16_f32 v0, v63, v129
	ds_write_b16 v64, v0 offset:6912
	v_cvt_pk_bf16_f32 v0, v47, v129
	ds_write_b16 v64, v0 offset:6976
	v_cvt_pk_bf16_f32 v0, v31, v129
	ds_write_b16 v64, v0 offset:7040
	v_cvt_pk_bf16_f32 v0, v15, v129
	v_mov_b32_e32 v145, v129
	ds_write_b16 v64, v0 offset:7104
	v_or_b32_e32 v34, s11, v130
	v_lshl_add_u64 v[0:1], s[82:83], 0, v[144:145]
	s_mov_b64 s[0:1], 0x10200000
	v_mov_b32_e32 v35, v129
	v_lshl_add_u64 v[4:5], v[0:1], 0, s[0:1]
	v_lshlrev_b64 v[0:1], 8, v[34:35]
	s_waitcnt lgkmcnt(0)
	v_lshl_add_u64 v[0:1], v[4:5], 0, v[0:1]
	global_load_dwordx4 v[0:3], v[0:1], off nt
	v_or_b32_e32 v6, 4, v34
	v_mov_b32_e32 v7, v129
	v_lshlrev_b64 v[6:7], 8, v[6:7]
	v_lshl_add_u64 v[8:9], v[4:5], 0, v[6:7]
	v_or_b32_e32 v6, 8, v34
	v_mov_b32_e32 v7, v129
	v_lshlrev_b64 v[6:7], 8, v[6:7]
	v_lshl_add_u64 v[10:11], v[4:5], 0, v[6:7]
	v_or_b32_e32 v6, 12, v34
	v_mov_b32_e32 v7, v129
	v_lshlrev_b64 v[6:7], 8, v[6:7]
	global_load_dwordx4 v[22:25], v[8:9], off nt
	v_lshl_add_u64 v[12:13], v[4:5], 0, v[6:7]
	v_or_b32_e32 v6, 16, v34
	v_mov_b32_e32 v7, v129
	v_lshlrev_b64 v[6:7], 8, v[6:7]
	v_lshl_add_u64 v[14:15], v[4:5], 0, v[6:7]
	v_or_b32_e32 v6, 20, v34
	v_mov_b32_e32 v7, v129
	v_lshlrev_b64 v[6:7], 8, v[6:7]
	v_lshl_add_u64 v[30:31], v[4:5], 0, v[6:7]
	v_or_b32_e32 v6, 24, v34
	v_mov_b32_e32 v7, v129
	v_lshlrev_b64 v[6:7], 8, v[6:7]
	v_lshl_add_u64 v[32:33], v[4:5], 0, v[6:7]
	v_or_b32_e32 v6, 28, v34
	v_mov_b32_e32 v7, v129
	v_lshlrev_b64 v[6:7], 8, v[6:7]
	v_add_u32_e32 v20, s12, v132
	v_lshl_add_u64 v[36:37], v[4:5], 0, v[6:7]
	v_add_u32_e32 v4, v20, v194
	ds_read_b128 v[4:7], v4
	v_lshlrev_b64 v[34:35], 12, v[34:35]
	v_lshl_add_u64 v[34:35], s[92:93], 0, v[34:35]
	s_lshl_b32 s4, s10, 1
	v_lshl_add_u64 v[34:35], v[34:35], 0, s[4:5]
	s_waitcnt lgkmcnt(0)
; __device__ __forceinline__ float bf2f(short s) { return __uint_as_float(((unsigned)(unsigned short)s) << 16); }
; __device__ __forceinline__ float silu_fast(float g) { return g * __builtin_amdgcn_rcpf(1.f + __builtin_amdgcn_exp2f(-g * LOG2E)); }
; __device__ __forceinline__ bf16x8 tobf8(f32x8 x) { u32x4 w = {cvtpk(x[0], x[1]), cvtpk(x[2], x[3]), cvtpk(x[4], x[5]), cvtpk(x[6], x[7])}; return *reinterpret_cast<bf16x8*>(&w); }
; template <int MODE, bool SAMPLE>
; __device__ __forceinline__ void attn_unit(const Params& p, char* lds, int b, int h, int qb) {
;     ...
;         for (int it = 0; it < NIT; ++it) gt[it] = __builtin_nontemporal_load((const bf16x8*)(P1q + 24 * HB + (rbase + it * 4 + er) * 128 + ec));
; #pragma unroll
;         for (int it = 0; it < NIT; ++it) { const int row = it * 4 + er; const bf16x8 mx = *(const bf16x8*)(Qs + row * 256 + ec * 2); f32x8 y;
; #pragma unroll
;             for (int i = 0; i < 8; ++i) y[i] = bf2f(mx[i]) * silu_fast(bf2f(gt[it][i]));
;             *(bf16x8*)(MIX + (rbase + row) * DM + MODE * 1024 + h * HD + ec) = tobf8(y); }
	v_lshlrev_b32_e32 v17, 16, v4
	v_and_b32_e32 v4, 0xffff0000, v4
	v_lshl_add_u64 v[34:35], v[34:35], 0, v[144:145]
	v_add_co_u32_e32 v34, vcc, s8, v34
	v_readlane_b32 s0, v253, 9
	s_nop 0
	v_addc_co_u32_e32 v35, vcc, 0, v35, vcc
	s_add_i32 s9, s9, s0
	s_cmpk_gt_i32 s9, 0xff
	v_readlane_b32 s1, v253, 10
	s_waitcnt vmcnt(1)
	v_lshlrev_b32_e32 v8, 16, v0
	v_and_b32_e32 v0, 0xffff0000, v0
	v_mul_f32_e32 v16, 0xbfb8aa3b, v0
	v_exp_f32_e32 v16, v16
	v_mul_f32_e32 v9, 0xbfb8aa3b, v8
	v_exp_f32_e32 v9, v9
	v_add_f32_e32 v16, 1.0, v16
	v_rcp_f32_e32 v16, v16
	v_add_f32_e32 v9, 1.0, v9
	v_rcp_f32_e32 v9, v9
	v_mul_f32_e32 v0, v16, v0
	v_mul_f32_e32 v38, v0, v4
	v_lshlrev_b32_e32 v0, 16, v1
	v_mul_f32_e32 v8, v9, v8
	v_mul_f32_e32 v4, 0xbfb8aa3b, v0
	v_and_b32_e32 v1, 0xffff0000, v1
	v_mul_f32_e32 v21, v8, v17
	v_exp_f32_e32 v4, v4
	v_mul_f32_e32 v8, 0xbfb8aa3b, v1
	v_exp_f32_e32 v8, v8
	v_lshlrev_b32_e32 v9, 16, v5
	v_add_f32_e32 v4, 1.0, v4
	v_rcp_f32_e32 v4, v4
	v_add_f32_e32 v8, 1.0, v8
	v_rcp_f32_e32 v8, v8
	v_mul_f32_e32 v0, v4, v0
	v_mul_f32_e32 v39, v0, v9
	v_and_b32_e32 v0, 0xffff0000, v5
	v_mul_f32_e32 v1, v8, v1
	v_mul_f32_e32 v40, v1, v0
	v_lshlrev_b32_e32 v0, 16, v2
	v_mul_f32_e32 v1, 0xbfb8aa3b, v0
	v_and_b32_e32 v2, 0xffff0000, v2
	v_exp_f32_e32 v1, v1
	v_mul_f32_e32 v4, 0xbfb8aa3b, v2
	v_exp_f32_e32 v4, v4
	v_lshlrev_b32_e32 v5, 16, v6
	v_add_f32_e32 v1, 1.0, v1
	v_rcp_f32_e32 v1, v1
	v_add_f32_e32 v4, 1.0, v4
	v_rcp_f32_e32 v4, v4
	v_mul_f32_e32 v0, v1, v0
	v_mul_f32_e32 v41, v0, v5
	v_and_b32_e32 v0, 0xffff0000, v6
	v_mul_f32_e32 v1, v4, v2
	v_mul_f32_e32 v42, v1, v0
	v_lshlrev_b32_e32 v0, 16, v3
	v_mul_f32_e32 v1, 0xbfb8aa3b, v0
	v_and_b32_e32 v2, 0xffff0000, v3
	v_exp_f32_e32 v1, v1
	v_mul_f32_e32 v3, 0xbfb8aa3b, v2
	v_exp_f32_e32 v3, v3
	v_lshlrev_b32_e32 v4, 16, v7
	v_add_f32_e32 v1, 1.0, v1
	v_rcp_f32_e32 v1, v1
	v_add_f32_e32 v3, 1.0, v3
	v_rcp_f32_e32 v3, v3
	v_mul_f32_e32 v0, v1, v0
	v_mul_f32_e32 v43, v0, v4
	v_and_b32_e32 v0, 0xffff0000, v7
	v_mul_f32_e32 v1, v3, v2
	v_mul_f32_e32 v44, v1, v0
	global_load_dwordx4 v[26:29], v[10:11], off nt
	global_load_dwordx4 v[16:19], v[12:13], off nt
	s_nop 0
	global_load_dwordx4 v[12:15], v[14:15], off nt
	s_nop 0
	global_load_dwordx4 v[8:11], v[30:31], off nt
	global_load_dwordx4 v[4:7], v[32:33], off nt
	global_load_dwordx4 v[0:3], v[36:37], off nt
	v_cvt_pk_bf16_f32 v30, v21, v38
	v_cvt_pk_bf16_f32 v31, v39, v40
	v_cvt_pk_bf16_f32 v32, v41, v42
	v_cvt_pk_bf16_f32 v33, v43, v44
	v_add_u32_e32 v21, v20, v195
	global_store_dwordx4 v[34:35], v[30:33], off offset:2048
	ds_read_b128 v[30:33], v21
	s_waitcnt vmcnt(7)
	v_lshlrev_b32_e32 v21, 16, v22
	v_and_b32_e32 v22, 0xffff0000, v22
	v_mul_f32_e32 v35, 0xbfb8aa3b, v22
	v_exp_f32_e32 v35, v35
	v_mul_f32_e32 v34, 0xbfb8aa3b, v21
	v_exp_f32_e32 v34, v34
	s_waitcnt lgkmcnt(0)
	v_lshlrev_b32_e32 v36, 16, v30
	v_add_f32_e32 v35, 1.0, v35
	v_rcp_f32_e32 v35, v35
	v_and_b32_e32 v30, 0xffff0000, v30
	v_add_f32_e32 v34, 1.0, v34
	v_rcp_f32_e32 v34, v34
	v_mul_f32_e32 v22, v35, v22
	v_mul_f32_e32 v22, v22, v30
	v_lshlrev_b32_e32 v30, 16, v23
	v_and_b32_e32 v23, 0xffff0000, v23
	v_mul_f32_e32 v35, 0xbfb8aa3b, v23
	v_exp_f32_e32 v35, v35
	v_mul_f32_e32 v21, v34, v21
	v_mul_f32_e32 v34, 0xbfb8aa3b, v30
	v_exp_f32_e32 v34, v34
	v_add_f32_e32 v35, 1.0, v35
	v_rcp_f32_e32 v35, v35
	v_mul_f32_e32 v21, v21, v36
	v_add_f32_e32 v34, 1.0, v34
	v_lshlrev_b32_e32 v36, 16, v31
	v_and_b32_e32 v31, 0xffff0000, v31
	v_mul_f32_e32 v23, v35, v23
	v_rcp_f32_e32 v34, v34
	v_mul_f32_e32 v23, v23, v31
	v_lshlrev_b32_e32 v31, 16, v24
	v_and_b32_e32 v24, 0xffff0000, v24
	v_mul_f32_e32 v35, 0xbfb8aa3b, v24
	v_exp_f32_e32 v35, v35
	v_mul_f32_e32 v30, v34, v30
	v_mul_f32_e32 v34, 0xbfb8aa3b, v31
	v_exp_f32_e32 v34, v34
	v_add_f32_e32 v35, 1.0, v35
	v_rcp_f32_e32 v35, v35
	v_mul_f32_e32 v30, v30, v36
	v_add_f32_e32 v34, 1.0, v34
	v_rcp_f32_e32 v34, v34
	v_lshlrev_b32_e32 v36, 16, v32
	v_and_b32_e32 v32, 0xffff0000, v32
	v_mul_f32_e32 v24, v35, v24
	v_mul_f32_e32 v24, v24, v32
	v_lshlrev_b32_e32 v32, 16, v25
	v_and_b32_e32 v25, 0xffff0000, v25
	v_mul_f32_e32 v35, 0xbfb8aa3b, v25
	v_mul_f32_e32 v31, v34, v31
	v_mul_f32_e32 v34, 0xbfb8aa3b, v32
	v_exp_f32_e32 v35, v35
	v_exp_f32_e32 v34, v34
	v_mul_f32_e32 v31, v31, v36
	v_cvt_pk_bf16_f32 v22, v21, v22
	v_add_f32_e32 v35, 1.0, v35
	v_add_f32_e32 v34, 1.0, v34
	v_rcp_f32_e32 v35, v35
	v_cvt_pk_bf16_f32 v23, v30, v23
	v_cvt_pk_bf16_f32 v24, v31, v24
	v_or_b32_e32 v30, s11, v136
	v_mov_b32_e32 v31, v129
	v_rcp_f32_e32 v34, v34
	v_lshlrev_b64 v[30:31], 12, v[30:31]
	v_lshl_add_u64 v[30:31], s[92:93], 0, v[30:31]
	v_lshl_add_u64 v[30:31], v[30:31], 0, s[4:5]
	v_lshlrev_b32_e32 v36, 16, v33
	v_and_b32_e32 v33, 0xffff0000, v33
	v_mul_f32_e32 v25, v35, v25
	v_lshl_add_u64 v[30:31], v[30:31], 0, v[144:145]
	v_mul_f32_e32 v32, v34, v32
	v_mul_f32_e32 v25, v25, v33
	v_add_co_u32_e32 v30, vcc, s8, v30
	v_mul_f32_e32 v32, v32, v36
	v_cvt_pk_bf16_f32 v25, v32, v25
	s_nop 0
	v_addc_co_u32_e32 v31, vcc, 0, v31, vcc
	v_add_u32_e32 v21, v20, v196
	global_store_dwordx4 v[30:31], v[22:25], off offset:2048
	ds_read_b128 v[22:25], v21
	s_waitcnt vmcnt(7)
	v_lshlrev_b32_e32 v21, 16, v26
	v_and_b32_e32 v26, 0xffff0000, v26
	v_mul_f32_e32 v31, 0xbfb8aa3b, v26
	v_exp_f32_e32 v31, v31
	v_mul_f32_e32 v30, 0xbfb8aa3b, v21
	v_exp_f32_e32 v30, v30
	s_waitcnt lgkmcnt(0)
; __device__ __forceinline__ float bf2f(short s) { return __uint_as_float(((unsigned)(unsigned short)s) << 16); }
; __device__ __forceinline__ float silu_fast(float g) { return g * __builtin_amdgcn_rcpf(1.f + __builtin_amdgcn_exp2f(-g * LOG2E)); }
; __device__ __forceinline__ bf16x8 tobf8(f32x8 x) { u32x4 w = {cvtpk(x[0], x[1]), cvtpk(x[2], x[3]), cvtpk(x[4], x[5]), cvtpk(x[6], x[7])}; return *reinterpret_cast<bf16x8*>(&w); }
; template <int MODE, bool SAMPLE>
; __device__ __forceinline__ void attn_unit(const Params& p, char* lds, int b, int h, int qb) {
;     ...
;         for (int it = 0; it < NIT; ++it) { const int row = it * 4 + er; const bf16x8 mx = *(const bf16x8*)(Qs + row * 256 + ec * 2); f32x8 y;
; #pragma unroll
;             for (int i = 0; i < 8; ++i) y[i] = bf2f(mx[i]) * silu_fast(bf2f(gt[it][i]));
;             *(bf16x8*)(MIX + (rbase + row) * DM + MODE * 1024 + h * HD + ec) = tobf8(y); }
	v_lshlrev_b32_e32 v32, 16, v22
	v_add_f32_e32 v31, 1.0, v31
	v_rcp_f32_e32 v31, v31
	v_and_b32_e32 v22, 0xffff0000, v22
	v_add_f32_e32 v30, 1.0, v30
	v_rcp_f32_e32 v30, v30
	v_mul_f32_e32 v26, v31, v26
	v_mul_f32_e32 v22, v26, v22
	v_lshlrev_b32_e32 v26, 16, v27
	v_and_b32_e32 v27, 0xffff0000, v27
	v_mul_f32_e32 v31, 0xbfb8aa3b, v27
	v_exp_f32_e32 v31, v31
	v_mul_f32_e32 v21, v30, v21
	v_mul_f32_e32 v30, 0xbfb8aa3b, v26
	v_exp_f32_e32 v30, v30
	v_add_f32_e32 v31, 1.0, v31
	v_rcp_f32_e32 v31, v31
	v_mul_f32_e32 v21, v21, v32
	v_add_f32_e32 v30, 1.0, v30
	v_lshlrev_b32_e32 v32, 16, v23
	v_and_b32_e32 v23, 0xffff0000, v23
	v_mul_f32_e32 v27, v31, v27
	v_rcp_f32_e32 v30, v30
	v_mul_f32_e32 v23, v27, v23
	v_lshlrev_b32_e32 v27, 16, v28
	v_and_b32_e32 v28, 0xffff0000, v28
	v_mul_f32_e32 v31, 0xbfb8aa3b, v28
	v_exp_f32_e32 v31, v31
	v_mul_f32_e32 v26, v30, v26
	v_mul_f32_e32 v30, 0xbfb8aa3b, v27
	v_exp_f32_e32 v30, v30
	v_add_f32_e32 v31, 1.0, v31
	v_rcp_f32_e32 v31, v31
	v_mul_f32_e32 v26, v26, v32
	v_add_f32_e32 v30, 1.0, v30
	v_rcp_f32_e32 v30, v30
	v_lshlrev_b32_e32 v32, 16, v24
	v_and_b32_e32 v24, 0xffff0000, v24
	v_mul_f32_e32 v28, v31, v28
	v_mul_f32_e32 v24, v28, v24
	v_lshlrev_b32_e32 v28, 16, v29
	v_and_b32_e32 v29, 0xffff0000, v29
	v_mul_f32_e32 v31, 0xbfb8aa3b, v29
	v_mul_f32_e32 v27, v30, v27
	v_mul_f32_e32 v30, 0xbfb8aa3b, v28
	v_exp_f32_e32 v31, v31
	v_exp_f32_e32 v30, v30
	v_mul_f32_e32 v27, v27, v32
	v_cvt_pk_bf16_f32 v22, v21, v22
	v_add_f32_e32 v31, 1.0, v31
	v_add_f32_e32 v30, 1.0, v30
	v_rcp_f32_e32 v31, v31
	v_cvt_pk_bf16_f32 v23, v26, v23
	v_cvt_pk_bf16_f32 v24, v27, v24
	v_or_b32_e32 v26, s11, v138
	v_mov_b32_e32 v27, v129
	v_rcp_f32_e32 v30, v30
	v_lshlrev_b64 v[26:27], 12, v[26:27]
	v_lshl_add_u64 v[26:27], s[92:93], 0, v[26:27]
	v_lshl_add_u64 v[26:27], v[26:27], 0, s[4:5]
	v_lshlrev_b32_e32 v32, 16, v25
	v_and_b32_e32 v25, 0xffff0000, v25
	v_mul_f32_e32 v29, v31, v29
	v_lshl_add_u64 v[26:27], v[26:27], 0, v[144:145]
	v_mul_f32_e32 v28, v30, v28
	v_mul_f32_e32 v25, v29, v25
	v_add_co_u32_e32 v26, vcc, s8, v26
	v_mul_f32_e32 v28, v28, v32
	v_cvt_pk_bf16_f32 v25, v28, v25
	s_nop 0
	v_addc_co_u32_e32 v27, vcc, 0, v27, vcc
	v_add_u32_e32 v21, v20, v197
	global_store_dwordx4 v[26:27], v[22:25], off offset:2048
	ds_read_b128 v[22:25], v21
	s_waitcnt vmcnt(7)
	v_lshlrev_b32_e32 v21, 16, v16
	v_and_b32_e32 v16, 0xffff0000, v16
	v_mul_f32_e32 v27, 0xbfb8aa3b, v16
	v_exp_f32_e32 v27, v27
	v_mul_f32_e32 v26, 0xbfb8aa3b, v21
	v_exp_f32_e32 v26, v26
	s_waitcnt lgkmcnt(0)
	v_lshlrev_b32_e32 v28, 16, v22
	v_add_f32_e32 v27, 1.0, v27
	v_rcp_f32_e32 v27, v27
	v_and_b32_e32 v22, 0xffff0000, v22
	v_add_f32_e32 v26, 1.0, v26
	v_rcp_f32_e32 v26, v26
	v_mul_f32_e32 v16, v27, v16
	v_mul_f32_e32 v16, v16, v22
	v_lshlrev_b32_e32 v22, 16, v17
	v_and_b32_e32 v17, 0xffff0000, v17
	v_mul_f32_e32 v27, 0xbfb8aa3b, v17
	v_exp_f32_e32 v27, v27
	v_mul_f32_e32 v21, v26, v21
	v_mul_f32_e32 v26, 0xbfb8aa3b, v22
	v_exp_f32_e32 v26, v26
	v_add_f32_e32 v27, 1.0, v27
	v_rcp_f32_e32 v27, v27
	v_mul_f32_e32 v21, v21, v28
	v_add_f32_e32 v26, 1.0, v26
	v_lshlrev_b32_e32 v28, 16, v23
	v_and_b32_e32 v23, 0xffff0000, v23
	v_mul_f32_e32 v17, v27, v17
	v_rcp_f32_e32 v26, v26
	v_mul_f32_e32 v17, v17, v23
	v_lshlrev_b32_e32 v23, 16, v18
	v_and_b32_e32 v18, 0xffff0000, v18
	v_mul_f32_e32 v27, 0xbfb8aa3b, v18
	v_exp_f32_e32 v27, v27
	v_mul_f32_e32 v22, v26, v22
	v_mul_f32_e32 v26, 0xbfb8aa3b, v23
	v_exp_f32_e32 v26, v26
	v_add_f32_e32 v27, 1.0, v27
	v_rcp_f32_e32 v27, v27
	v_mul_f32_e32 v22, v22, v28
	v_add_f32_e32 v26, 1.0, v26
	v_rcp_f32_e32 v26, v26
	v_lshlrev_b32_e32 v28, 16, v24
	v_and_b32_e32 v24, 0xffff0000, v24
	v_mul_f32_e32 v18, v27, v18
	v_mul_f32_e32 v18, v18, v24
	v_lshlrev_b32_e32 v24, 16, v19
	v_and_b32_e32 v19, 0xffff0000, v19
	v_mul_f32_e32 v27, 0xbfb8aa3b, v19
	v_mul_f32_e32 v23, v26, v23
	v_mul_f32_e32 v26, 0xbfb8aa3b, v24
	v_exp_f32_e32 v27, v27
	v_exp_f32_e32 v26, v26
	v_mul_f32_e32 v23, v23, v28
	v_cvt_pk_bf16_f32 v16, v21, v16
	v_add_f32_e32 v27, 1.0, v27
	v_cvt_pk_bf16_f32 v17, v22, v17
	v_cvt_pk_bf16_f32 v18, v23, v18
	v_or_b32_e32 v22, s11, v140
	v_mov_b32_e32 v23, v129
	v_add_f32_e32 v26, 1.0, v26
	v_rcp_f32_e32 v27, v27
	v_lshlrev_b64 v[22:23], 12, v[22:23]
	v_rcp_f32_e32 v26, v26
	v_lshl_add_u64 v[22:23], s[92:93], 0, v[22:23]
	v_lshl_add_u64 v[22:23], v[22:23], 0, s[4:5]
	v_lshl_add_u64 v[22:23], v[22:23], 0, v[144:145]
	v_lshlrev_b32_e32 v28, 16, v25
	v_and_b32_e32 v25, 0xffff0000, v25
	v_mul_f32_e32 v19, v27, v19
	v_add_co_u32_e32 v22, vcc, s8, v22
	v_mul_f32_e32 v24, v26, v24
	v_mul_f32_e32 v19, v19, v25
	v_addc_co_u32_e32 v23, vcc, 0, v23, vcc
	s_waitcnt vmcnt(6)
	v_lshlrev_b32_e32 v21, 16, v12
	v_and_b32_e32 v12, 0xffff0000, v12
	v_mul_f32_e32 v24, v24, v28
	v_cvt_pk_bf16_f32 v19, v24, v19
	global_store_dwordx4 v[22:23], v[16:19], off offset:2048
	v_mul_f32_e32 v23, 0xbfb8aa3b, v12
	v_exp_f32_e32 v23, v23
	v_add_u32_e32 v16, v20, v171
	ds_read_b128 v[16:19], v16
	v_mul_f32_e32 v22, 0xbfb8aa3b, v21
	v_add_f32_e32 v23, 1.0, v23
	v_rcp_f32_e32 v23, v23
	v_exp_f32_e32 v22, v22
	s_waitcnt lgkmcnt(0)
; __device__ __forceinline__ float bf2f(short s) { return __uint_as_float(((unsigned)(unsigned short)s) << 16); }
; __device__ __forceinline__ float silu_fast(float g) { return g * __builtin_amdgcn_rcpf(1.f + __builtin_amdgcn_exp2f(-g * LOG2E)); }
; __device__ __forceinline__ bf16x8 tobf8(f32x8 x) { u32x4 w = {cvtpk(x[0], x[1]), cvtpk(x[2], x[3]), cvtpk(x[4], x[5]), cvtpk(x[6], x[7])}; return *reinterpret_cast<bf16x8*>(&w); }
; template <int MODE, bool SAMPLE>
; __device__ __forceinline__ void attn_unit(const Params& p, char* lds, int b, int h, int qb) {
;     ...
;         for (int it = 0; it < NIT; ++it) { const int row = it * 4 + er; const bf16x8 mx = *(const bf16x8*)(Qs + row * 256 + ec * 2); f32x8 y;
; #pragma unroll
;             for (int i = 0; i < 8; ++i) y[i] = bf2f(mx[i]) * silu_fast(bf2f(gt[it][i]));
;             *(bf16x8*)(MIX + (rbase + row) * DM + MODE * 1024 + h * HD + ec) = tobf8(y); }
	v_lshlrev_b32_e32 v24, 16, v16
	v_and_b32_e32 v16, 0xffff0000, v16
	v_mul_f32_e32 v12, v23, v12
	v_mul_f32_e32 v12, v12, v16
	v_lshlrev_b32_e32 v16, 16, v13
	v_and_b32_e32 v13, 0xffff0000, v13
	v_add_f32_e32 v22, 1.0, v22
	v_mul_f32_e32 v23, 0xbfb8aa3b, v13
	v_rcp_f32_e32 v22, v22
	v_exp_f32_e32 v23, v23
	v_mul_f32_e32 v21, v22, v21
	v_mul_f32_e32 v22, 0xbfb8aa3b, v16
	v_add_f32_e32 v23, 1.0, v23
	v_exp_f32_e32 v22, v22
	v_rcp_f32_e32 v23, v23
	v_mul_f32_e32 v21, v21, v24
	v_lshlrev_b32_e32 v24, 16, v17
	v_add_f32_e32 v22, 1.0, v22
	v_and_b32_e32 v17, 0xffff0000, v17
	v_mul_f32_e32 v13, v23, v13
	v_rcp_f32_e32 v22, v22
	v_mul_f32_e32 v13, v13, v17
	v_lshlrev_b32_e32 v17, 16, v14
	v_and_b32_e32 v14, 0xffff0000, v14
	v_mul_f32_e32 v23, 0xbfb8aa3b, v14
	v_exp_f32_e32 v23, v23
	v_mul_f32_e32 v16, v22, v16
	v_mul_f32_e32 v22, 0xbfb8aa3b, v17
	v_exp_f32_e32 v22, v22
	v_add_f32_e32 v23, 1.0, v23
	v_rcp_f32_e32 v23, v23
	v_mul_f32_e32 v16, v16, v24
	v_add_f32_e32 v22, 1.0, v22
	v_rcp_f32_e32 v22, v22
	v_lshlrev_b32_e32 v24, 16, v18
	v_and_b32_e32 v18, 0xffff0000, v18
	v_mul_f32_e32 v14, v23, v14
	v_mul_f32_e32 v14, v14, v18
	v_lshlrev_b32_e32 v18, 16, v15
	v_and_b32_e32 v15, 0xffff0000, v15
	v_mul_f32_e32 v23, 0xbfb8aa3b, v15
	v_mul_f32_e32 v17, v22, v17
	v_mul_f32_e32 v22, 0xbfb8aa3b, v18
	v_exp_f32_e32 v23, v23
	v_exp_f32_e32 v22, v22
	v_mul_f32_e32 v17, v17, v24
	v_cvt_pk_bf16_f32 v12, v21, v12
	v_add_f32_e32 v23, 1.0, v23
	v_cvt_pk_bf16_f32 v13, v16, v13
	v_cvt_pk_bf16_f32 v14, v17, v14
	v_or_b32_e32 v16, s11, v148
	v_mov_b32_e32 v17, v129
	v_add_f32_e32 v22, 1.0, v22
	v_rcp_f32_e32 v23, v23
	v_lshlrev_b64 v[16:17], 12, v[16:17]
	v_rcp_f32_e32 v22, v22
	v_lshl_add_u64 v[16:17], s[92:93], 0, v[16:17]
	v_lshl_add_u64 v[16:17], v[16:17], 0, s[4:5]
	v_lshl_add_u64 v[16:17], v[16:17], 0, v[144:145]
	v_lshlrev_b32_e32 v24, 16, v19
	v_and_b32_e32 v19, 0xffff0000, v19
	v_mul_f32_e32 v15, v23, v15
	v_add_co_u32_e32 v16, vcc, s8, v16
	v_mul_f32_e32 v18, v22, v18
	v_mul_f32_e32 v15, v15, v19
	v_addc_co_u32_e32 v17, vcc, 0, v17, vcc
	v_mul_f32_e32 v18, v18, v24
	v_cvt_pk_bf16_f32 v15, v18, v15
	global_store_dwordx4 v[16:17], v[12:15], off offset:2048
	s_waitcnt vmcnt(7)
	v_lshlrev_b32_e32 v16, 16, v8
	v_and_b32_e32 v8, 0xffff0000, v8
	v_mul_f32_e32 v18, 0xbfb8aa3b, v8
	v_exp_f32_e32 v18, v18
	v_add_u32_e32 v12, v20, v210
	ds_read_b128 v[12:15], v12
	v_mul_f32_e32 v17, 0xbfb8aa3b, v16
	v_add_f32_e32 v18, 1.0, v18
	v_rcp_f32_e32 v18, v18
	v_exp_f32_e32 v17, v17
	s_waitcnt lgkmcnt(0)
	v_lshlrev_b32_e32 v19, 16, v12
	v_and_b32_e32 v12, 0xffff0000, v12
	v_mul_f32_e32 v8, v18, v8
	v_mul_f32_e32 v8, v8, v12
	v_lshlrev_b32_e32 v12, 16, v9
	v_and_b32_e32 v9, 0xffff0000, v9
	v_add_f32_e32 v17, 1.0, v17
	v_mul_f32_e32 v18, 0xbfb8aa3b, v9
	v_rcp_f32_e32 v17, v17
	v_exp_f32_e32 v18, v18
	v_mul_f32_e32 v16, v17, v16
	v_mul_f32_e32 v17, 0xbfb8aa3b, v12
	v_add_f32_e32 v18, 1.0, v18
	v_exp_f32_e32 v17, v17
	v_rcp_f32_e32 v18, v18
	v_mul_f32_e32 v16, v16, v19
	v_lshlrev_b32_e32 v19, 16, v13
	v_add_f32_e32 v17, 1.0, v17
	v_and_b32_e32 v13, 0xffff0000, v13
	v_mul_f32_e32 v9, v18, v9
	v_rcp_f32_e32 v17, v17
	v_mul_f32_e32 v9, v9, v13
	v_lshlrev_b32_e32 v13, 16, v10
	v_and_b32_e32 v10, 0xffff0000, v10
	v_mul_f32_e32 v18, 0xbfb8aa3b, v10
	v_exp_f32_e32 v18, v18
	v_mul_f32_e32 v12, v17, v12
	v_mul_f32_e32 v17, 0xbfb8aa3b, v13
	v_exp_f32_e32 v17, v17
	v_add_f32_e32 v18, 1.0, v18
	v_rcp_f32_e32 v18, v18
	v_mul_f32_e32 v12, v12, v19
	v_add_f32_e32 v17, 1.0, v17
	v_rcp_f32_e32 v17, v17
	v_lshlrev_b32_e32 v19, 16, v14
	v_and_b32_e32 v14, 0xffff0000, v14
	v_mul_f32_e32 v10, v18, v10
	v_mul_f32_e32 v10, v10, v14
	v_lshlrev_b32_e32 v14, 16, v11
	v_and_b32_e32 v11, 0xffff0000, v11
	v_mul_f32_e32 v18, 0xbfb8aa3b, v11
	v_mul_f32_e32 v13, v17, v13
	v_mul_f32_e32 v17, 0xbfb8aa3b, v14
	v_exp_f32_e32 v18, v18
	v_exp_f32_e32 v17, v17
	v_mul_f32_e32 v13, v13, v19
	v_cvt_pk_bf16_f32 v8, v16, v8
	v_add_f32_e32 v18, 1.0, v18
	v_cvt_pk_bf16_f32 v9, v12, v9
	v_cvt_pk_bf16_f32 v10, v13, v10
	v_or_b32_e32 v12, s11, v150
	v_mov_b32_e32 v13, v129
	v_add_f32_e32 v17, 1.0, v17
	v_rcp_f32_e32 v18, v18
	v_lshlrev_b64 v[12:13], 12, v[12:13]
	v_rcp_f32_e32 v17, v17
	v_lshl_add_u64 v[12:13], s[92:93], 0, v[12:13]
	v_lshl_add_u64 v[12:13], v[12:13], 0, s[4:5]
	v_lshl_add_u64 v[12:13], v[12:13], 0, v[144:145]
	v_lshlrev_b32_e32 v19, 16, v15
	v_and_b32_e32 v15, 0xffff0000, v15
	v_mul_f32_e32 v11, v18, v11
	v_add_co_u32_e32 v12, vcc, s8, v12
	v_mul_f32_e32 v14, v17, v14
	v_mul_f32_e32 v11, v11, v15
	v_addc_co_u32_e32 v13, vcc, 0, v13, vcc
	v_mul_f32_e32 v14, v14, v19
	v_cvt_pk_bf16_f32 v11, v14, v11
	global_store_dwordx4 v[12:13], v[8:11], off offset:2048
	s_waitcnt vmcnt(7)
; __device__ __forceinline__ float bf2f(short s) { return __uint_as_float(((unsigned)(unsigned short)s) << 16); }
; __device__ __forceinline__ float silu_fast(float g) { return g * __builtin_amdgcn_rcpf(1.f + __builtin_amdgcn_exp2f(-g * LOG2E)); }
; __device__ __forceinline__ bf16x8 tobf8(f32x8 x) { u32x4 w = {cvtpk(x[0], x[1]), cvtpk(x[2], x[3]), cvtpk(x[4], x[5]), cvtpk(x[6], x[7])}; return *reinterpret_cast<bf16x8*>(&w); }
; template <int MODE, bool SAMPLE>
; __device__ __forceinline__ void attn_unit(const Params& p, char* lds, int b, int h, int qb) {
;     ...
;         for (int it = 0; it < NIT; ++it) { const int row = it * 4 + er; const bf16x8 mx = *(const bf16x8*)(Qs + row * 256 + ec * 2); f32x8 y;
; #pragma unroll
;             for (int i = 0; i < 8; ++i) y[i] = bf2f(mx[i]) * silu_fast(bf2f(gt[it][i]));
;             *(bf16x8*)(MIX + (rbase + row) * DM + MODE * 1024 + h * HD + ec) = tobf8(y); }
;     }
;     __syncthreads();
	v_lshlrev_b32_e32 v12, 16, v4
	v_and_b32_e32 v4, 0xffff0000, v4
	v_mul_f32_e32 v14, 0xbfb8aa3b, v4
	v_exp_f32_e32 v14, v14
	v_add_u32_e32 v8, v20, v211
	ds_read_b128 v[8:11], v8
	v_mul_f32_e32 v13, 0xbfb8aa3b, v12
	v_add_f32_e32 v14, 1.0, v14
	v_rcp_f32_e32 v14, v14
	v_exp_f32_e32 v13, v13
	s_waitcnt lgkmcnt(0)
	v_lshlrev_b32_e32 v15, 16, v8
	v_and_b32_e32 v8, 0xffff0000, v8
	v_mul_f32_e32 v4, v14, v4
	v_mul_f32_e32 v4, v4, v8
	v_lshlrev_b32_e32 v8, 16, v5
	v_and_b32_e32 v5, 0xffff0000, v5
	v_add_f32_e32 v13, 1.0, v13
	v_mul_f32_e32 v14, 0xbfb8aa3b, v5
	v_rcp_f32_e32 v13, v13
	v_exp_f32_e32 v14, v14
	v_mul_f32_e32 v12, v13, v12
	v_mul_f32_e32 v13, 0xbfb8aa3b, v8
	v_add_f32_e32 v14, 1.0, v14
	v_exp_f32_e32 v13, v13
	v_rcp_f32_e32 v14, v14
	v_mul_f32_e32 v12, v12, v15
	v_lshlrev_b32_e32 v15, 16, v9
	v_add_f32_e32 v13, 1.0, v13
	v_and_b32_e32 v9, 0xffff0000, v9
	v_mul_f32_e32 v5, v14, v5
	v_rcp_f32_e32 v13, v13
	v_mul_f32_e32 v5, v5, v9
	v_lshlrev_b32_e32 v9, 16, v6
	v_and_b32_e32 v6, 0xffff0000, v6
	v_mul_f32_e32 v14, 0xbfb8aa3b, v6
	v_exp_f32_e32 v14, v14
	v_mul_f32_e32 v8, v13, v8
	v_mul_f32_e32 v13, 0xbfb8aa3b, v9
	v_exp_f32_e32 v13, v13
	v_add_f32_e32 v14, 1.0, v14
	v_rcp_f32_e32 v14, v14
	v_mul_f32_e32 v8, v8, v15
	v_add_f32_e32 v13, 1.0, v13
	v_rcp_f32_e32 v13, v13
	v_lshlrev_b32_e32 v15, 16, v10
	v_and_b32_e32 v10, 0xffff0000, v10
	v_mul_f32_e32 v6, v14, v6
	v_mul_f32_e32 v6, v6, v10
	v_lshlrev_b32_e32 v10, 16, v7
	v_and_b32_e32 v7, 0xffff0000, v7
	v_mul_f32_e32 v14, 0xbfb8aa3b, v7
	v_mul_f32_e32 v9, v13, v9
	v_mul_f32_e32 v13, 0xbfb8aa3b, v10
	v_exp_f32_e32 v14, v14
	v_exp_f32_e32 v13, v13
	v_mul_f32_e32 v9, v9, v15
	v_cvt_pk_bf16_f32 v4, v12, v4
	v_add_f32_e32 v14, 1.0, v14
	v_cvt_pk_bf16_f32 v5, v8, v5
	v_cvt_pk_bf16_f32 v6, v9, v6
	v_or_b32_e32 v8, s11, v152
	v_mov_b32_e32 v9, v129
	v_add_f32_e32 v13, 1.0, v13
	v_rcp_f32_e32 v14, v14
	v_lshlrev_b64 v[8:9], 12, v[8:9]
	v_rcp_f32_e32 v13, v13
	v_lshl_add_u64 v[8:9], s[92:93], 0, v[8:9]
	v_lshl_add_u64 v[8:9], v[8:9], 0, s[4:5]
	v_lshl_add_u64 v[8:9], v[8:9], 0, v[144:145]
	v_lshlrev_b32_e32 v15, 16, v11
	v_and_b32_e32 v11, 0xffff0000, v11
	v_mul_f32_e32 v7, v14, v7
	v_add_co_u32_e32 v8, vcc, s8, v8
	v_mul_f32_e32 v10, v13, v10
	v_mul_f32_e32 v7, v7, v11
	v_addc_co_u32_e32 v9, vcc, 0, v9, vcc
	v_mul_f32_e32 v10, v10, v15
	v_cvt_pk_bf16_f32 v7, v10, v7
	global_store_dwordx4 v[8:9], v[4:7], off offset:2048
	s_waitcnt vmcnt(7)
	v_lshlrev_b32_e32 v8, 16, v0
	v_and_b32_e32 v0, 0xffff0000, v0
	v_mul_f32_e32 v10, 0xbfb8aa3b, v0
	v_exp_f32_e32 v10, v10
	v_add_u32_e32 v4, v20, v212
	ds_read_b128 v[4:7], v4
	v_mul_f32_e32 v9, 0xbfb8aa3b, v8
	v_add_f32_e32 v10, 1.0, v10
	v_rcp_f32_e32 v10, v10
	v_exp_f32_e32 v9, v9
	s_waitcnt lgkmcnt(0)
	v_lshlrev_b32_e32 v11, 16, v4
	v_and_b32_e32 v4, 0xffff0000, v4
	v_mul_f32_e32 v0, v10, v0
	v_mul_f32_e32 v0, v0, v4
	v_lshlrev_b32_e32 v4, 16, v1
	v_and_b32_e32 v1, 0xffff0000, v1
	v_add_f32_e32 v9, 1.0, v9
	v_mul_f32_e32 v10, 0xbfb8aa3b, v1
	v_rcp_f32_e32 v9, v9
	v_exp_f32_e32 v10, v10
	v_mul_f32_e32 v8, v9, v8
	v_mul_f32_e32 v9, 0xbfb8aa3b, v4
	v_add_f32_e32 v10, 1.0, v10
	v_exp_f32_e32 v9, v9
	v_rcp_f32_e32 v10, v10
	v_mul_f32_e32 v8, v8, v11
	v_lshlrev_b32_e32 v11, 16, v5
	v_add_f32_e32 v9, 1.0, v9
	v_and_b32_e32 v5, 0xffff0000, v5
	v_mul_f32_e32 v1, v10, v1
	v_rcp_f32_e32 v9, v9
	v_mul_f32_e32 v1, v1, v5
	v_lshlrev_b32_e32 v5, 16, v2
	v_and_b32_e32 v2, 0xffff0000, v2
	v_mul_f32_e32 v10, 0xbfb8aa3b, v2
	v_exp_f32_e32 v10, v10
	v_mul_f32_e32 v4, v9, v4
	v_mul_f32_e32 v9, 0xbfb8aa3b, v5
	v_exp_f32_e32 v9, v9
	v_add_f32_e32 v10, 1.0, v10
	v_rcp_f32_e32 v10, v10
	v_mul_f32_e32 v4, v4, v11
	v_add_f32_e32 v9, 1.0, v9
	v_rcp_f32_e32 v9, v9
	v_lshlrev_b32_e32 v11, 16, v6
	v_and_b32_e32 v6, 0xffff0000, v6
	v_mul_f32_e32 v2, v10, v2
	v_mul_f32_e32 v2, v2, v6
	v_lshlrev_b32_e32 v6, 16, v3
	v_and_b32_e32 v3, 0xffff0000, v3
	v_mul_f32_e32 v10, 0xbfb8aa3b, v3
	v_mul_f32_e32 v5, v9, v5
	v_mul_f32_e32 v9, 0xbfb8aa3b, v6
	v_exp_f32_e32 v10, v10
	v_exp_f32_e32 v9, v9
	v_mul_f32_e32 v5, v5, v11
	v_cvt_pk_bf16_f32 v0, v8, v0
	v_add_f32_e32 v10, 1.0, v10
	v_cvt_pk_bf16_f32 v1, v4, v1
	v_cvt_pk_bf16_f32 v2, v5, v2
	v_or_b32_e32 v4, s11, v154
	v_mov_b32_e32 v5, v129
	v_add_f32_e32 v9, 1.0, v9
	v_rcp_f32_e32 v10, v10
	v_lshlrev_b64 v[4:5], 12, v[4:5]
	v_rcp_f32_e32 v9, v9
	v_lshl_add_u64 v[4:5], s[92:93], 0, v[4:5]
	v_lshl_add_u64 v[4:5], v[4:5], 0, s[4:5]
	v_lshl_add_u64 v[4:5], v[4:5], 0, v[144:145]
	v_lshlrev_b32_e32 v11, 16, v7
	v_and_b32_e32 v7, 0xffff0000, v7
	v_mul_f32_e32 v3, v10, v3
	v_add_co_u32_e32 v4, vcc, 0x11300000, v4
	v_mul_f32_e32 v6, v9, v6
	v_mul_f32_e32 v3, v3, v7
	v_addc_co_u32_e32 v5, vcc, 0, v5, vcc
	v_mul_f32_e32 v6, v6, v11
	v_cvt_pk_bf16_f32 v3, v6, v3
	global_store_dwordx4 v[4:5], v[0:3], off offset:2048
	s_barrier
	s_cbranch_scc1 .LBB0_721

; template <int MODE, bool SAMPLE>
; __device__ __forceinline__ void attn_unit(const Params& p, char* lds, int b, int h, int qb) {
;     ...
; #pragma unroll
;     ...
;         const int j = 2 * jj + par;
;         if (j > jfirst) continue;
;         const int buf = par;
;         WRITET(buf, stg2[NS == 2 ? par : 0]);
;         if (j >= NS) LOADT(j - NS, stg2[NS == 2 ? par : 0]);
;         __syncthreads();
;         if (wact && j <= jd && var < 2) {
.LBB0_682:
	v_readfirstlane_b32 s98, v183
	s_cmpk_lt_u32 s98, 0x100
	s_cbranch_scc1 .Lsp_0
	s_setprio 1

; __device__ __forceinline__ unsigned cvtpk(float lo, float hi) { unsigned r; asm volatile("v_cvt_pk_bf16_f32 %0, %1, %2" : "=v"(r) : "v"(lo), "v"(hi)); return r; }
; __device__ __forceinline__ int crow(int r, int hi) { return (r & 3) + 8 * (r >> 2) + 4 * hi; }
; template <int MODE, bool SAMPLE>
; __device__ __forceinline__ void attn_unit(const Params& p, char* lds, int b, int h, int qb) {
;     ...
;         if (MODE == 0) { if (hi == 0) wsc[32 + r32] = l_reg; asm volatile("s_waitcnt lgkmcnt(0)" ::: "memory");
; #pragma unroll
;             for (int r = 0; r < 16; ++r) rli[r] = __builtin_amdgcn_rcpf(wsc[32 + crow(r, hi)]); }
; #pragma unroll
;         for (int r = 0; r < 16; ++r) { const int orow = crow(r, hi);
;             if (!SAMPLE || orow < TS) {
; #pragma unroll
;                 for (int d0 = 0; d0 < 4; ++d0) { float ov = o[d0][r]; if (MODE == 0) ov *= rli[r];
;                     const unsigned pk = cvtpk(ov, 0.f); *(bf16_t*)(Qs + orow * 256 + (d0 * 32 + r32) * 2) = (bf16_t)(pk & 0xffffu); } } }
.LBB0_703:
	s_waitcnt vmcnt(0)
	s_setprio 0
	s_and_saveexec_b64 s[18:19], s[14:15]
	ds_write_b32 v147, v219 offset:128
	s_or_b64 exec, exec, s[18:19]
	s_waitcnt lgkmcnt(0)
	v_add_u32_e32 v72, s12, v137
	ds_read_b128 v[64:67], v72 offset:128
	ds_read_b128 v[68:71], v72 offset:160
	s_ashr_i32 s4, s10, 31
	v_mov_b32_e32 v145, v129
	v_mov_b32_e32 v147, v129
	s_waitcnt lgkmcnt(1)
	v_rcp_f32_e32 v73, v64
	v_rcp_f32_e32 v74, v65
	v_rcp_f32_e32 v75, v66
	v_rcp_f32_e32 v76, v67
	v_mul_f32_e32 v16, v16, v73
	s_waitcnt lgkmcnt(0)
	v_rcp_f32_e32 v77, v68
	ds_read_b128 v[64:67], v72 offset:192
	v_rcp_f32_e32 v78, v69
	v_rcp_f32_e32 v79, v70
	v_rcp_f32_e32 v80, v71
	ds_read_b128 v[68:71], v72 offset:224
	v_add3_u32 v72, s26, v193, v192
	v_cvt_pk_bf16_f32 v16, v16, v129
	ds_write_b16 v72, v16
	v_mul_f32_e32 v16, v48, v73
	v_cvt_pk_bf16_f32 v16, v16, v129
	ds_write_b16 v72, v16 offset:64
	v_mul_f32_e32 v16, v32, v73
	v_mul_f32_e32 v0, v0, v73
	v_cvt_pk_bf16_f32 v16, v16, v129
	ds_write_b16 v72, v16 offset:128
	v_cvt_pk_bf16_f32 v0, v0, v129
	ds_write_b16 v72, v0 offset:192
	v_mul_f32_e32 v0, v17, v74
	v_cvt_pk_bf16_f32 v0, v0, v129
	ds_write_b16 v72, v0 offset:256
	v_mul_f32_e32 v0, v49, v74
	v_cvt_pk_bf16_f32 v0, v0, v129
	ds_write_b16 v72, v0 offset:320
	v_mul_f32_e32 v0, v33, v74
	v_cvt_pk_bf16_f32 v0, v0, v129
	ds_write_b16 v72, v0 offset:384
	v_mul_f32_e32 v0, v1, v74
	v_cvt_pk_bf16_f32 v0, v0, v129
	ds_write_b16 v72, v0 offset:448
	v_mul_f32_e32 v0, v18, v75
	v_cvt_pk_bf16_f32 v0, v0, v129
	ds_write_b16 v72, v0 offset:512
	v_mul_f32_e32 v0, v50, v75
	v_cvt_pk_bf16_f32 v0, v0, v129
	ds_write_b16 v72, v0 offset:576
	v_mul_f32_e32 v0, v34, v75
	v_cvt_pk_bf16_f32 v0, v0, v129
	ds_write_b16 v72, v0 offset:640
	v_mul_f32_e32 v0, v2, v75
	v_cvt_pk_bf16_f32 v0, v0, v129
	ds_write_b16 v72, v0 offset:704
	v_mul_f32_e32 v0, v19, v76
	v_cvt_pk_bf16_f32 v0, v0, v129
	ds_write_b16 v72, v0 offset:768
	v_mul_f32_e32 v0, v51, v76
	v_cvt_pk_bf16_f32 v0, v0, v129
	ds_write_b16 v72, v0 offset:832
	v_mul_f32_e32 v0, v35, v76
	v_cvt_pk_bf16_f32 v0, v0, v129
	ds_write_b16 v72, v0 offset:896
	v_mul_f32_e32 v0, v3, v76
	v_cvt_pk_bf16_f32 v0, v0, v129
	ds_write_b16 v72, v0 offset:960
	v_mul_f32_e32 v0, v20, v77
	v_cvt_pk_bf16_f32 v0, v0, v129
	ds_write_b16 v72, v0 offset:2048
	v_mul_f32_e32 v0, v52, v77
	v_cvt_pk_bf16_f32 v0, v0, v129
	ds_write_b16 v72, v0 offset:2112
	v_mul_f32_e32 v0, v36, v77
	v_cvt_pk_bf16_f32 v0, v0, v129
	ds_write_b16 v72, v0 offset:2176
	v_mul_f32_e32 v0, v4, v77
	v_cvt_pk_bf16_f32 v0, v0, v129
	ds_write_b16 v72, v0 offset:2240
	v_mul_f32_e32 v0, v21, v78
	v_cvt_pk_bf16_f32 v0, v0, v129
	ds_write_b16 v72, v0 offset:2304
	v_mul_f32_e32 v0, v53, v78
	v_cvt_pk_bf16_f32 v0, v0, v129
	ds_write_b16 v72, v0 offset:2368
	v_mul_f32_e32 v0, v37, v78
	v_cvt_pk_bf16_f32 v0, v0, v129
	ds_write_b16 v72, v0 offset:2432
	v_mul_f32_e32 v0, v5, v78
	v_cvt_pk_bf16_f32 v0, v0, v129
	ds_write_b16 v72, v0 offset:2496
	v_mul_f32_e32 v0, v22, v79
	v_cvt_pk_bf16_f32 v0, v0, v129
	ds_write_b16 v72, v0 offset:2560
	v_mul_f32_e32 v0, v54, v79
	v_cvt_pk_bf16_f32 v0, v0, v129
	ds_write_b16 v72, v0 offset:2624
	v_mul_f32_e32 v0, v38, v79
	v_cvt_pk_bf16_f32 v0, v0, v129
	ds_write_b16 v72, v0 offset:2688
	v_mul_f32_e32 v0, v6, v79
	v_cvt_pk_bf16_f32 v0, v0, v129
	ds_write_b16 v72, v0 offset:2752
	v_mul_f32_e32 v0, v23, v80
	v_cvt_pk_bf16_f32 v0, v0, v129
	ds_write_b16 v72, v0 offset:2816
	v_mul_f32_e32 v0, v55, v80
	v_cvt_pk_bf16_f32 v0, v0, v129
	s_waitcnt lgkmcnt(14)
	v_rcp_f32_e32 v64, v64
	ds_write_b16 v72, v0 offset:2880
	v_mul_f32_e32 v0, v39, v80
	v_cvt_pk_bf16_f32 v0, v0, v129
	ds_write_b16 v72, v0 offset:2944
	v_mul_f32_e32 v0, v7, v80
	v_cvt_pk_bf16_f32 v0, v0, v129
	ds_write_b16 v72, v0 offset:3008
	v_mul_f32_e32 v0, v24, v64
	v_cvt_pk_bf16_f32 v0, v0, v129
	ds_write_b16 v72, v0 offset:4096
	v_mul_f32_e32 v0, v56, v64
	v_cvt_pk_bf16_f32 v0, v0, v129
	v_rcp_f32_e32 v65, v65
	ds_write_b16 v72, v0 offset:4160
	v_mul_f32_e32 v0, v40, v64
	v_cvt_pk_bf16_f32 v0, v0, v129
	ds_write_b16 v72, v0 offset:4224
	v_mul_f32_e32 v0, v8, v64
	v_cvt_pk_bf16_f32 v0, v0, v129
	ds_write_b16 v72, v0 offset:4288
	v_mul_f32_e32 v0, v25, v65
	v_cvt_pk_bf16_f32 v0, v0, v129
	ds_write_b16 v72, v0 offset:4352
	v_mul_f32_e32 v0, v57, v65
	v_cvt_pk_bf16_f32 v0, v0, v129
	v_rcp_f32_e32 v66, v66
	ds_write_b16 v72, v0 offset:4416
	v_mul_f32_e32 v0, v41, v65
	v_cvt_pk_bf16_f32 v0, v0, v129
	ds_write_b16 v72, v0 offset:4480
	v_mul_f32_e32 v0, v9, v65
	v_cvt_pk_bf16_f32 v0, v0, v129
	ds_write_b16 v72, v0 offset:4544
	v_mul_f32_e32 v0, v26, v66
	v_cvt_pk_bf16_f32 v0, v0, v129
	ds_write_b16 v72, v0 offset:4608
	v_mul_f32_e32 v0, v58, v66
	v_cvt_pk_bf16_f32 v0, v0, v129
	v_rcp_f32_e32 v67, v67
	ds_write_b16 v72, v0 offset:4672
	v_mul_f32_e32 v0, v42, v66
	v_cvt_pk_bf16_f32 v0, v0, v129
	ds_write_b16 v72, v0 offset:4736
	v_mul_f32_e32 v0, v10, v66
	v_cvt_pk_bf16_f32 v0, v0, v129
	ds_write_b16 v72, v0 offset:4800
	v_mul_f32_e32 v0, v27, v67
	v_cvt_pk_bf16_f32 v0, v0, v129
	ds_write_b16 v72, v0 offset:4864
	v_mul_f32_e32 v0, v59, v67
	v_cvt_pk_bf16_f32 v0, v0, v129
	v_rcp_f32_e32 v68, v68
	ds_write_b16 v72, v0 offset:4928
	v_mul_f32_e32 v0, v43, v67
	v_cvt_pk_bf16_f32 v0, v0, v129
	ds_write_b16 v72, v0 offset:4992
	v_mul_f32_e32 v0, v11, v67
	v_cvt_pk_bf16_f32 v0, v0, v129
	ds_write_b16 v72, v0 offset:5056
	v_mul_f32_e32 v0, v28, v68
	v_cvt_pk_bf16_f32 v0, v0, v129
	ds_write_b16 v72, v0 offset:6144
	v_mul_f32_e32 v0, v60, v68
	v_cvt_pk_bf16_f32 v0, v0, v129
	v_rcp_f32_e32 v69, v69
	ds_write_b16 v72, v0 offset:6208
	v_mul_f32_e32 v0, v44, v68
	v_cvt_pk_bf16_f32 v0, v0, v129
	ds_write_b16 v72, v0 offset:6272
; __device__ __forceinline__ unsigned cvtpk(float lo, float hi) { unsigned r; asm volatile("v_cvt_pk_bf16_f32 %0, %1, %2" : "=v"(r) : "v"(lo), "v"(hi)); return r; }
; __device__ __forceinline__ float bf2f(short s) { return __uint_as_float(((unsigned)(unsigned short)s) << 16); }
; __device__ __forceinline__ float silu_fast(float g) { return g * __builtin_amdgcn_rcpf(1.f + __builtin_amdgcn_exp2f(-g * LOG2E)); }
; __device__ __forceinline__ bf16x8 tobf8(f32x8 x) { u32x4 w = {cvtpk(x[0], x[1]), cvtpk(x[2], x[3]), cvtpk(x[4], x[5]), cvtpk(x[6], x[7])}; return *reinterpret_cast<bf16x8*>(&w); }
; template <int MODE, bool SAMPLE>
; __device__ __forceinline__ void attn_unit(const Params& p, char* lds, int b, int h, int qb) {
;     ...
;     const int qw0 = SAMPLE ? PAST : qb * 256 + wid * 32;
;     const int qpos = SAMPLE ? PAST + (r32 & 15) : qw0 + r32;
;     const int jd = SAMPLE ? 16 : (qw0 >> 6);
;     const int jfirst = SAMPLE ? 16 : qb * 4 + 3;
;     ...
;                     const unsigned pk = cvtpk(ov, 0.f); *(bf16_t*)(Qs + orow * 256 + (d0 * 32 + r32) * 2) = (bf16_t)(pk & 0xffffu); } } }
;         asm volatile("s_waitcnt lgkmcnt(0)" ::: "memory");
;         bf16x8 gt[NIT];
; #pragma unroll
;         for (int it = 0; it < NIT; ++it) gt[it] = __builtin_nontemporal_load((const bf16x8*)(P1q + 24 * HB + (rbase + it * 4 + er) * 128 + ec));
; #pragma unroll
;         for (int it = 0; it < NIT; ++it) { const int row = it * 4 + er; const bf16x8 mx = *(const bf16x8*)(Qs + row * 256 + ec * 2); f32x8 y;
; #pragma unroll
;             for (int i = 0; i < 8; ++i) y[i] = bf2f(mx[i]) * silu_fast(bf2f(gt[it][i]));
;             *(bf16x8*)(MIX + (rbase + row) * DM + MODE * 1024 + h * HD + ec) = tobf8(y); }
	v_mul_f32_e32 v0, v12, v68
	v_cvt_pk_bf16_f32 v0, v0, v129
	ds_write_b16 v72, v0 offset:6336
	v_mul_f32_e32 v0, v29, v69
	v_cvt_pk_bf16_f32 v0, v0, v129
	ds_write_b16 v72, v0 offset:6400
	v_mul_f32_e32 v0, v61, v69
	v_cvt_pk_bf16_f32 v0, v0, v129
	v_rcp_f32_e32 v70, v70
	ds_write_b16 v72, v0 offset:6464
	v_mul_f32_e32 v0, v45, v69
	v_cvt_pk_bf16_f32 v0, v0, v129
	ds_write_b16 v72, v0 offset:6528
	v_mul_f32_e32 v0, v13, v69
	v_cvt_pk_bf16_f32 v0, v0, v129
	ds_write_b16 v72, v0 offset:6592
	v_mul_f32_e32 v0, v30, v70
	v_cvt_pk_bf16_f32 v0, v0, v129
	ds_write_b16 v72, v0 offset:6656
	v_mul_f32_e32 v0, v62, v70
	v_cvt_pk_bf16_f32 v0, v0, v129
	v_rcp_f32_e32 v71, v71
	ds_write_b16 v72, v0 offset:6720
	v_mul_f32_e32 v0, v46, v70
	v_cvt_pk_bf16_f32 v0, v0, v129
	ds_write_b16 v72, v0 offset:6784
	v_mul_f32_e32 v0, v14, v70
	v_cvt_pk_bf16_f32 v0, v0, v129
	ds_write_b16 v72, v0 offset:6848
	v_mul_f32_e32 v0, v31, v71
	v_cvt_pk_bf16_f32 v0, v0, v129
	ds_write_b16 v72, v0 offset:6912
	v_mul_f32_e32 v0, v63, v71
	v_cvt_pk_bf16_f32 v0, v0, v129
	ds_write_b16 v72, v0 offset:6976
	v_mul_f32_e32 v0, v47, v71
	v_cvt_pk_bf16_f32 v0, v0, v129
	ds_write_b16 v72, v0 offset:7040
	v_mul_f32_e32 v0, v15, v71
	v_cvt_pk_bf16_f32 v0, v0, v129
	ds_write_b16 v72, v0 offset:7104
	v_lshl_add_u64 v[0:1], s[0:1], 0, v[144:145]
	s_mov_b64 s[0:1], 0x3300000
	v_mov_b32_e32 v51, s4
	v_or_b32_e32 v50, s10, v130
	v_lshl_add_u64 v[4:5], v[0:1], 0, s[0:1]
	v_lshlrev_b64 v[0:1], 8, v[50:51]
	s_waitcnt lgkmcnt(0)
	v_lshl_add_u64 v[0:1], v[4:5], 0, v[0:1]
	global_load_dwordx4 v[0:3], v[0:1], off nt
	v_mov_b32_e32 v35, s4
	v_or_b32_e32 v34, s10, v136
	v_lshlrev_b64 v[6:7], 8, v[34:35]
	v_lshl_add_u64 v[8:9], v[4:5], 0, v[6:7]
	global_load_dwordx4 v[38:41], v[8:9], off nt
	v_mov_b32_e32 v33, s4
	v_or_b32_e32 v32, s10, v138
	v_lshlrev_b64 v[6:7], 8, v[32:33]
	v_mov_b32_e32 v31, s4
	v_or_b32_e32 v30, s10, v140
	v_lshl_add_u64 v[10:11], v[4:5], 0, v[6:7]
	v_lshlrev_b64 v[6:7], 8, v[30:31]
	v_mov_b32_e32 v29, s4
	v_or_b32_e32 v28, s10, v148
	v_lshl_add_u64 v[12:13], v[4:5], 0, v[6:7]
	v_lshlrev_b64 v[6:7], 8, v[28:29]
	v_mov_b32_e32 v27, s4
	v_or_b32_e32 v26, s10, v150
	v_lshl_add_u64 v[14:15], v[4:5], 0, v[6:7]
	v_lshlrev_b64 v[6:7], 8, v[26:27]
	v_mov_b32_e32 v25, s4
	v_or_b32_e32 v24, s10, v152
	v_lshl_add_u64 v[46:47], v[4:5], 0, v[6:7]
	v_lshlrev_b64 v[6:7], 8, v[24:25]
	v_mov_b32_e32 v21, s4
	v_or_b32_e32 v20, s10, v154
	v_lshl_add_u64 v[48:49], v[4:5], 0, v[6:7]
	v_lshlrev_b64 v[6:7], 8, v[20:21]
	v_add_u32_e32 v36, s26, v132
	v_lshl_add_u64 v[52:53], v[4:5], 0, v[6:7]
	v_add_u32_e32 v4, v36, v194
	ds_read_b128 v[4:7], v4
	s_lshl_b32 s4, s11, 8
	v_lshl_add_u64 v[22:23], v[142:143], 0, s[4:5]
	v_lshlrev_b64 v[50:51], 12, v[50:51]
	v_lshl_add_u64 v[50:51], v[22:23], 0, v[50:51]
	s_waitcnt lgkmcnt(0)
	v_lshlrev_b32_e32 v17, 16, v4
	v_and_b32_e32 v4, 0xffff0000, v4
	v_lshlrev_b64 v[34:35], 12, v[34:35]
	v_lshl_add_u64 v[34:35], v[22:23], 0, v[34:35]
	v_lshlrev_b64 v[32:33], 12, v[32:33]
	v_lshl_add_u64 v[32:33], v[22:23], 0, v[32:33]
	v_lshlrev_b64 v[30:31], 12, v[30:31]
	v_lshl_add_u64 v[30:31], v[22:23], 0, v[30:31]
	v_readfirstlane_b32 s0, v183
	s_lshl_b32 s10, s11, 7
	s_sub_i32 s4, 7, s23
	s_lshr_b32 s6, s0, 6
	s_add_u32 s82, s92, s24
	s_addc_u32 s83, s93, 0
	s_lshl_b32 s17, s4, 8
	s_lshl_b32 s0, s6, 5
	s_add_i32 s20, s0, s17
	s_add_i32 s11, s20, s22
	s_mov_b32 s0, 0xcf00000
	s_lshr_b32 s13, s20, 6
	v_mov_b32_e32 v161, v129
	s_waitcnt vmcnt(1)
	v_lshlrev_b32_e32 v8, 16, v0
	v_and_b32_e32 v0, 0xffff0000, v0
	v_mul_f32_e32 v16, 0xbfb8aa3b, v0
	v_exp_f32_e32 v16, v16
	v_mul_f32_e32 v9, 0xbfb8aa3b, v8
	v_exp_f32_e32 v9, v9
	v_add_f32_e32 v16, 1.0, v16
	v_rcp_f32_e32 v16, v16
	v_add_f32_e32 v9, 1.0, v9
	v_rcp_f32_e32 v9, v9
	v_mul_f32_e32 v0, v16, v0
	v_mul_f32_e32 v54, v0, v4
	v_lshlrev_b32_e32 v0, 16, v1
	v_mul_f32_e32 v8, v9, v8
	v_mul_f32_e32 v4, 0xbfb8aa3b, v0
	v_and_b32_e32 v1, 0xffff0000, v1
	v_mul_f32_e32 v37, v8, v17
	v_exp_f32_e32 v4, v4
	v_mul_f32_e32 v8, 0xbfb8aa3b, v1
	v_exp_f32_e32 v8, v8
	v_lshlrev_b32_e32 v9, 16, v5
	v_add_f32_e32 v4, 1.0, v4
	v_rcp_f32_e32 v4, v4
	v_add_f32_e32 v8, 1.0, v8
	v_rcp_f32_e32 v8, v8
	v_mul_f32_e32 v0, v4, v0
	v_mul_f32_e32 v55, v0, v9
	v_and_b32_e32 v0, 0xffff0000, v5
	v_mul_f32_e32 v1, v8, v1
	v_mul_f32_e32 v56, v1, v0
	v_lshlrev_b32_e32 v0, 16, v2
	v_mul_f32_e32 v1, 0xbfb8aa3b, v0
	v_and_b32_e32 v2, 0xffff0000, v2
	v_exp_f32_e32 v1, v1
	v_mul_f32_e32 v4, 0xbfb8aa3b, v2
	v_exp_f32_e32 v4, v4
	v_lshlrev_b32_e32 v5, 16, v6
	v_add_f32_e32 v1, 1.0, v1
	v_rcp_f32_e32 v1, v1
	v_add_f32_e32 v4, 1.0, v4
	v_rcp_f32_e32 v4, v4
	v_mul_f32_e32 v0, v1, v0
	v_mul_f32_e32 v57, v0, v5
	v_and_b32_e32 v0, 0xffff0000, v6
	v_mul_f32_e32 v1, v4, v2
	v_mul_f32_e32 v58, v1, v0
	v_lshlrev_b32_e32 v0, 16, v3
	v_mul_f32_e32 v1, 0xbfb8aa3b, v0
	v_and_b32_e32 v2, 0xffff0000, v3
	v_exp_f32_e32 v1, v1
	v_mul_f32_e32 v3, 0xbfb8aa3b, v2
	v_exp_f32_e32 v3, v3
	v_lshlrev_b32_e32 v4, 16, v7
	v_add_f32_e32 v1, 1.0, v1
	v_rcp_f32_e32 v1, v1
	v_add_f32_e32 v3, 1.0, v3
	v_rcp_f32_e32 v3, v3
	v_mul_f32_e32 v0, v1, v0
	v_mul_f32_e32 v59, v0, v4
	v_and_b32_e32 v0, 0xffff0000, v7
	v_mul_f32_e32 v1, v3, v2
	v_mul_f32_e32 v60, v1, v0
	global_load_dwordx4 v[42:45], v[10:11], off nt
	global_load_dwordx4 v[16:19], v[12:13], off nt
	s_nop 0
	global_load_dwordx4 v[12:15], v[14:15], off nt
	s_nop 0
	global_load_dwordx4 v[8:11], v[46:47], off nt
	global_load_dwordx4 v[4:7], v[48:49], off nt
	global_load_dwordx4 v[0:3], v[52:53], off nt
	v_cvt_pk_bf16_f32 v46, v37, v54
	v_cvt_pk_bf16_f32 v47, v55, v56
	v_cvt_pk_bf16_f32 v48, v57, v58
	v_cvt_pk_bf16_f32 v49, v59, v60
	v_add_u32_e32 v37, v36, v195
	global_store_dwordx4 v[50:51], v[46:49], off
	ds_read_b128 v[46:49], v37
	s_waitcnt vmcnt(7)
; __device__ __forceinline__ float bf2f(short s) { return __uint_as_float(((unsigned)(unsigned short)s) << 16); }
; __device__ __forceinline__ float silu_fast(float g) { return g * __builtin_amdgcn_rcpf(1.f + __builtin_amdgcn_exp2f(-g * LOG2E)); }
; __device__ __forceinline__ bf16x8 tobf8(f32x8 x) { u32x4 w = {cvtpk(x[0], x[1]), cvtpk(x[2], x[3]), cvtpk(x[4], x[5]), cvtpk(x[6], x[7])}; return *reinterpret_cast<bf16x8*>(&w); }
; template <int MODE, bool SAMPLE>
; __device__ __forceinline__ void attn_unit(const Params& p, char* lds, int b, int h, int qb) {
;     ...
;         for (int it = 0; it < NIT; ++it) gt[it] = __builtin_nontemporal_load((const bf16x8*)(P1q + 24 * HB + (rbase + it * 4 + er) * 128 + ec));
; #pragma unroll
;         for (int it = 0; it < NIT; ++it) { const int row = it * 4 + er; const bf16x8 mx = *(const bf16x8*)(Qs + row * 256 + ec * 2); f32x8 y;
; #pragma unroll
;             for (int i = 0; i < 8; ++i) y[i] = bf2f(mx[i]) * silu_fast(bf2f(gt[it][i]));
;             *(bf16x8*)(MIX + (rbase + row) * DM + MODE * 1024 + h * HD + ec) = tobf8(y); }
	v_lshlrev_b32_e32 v37, 16, v38
	v_and_b32_e32 v38, 0xffff0000, v38
	v_mul_f32_e32 v51, 0xbfb8aa3b, v38
	v_exp_f32_e32 v51, v51
	v_mul_f32_e32 v50, 0xbfb8aa3b, v37
	v_exp_f32_e32 v50, v50
	s_waitcnt lgkmcnt(0)
	v_lshlrev_b32_e32 v52, 16, v46
	v_add_f32_e32 v51, 1.0, v51
	v_rcp_f32_e32 v51, v51
	v_and_b32_e32 v46, 0xffff0000, v46
	v_add_f32_e32 v50, 1.0, v50
	v_rcp_f32_e32 v50, v50
	v_mul_f32_e32 v38, v51, v38
	v_mul_f32_e32 v38, v38, v46
	v_lshlrev_b32_e32 v46, 16, v39
	v_and_b32_e32 v39, 0xffff0000, v39
	v_mul_f32_e32 v51, 0xbfb8aa3b, v39
	v_exp_f32_e32 v51, v51
	v_mul_f32_e32 v37, v50, v37
	v_mul_f32_e32 v50, 0xbfb8aa3b, v46
	v_exp_f32_e32 v50, v50
	v_add_f32_e32 v51, 1.0, v51
	v_rcp_f32_e32 v51, v51
	v_mul_f32_e32 v37, v37, v52
	v_add_f32_e32 v50, 1.0, v50
	v_lshlrev_b32_e32 v52, 16, v47
	v_and_b32_e32 v47, 0xffff0000, v47
	v_mul_f32_e32 v39, v51, v39
	v_rcp_f32_e32 v50, v50
	v_mul_f32_e32 v39, v39, v47
	v_lshlrev_b32_e32 v47, 16, v40
	v_and_b32_e32 v40, 0xffff0000, v40
	v_mul_f32_e32 v51, 0xbfb8aa3b, v40
	v_exp_f32_e32 v51, v51
	v_mul_f32_e32 v46, v50, v46
	v_mul_f32_e32 v50, 0xbfb8aa3b, v47
	v_exp_f32_e32 v50, v50
	v_add_f32_e32 v51, 1.0, v51
	v_rcp_f32_e32 v51, v51
	v_mul_f32_e32 v46, v46, v52
	v_add_f32_e32 v50, 1.0, v50
	v_rcp_f32_e32 v50, v50
	v_lshlrev_b32_e32 v52, 16, v48
	v_and_b32_e32 v48, 0xffff0000, v48
	v_mul_f32_e32 v40, v51, v40
	v_mul_f32_e32 v40, v40, v48
	v_lshlrev_b32_e32 v48, 16, v41
	v_and_b32_e32 v41, 0xffff0000, v41
	v_mul_f32_e32 v51, 0xbfb8aa3b, v41
	v_mul_f32_e32 v47, v50, v47
	v_mul_f32_e32 v50, 0xbfb8aa3b, v48
	v_exp_f32_e32 v51, v51
	v_exp_f32_e32 v50, v50
	v_mul_f32_e32 v47, v47, v52
	v_lshlrev_b32_e32 v52, 16, v49
	v_add_f32_e32 v51, 1.0, v51
	v_add_f32_e32 v50, 1.0, v50
	v_rcp_f32_e32 v51, v51
	v_rcp_f32_e32 v50, v50
	v_and_b32_e32 v49, 0xffff0000, v49
	v_cvt_pk_bf16_f32 v38, v37, v38
	v_mul_f32_e32 v41, v51, v41
	v_mul_f32_e32 v48, v50, v48
	v_mul_f32_e32 v41, v41, v49
	v_mul_f32_e32 v48, v48, v52
	v_cvt_pk_bf16_f32 v39, v46, v39
	v_cvt_pk_bf16_f32 v40, v47, v40
	v_cvt_pk_bf16_f32 v41, v48, v41
	global_store_dwordx4 v[34:35], v[38:41], off
	v_add_u32_e32 v34, v36, v196
	ds_read_b128 v[38:41], v34
	s_waitcnt vmcnt(7)
	v_lshlrev_b32_e32 v34, 16, v42
	v_and_b32_e32 v37, 0xffff0000, v42
	v_mul_f32_e32 v35, 0xbfb8aa3b, v34
	v_mul_f32_e32 v42, 0xbfb8aa3b, v37
	v_exp_f32_e32 v35, v35
	v_exp_f32_e32 v42, v42
	s_waitcnt lgkmcnt(0)
	v_lshlrev_b32_e32 v46, 16, v38
	v_add_f32_e32 v35, 1.0, v35
	v_add_f32_e32 v42, 1.0, v42
	v_rcp_f32_e32 v35, v35
	v_rcp_f32_e32 v42, v42
	v_mul_f32_e32 v34, v35, v34
	v_and_b32_e32 v35, 0xffff0000, v38
	v_mul_f32_e32 v37, v42, v37
	v_mul_f32_e32 v35, v37, v35
	v_lshlrev_b32_e32 v37, 16, v43
	v_and_b32_e32 v42, 0xffff0000, v43
	v_mul_f32_e32 v38, 0xbfb8aa3b, v37
	v_mul_f32_e32 v43, 0xbfb8aa3b, v42
	v_exp_f32_e32 v38, v38
	v_exp_f32_e32 v43, v43
	v_mul_f32_e32 v34, v34, v46
	v_lshlrev_b32_e32 v46, 16, v39
	v_add_f32_e32 v38, 1.0, v38
	v_add_f32_e32 v43, 1.0, v43
	v_rcp_f32_e32 v38, v38
	v_rcp_f32_e32 v43, v43
	v_mul_f32_e32 v37, v38, v37
	v_and_b32_e32 v38, 0xffff0000, v39
	v_mul_f32_e32 v39, v43, v42
	v_mul_f32_e32 v39, v39, v38
	v_lshlrev_b32_e32 v38, 16, v44
	v_mul_f32_e32 v42, 0xbfb8aa3b, v38
	v_and_b32_e32 v43, 0xffff0000, v44
	v_exp_f32_e32 v42, v42
	v_mul_f32_e32 v44, 0xbfb8aa3b, v43
	v_exp_f32_e32 v44, v44
	v_mul_f32_e32 v37, v37, v46
	v_add_f32_e32 v42, 1.0, v42
	v_rcp_f32_e32 v42, v42
	v_add_f32_e32 v44, 1.0, v44
	v_rcp_f32_e32 v44, v44
	v_lshlrev_b32_e32 v46, 16, v40
	v_mul_f32_e32 v38, v42, v38
	v_mul_f32_e32 v42, v38, v46
	v_and_b32_e32 v38, 0xffff0000, v40
	v_mul_f32_e32 v40, v44, v43
	v_mul_f32_e32 v40, v40, v38
	v_lshlrev_b32_e32 v38, 16, v45
	v_mul_f32_e32 v43, 0xbfb8aa3b, v38
	v_and_b32_e32 v44, 0xffff0000, v45
	v_exp_f32_e32 v43, v43
	v_mul_f32_e32 v45, 0xbfb8aa3b, v44
	v_exp_f32_e32 v45, v45
	v_lshlrev_b32_e32 v46, 16, v41
	v_add_f32_e32 v43, 1.0, v43
	v_rcp_f32_e32 v43, v43
	v_add_f32_e32 v45, 1.0, v45
	v_rcp_f32_e32 v45, v45
	v_mul_f32_e32 v38, v43, v38
	v_mul_f32_e32 v43, v38, v46
	v_and_b32_e32 v38, 0xffff0000, v41
	v_mul_f32_e32 v41, v45, v44
	v_mul_f32_e32 v41, v41, v38
	v_cvt_pk_bf16_f32 v38, v34, v35
	v_cvt_pk_bf16_f32 v39, v37, v39
	s_waitcnt vmcnt(6)
	v_lshlrev_b32_e32 v37, 16, v16
	v_and_b32_e32 v16, 0xffff0000, v16
	v_cvt_pk_bf16_f32 v40, v42, v40
	v_cvt_pk_bf16_f32 v41, v43, v41
	global_store_dwordx4 v[32:33], v[38:41], off
	v_add_u32_e32 v32, v36, v197
	ds_read_b128 v[32:35], v32
	v_mul_f32_e32 v39, 0xbfb8aa3b, v16
	v_exp_f32_e32 v39, v39
	v_mul_f32_e32 v38, 0xbfb8aa3b, v37
	v_exp_f32_e32 v38, v38
	s_waitcnt lgkmcnt(0)
	v_lshlrev_b32_e32 v40, 16, v32
	v_add_f32_e32 v39, 1.0, v39
	v_rcp_f32_e32 v39, v39
	v_and_b32_e32 v32, 0xffff0000, v32
	v_add_f32_e32 v38, 1.0, v38
	v_rcp_f32_e32 v38, v38
	v_mul_f32_e32 v16, v39, v16
	v_mul_f32_e32 v16, v16, v32
	v_lshlrev_b32_e32 v32, 16, v17
	v_and_b32_e32 v17, 0xffff0000, v17
	v_mul_f32_e32 v39, 0xbfb8aa3b, v17
	v_exp_f32_e32 v39, v39
	v_mul_f32_e32 v37, v38, v37
	v_mul_f32_e32 v38, 0xbfb8aa3b, v32
	v_exp_f32_e32 v38, v38
	v_add_f32_e32 v39, 1.0, v39
	v_rcp_f32_e32 v39, v39
	v_mul_f32_e32 v37, v37, v40
	v_add_f32_e32 v38, 1.0, v38
	v_lshlrev_b32_e32 v40, 16, v33
	v_and_b32_e32 v33, 0xffff0000, v33
	v_mul_f32_e32 v17, v39, v17
	v_rcp_f32_e32 v38, v38
	v_mul_f32_e32 v17, v17, v33
	v_lshlrev_b32_e32 v33, 16, v18
	v_and_b32_e32 v18, 0xffff0000, v18
	v_mul_f32_e32 v39, 0xbfb8aa3b, v18
	v_exp_f32_e32 v39, v39
	v_mul_f32_e32 v32, v38, v32
	v_mul_f32_e32 v38, 0xbfb8aa3b, v33
	v_exp_f32_e32 v38, v38
	v_add_f32_e32 v39, 1.0, v39
	v_rcp_f32_e32 v39, v39
	v_mul_f32_e32 v32, v32, v40
	v_add_f32_e32 v38, 1.0, v38
	v_rcp_f32_e32 v38, v38
	v_lshlrev_b32_e32 v40, 16, v34
	v_and_b32_e32 v34, 0xffff0000, v34
	v_mul_f32_e32 v18, v39, v18
	v_mul_f32_e32 v18, v18, v34
	v_lshlrev_b32_e32 v34, 16, v19
	v_and_b32_e32 v19, 0xffff0000, v19
	v_mul_f32_e32 v39, 0xbfb8aa3b, v19
	v_mul_f32_e32 v33, v38, v33
	v_mul_f32_e32 v38, 0xbfb8aa3b, v34
	v_exp_f32_e32 v39, v39
	v_exp_f32_e32 v38, v38
	v_mul_f32_e32 v33, v33, v40
	v_lshlrev_b32_e32 v40, 16, v35
	v_add_f32_e32 v39, 1.0, v39
	v_add_f32_e32 v38, 1.0, v38
	v_rcp_f32_e32 v39, v39
	v_rcp_f32_e32 v38, v38
	v_and_b32_e32 v35, 0xffff0000, v35
	v_cvt_pk_bf16_f32 v16, v37, v16
	v_mul_f32_e32 v19, v39, v19
	v_mul_f32_e32 v34, v38, v34
	v_mul_f32_e32 v19, v19, v35
	v_mul_f32_e32 v34, v34, v40
	v_cvt_pk_bf16_f32 v17, v32, v17
	v_cvt_pk_bf16_f32 v18, v33, v18
	v_cvt_pk_bf16_f32 v19, v34, v19
	global_store_dwordx4 v[30:31], v[16:19], off
	s_waitcnt vmcnt(7)
; __device__ __forceinline__ float bf2f(short s) { return __uint_as_float(((unsigned)(unsigned short)s) << 16); }
; __device__ __forceinline__ float silu_fast(float g) { return g * __builtin_amdgcn_rcpf(1.f + __builtin_amdgcn_exp2f(-g * LOG2E)); }
; __device__ __forceinline__ bf16x8 tobf8(f32x8 x) { u32x4 w = {cvtpk(x[0], x[1]), cvtpk(x[2], x[3]), cvtpk(x[4], x[5]), cvtpk(x[6], x[7])}; return *reinterpret_cast<bf16x8*>(&w); }
; template <int MODE, bool SAMPLE>
; __device__ __forceinline__ void attn_unit(const Params& p, char* lds, int b, int h, int qb) {
;     ...
;         for (int it = 0; it < NIT; ++it) { const int row = it * 4 + er; const bf16x8 mx = *(const bf16x8*)(Qs + row * 256 + ec * 2); f32x8 y;
; #pragma unroll
;             for (int i = 0; i < 8; ++i) y[i] = bf2f(mx[i]) * silu_fast(bf2f(gt[it][i]));
;             *(bf16x8*)(MIX + (rbase + row) * DM + MODE * 1024 + h * HD + ec) = tobf8(y); }
	v_lshlrev_b32_e32 v30, 16, v12
	v_and_b32_e32 v12, 0xffff0000, v12
	v_mul_f32_e32 v32, 0xbfb8aa3b, v12
	v_exp_f32_e32 v32, v32
	v_add_u32_e32 v16, v36, v171
	ds_read_b128 v[16:19], v16
	v_mul_f32_e32 v31, 0xbfb8aa3b, v30
	v_add_f32_e32 v32, 1.0, v32
	v_rcp_f32_e32 v32, v32
	v_exp_f32_e32 v31, v31
	s_waitcnt lgkmcnt(0)
	v_lshlrev_b32_e32 v33, 16, v16
	v_and_b32_e32 v16, 0xffff0000, v16
	v_mul_f32_e32 v12, v32, v12
	v_mul_f32_e32 v12, v12, v16
	v_lshlrev_b32_e32 v16, 16, v13
	v_and_b32_e32 v13, 0xffff0000, v13
	v_add_f32_e32 v31, 1.0, v31
	v_mul_f32_e32 v32, 0xbfb8aa3b, v13
	v_rcp_f32_e32 v31, v31
	v_exp_f32_e32 v32, v32
	v_mul_f32_e32 v30, v31, v30
	v_mul_f32_e32 v31, 0xbfb8aa3b, v16
	v_add_f32_e32 v32, 1.0, v32
	v_exp_f32_e32 v31, v31
	v_rcp_f32_e32 v32, v32
	v_mul_f32_e32 v30, v30, v33
	v_lshlrev_b32_e32 v33, 16, v17
	v_add_f32_e32 v31, 1.0, v31
	v_and_b32_e32 v17, 0xffff0000, v17
	v_mul_f32_e32 v13, v32, v13
	v_rcp_f32_e32 v31, v31
	v_mul_f32_e32 v13, v13, v17
	v_lshlrev_b32_e32 v17, 16, v14
	v_and_b32_e32 v14, 0xffff0000, v14
	v_mul_f32_e32 v32, 0xbfb8aa3b, v14
	v_exp_f32_e32 v32, v32
	v_mul_f32_e32 v16, v31, v16
	v_mul_f32_e32 v31, 0xbfb8aa3b, v17
	v_exp_f32_e32 v31, v31
	v_add_f32_e32 v32, 1.0, v32
	v_rcp_f32_e32 v32, v32
	v_mul_f32_e32 v16, v16, v33
	v_add_f32_e32 v31, 1.0, v31
	v_rcp_f32_e32 v31, v31
	v_lshlrev_b32_e32 v33, 16, v18
	v_and_b32_e32 v18, 0xffff0000, v18
	v_mul_f32_e32 v14, v32, v14
	v_mul_f32_e32 v14, v14, v18
	v_lshlrev_b32_e32 v18, 16, v15
	v_and_b32_e32 v15, 0xffff0000, v15
	v_mul_f32_e32 v32, 0xbfb8aa3b, v15
	v_mul_f32_e32 v17, v31, v17
	v_mul_f32_e32 v31, 0xbfb8aa3b, v18
	v_exp_f32_e32 v32, v32
	v_exp_f32_e32 v31, v31
	v_mul_f32_e32 v17, v17, v33
	v_lshlrev_b32_e32 v33, 16, v19
	v_add_f32_e32 v32, 1.0, v32
	v_add_f32_e32 v31, 1.0, v31
	v_rcp_f32_e32 v32, v32
	v_rcp_f32_e32 v31, v31
	v_and_b32_e32 v19, 0xffff0000, v19
	v_cvt_pk_bf16_f32 v12, v30, v12
	v_mul_f32_e32 v15, v32, v15
	v_cvt_pk_bf16_f32 v13, v16, v13
	v_cvt_pk_bf16_f32 v14, v17, v14
	v_lshlrev_b64 v[16:17], 12, v[28:29]
	v_mul_f32_e32 v18, v31, v18
	v_mul_f32_e32 v15, v15, v19
	v_lshl_add_u64 v[16:17], v[22:23], 0, v[16:17]
	v_mul_f32_e32 v18, v18, v33
	v_cvt_pk_bf16_f32 v15, v18, v15
	global_store_dwordx4 v[16:17], v[12:15], off
	s_waitcnt vmcnt(7)
	v_lshlrev_b32_e32 v16, 16, v8
	v_and_b32_e32 v8, 0xffff0000, v8
	v_mul_f32_e32 v18, 0xbfb8aa3b, v8
	v_exp_f32_e32 v18, v18
	v_add_u32_e32 v12, v36, v210
	ds_read_b128 v[12:15], v12
	v_mul_f32_e32 v17, 0xbfb8aa3b, v16
	v_add_f32_e32 v18, 1.0, v18
	v_rcp_f32_e32 v18, v18
	v_exp_f32_e32 v17, v17
	s_waitcnt lgkmcnt(0)
	v_lshlrev_b32_e32 v19, 16, v12
	v_and_b32_e32 v12, 0xffff0000, v12
	v_mul_f32_e32 v8, v18, v8
	v_mul_f32_e32 v8, v8, v12
	v_lshlrev_b32_e32 v12, 16, v9
	v_and_b32_e32 v9, 0xffff0000, v9
	v_add_f32_e32 v17, 1.0, v17
	v_mul_f32_e32 v18, 0xbfb8aa3b, v9
	v_rcp_f32_e32 v17, v17
	v_exp_f32_e32 v18, v18
	v_mul_f32_e32 v16, v17, v16
	v_mul_f32_e32 v17, 0xbfb8aa3b, v12
	v_add_f32_e32 v18, 1.0, v18
	v_exp_f32_e32 v17, v17
	v_rcp_f32_e32 v18, v18
	v_mul_f32_e32 v16, v16, v19
	v_lshlrev_b32_e32 v19, 16, v13
	v_add_f32_e32 v17, 1.0, v17
	v_and_b32_e32 v13, 0xffff0000, v13
	v_mul_f32_e32 v9, v18, v9
	v_rcp_f32_e32 v17, v17
	v_mul_f32_e32 v9, v9, v13
	v_lshlrev_b32_e32 v13, 16, v10
	v_and_b32_e32 v10, 0xffff0000, v10
	v_mul_f32_e32 v18, 0xbfb8aa3b, v10
	v_exp_f32_e32 v18, v18
	v_mul_f32_e32 v12, v17, v12
	v_mul_f32_e32 v17, 0xbfb8aa3b, v13
	v_exp_f32_e32 v17, v17
	v_add_f32_e32 v18, 1.0, v18
	v_rcp_f32_e32 v18, v18
	v_mul_f32_e32 v12, v12, v19
	v_add_f32_e32 v17, 1.0, v17
	v_rcp_f32_e32 v17, v17
	v_lshlrev_b32_e32 v19, 16, v14
	v_and_b32_e32 v14, 0xffff0000, v14
	v_mul_f32_e32 v10, v18, v10
	v_mul_f32_e32 v10, v10, v14
	v_lshlrev_b32_e32 v14, 16, v11
	v_and_b32_e32 v11, 0xffff0000, v11
	v_mul_f32_e32 v18, 0xbfb8aa3b, v11
	v_mul_f32_e32 v13, v17, v13
	v_mul_f32_e32 v17, 0xbfb8aa3b, v14
	v_exp_f32_e32 v18, v18
	v_exp_f32_e32 v17, v17
	v_mul_f32_e32 v13, v13, v19
	v_lshlrev_b32_e32 v19, 16, v15
	v_add_f32_e32 v18, 1.0, v18
	v_add_f32_e32 v17, 1.0, v17
	v_rcp_f32_e32 v18, v18
	v_rcp_f32_e32 v17, v17
	v_and_b32_e32 v15, 0xffff0000, v15
	v_cvt_pk_bf16_f32 v8, v16, v8
	v_mul_f32_e32 v11, v18, v11
	v_cvt_pk_bf16_f32 v9, v12, v9
	v_cvt_pk_bf16_f32 v10, v13, v10
	v_lshlrev_b64 v[12:13], 12, v[26:27]
	v_mul_f32_e32 v14, v17, v14
	v_mul_f32_e32 v11, v11, v15
	v_lshl_add_u64 v[12:13], v[22:23], 0, v[12:13]
	v_mul_f32_e32 v14, v14, v19
	v_cvt_pk_bf16_f32 v11, v14, v11
	global_store_dwordx4 v[12:13], v[8:11], off
	s_waitcnt vmcnt(7)
	v_lshlrev_b32_e32 v12, 16, v4
	v_and_b32_e32 v4, 0xffff0000, v4
	v_mul_f32_e32 v14, 0xbfb8aa3b, v4
	v_exp_f32_e32 v14, v14
	v_add_u32_e32 v8, v36, v211
	ds_read_b128 v[8:11], v8
	v_mul_f32_e32 v13, 0xbfb8aa3b, v12
	v_add_f32_e32 v14, 1.0, v14
	v_rcp_f32_e32 v14, v14
	v_exp_f32_e32 v13, v13
	s_waitcnt lgkmcnt(0)
; __device__ __forceinline__ float bf2f(short s) { return __uint_as_float(((unsigned)(unsigned short)s) << 16); }
; __device__ __forceinline__ float silu_fast(float g) { return g * __builtin_amdgcn_rcpf(1.f + __builtin_amdgcn_exp2f(-g * LOG2E)); }
; __device__ __forceinline__ bf16x8 tobf8(f32x8 x) { u32x4 w = {cvtpk(x[0], x[1]), cvtpk(x[2], x[3]), cvtpk(x[4], x[5]), cvtpk(x[6], x[7])}; return *reinterpret_cast<bf16x8*>(&w); }
; template <int MODE, bool SAMPLE>
; __device__ __forceinline__ void attn_unit(const Params& p, char* lds, int b, int h, int qb) {
;     ...
;         for (int it = 0; it < NIT; ++it) { const int row = it * 4 + er; const bf16x8 mx = *(const bf16x8*)(Qs + row * 256 + ec * 2); f32x8 y;
; #pragma unroll
;             for (int i = 0; i < 8; ++i) y[i] = bf2f(mx[i]) * silu_fast(bf2f(gt[it][i]));
;             *(bf16x8*)(MIX + (rbase + row) * DM + MODE * 1024 + h * HD + ec) = tobf8(y); }
;     }
;     __syncthreads();
	v_lshlrev_b32_e32 v15, 16, v8
	v_and_b32_e32 v8, 0xffff0000, v8
	v_mul_f32_e32 v4, v14, v4
	v_mul_f32_e32 v4, v4, v8
	v_lshlrev_b32_e32 v8, 16, v5
	v_and_b32_e32 v5, 0xffff0000, v5
	v_add_f32_e32 v13, 1.0, v13
	v_mul_f32_e32 v14, 0xbfb8aa3b, v5
	v_rcp_f32_e32 v13, v13
	v_exp_f32_e32 v14, v14
	v_mul_f32_e32 v12, v13, v12
	v_mul_f32_e32 v13, 0xbfb8aa3b, v8
	v_add_f32_e32 v14, 1.0, v14
	v_exp_f32_e32 v13, v13
	v_rcp_f32_e32 v14, v14
	v_mul_f32_e32 v12, v12, v15
	v_lshlrev_b32_e32 v15, 16, v9
	v_add_f32_e32 v13, 1.0, v13
	v_and_b32_e32 v9, 0xffff0000, v9
	v_mul_f32_e32 v5, v14, v5
	v_rcp_f32_e32 v13, v13
	v_mul_f32_e32 v5, v5, v9
	v_lshlrev_b32_e32 v9, 16, v6
	v_and_b32_e32 v6, 0xffff0000, v6
	v_mul_f32_e32 v14, 0xbfb8aa3b, v6
	v_exp_f32_e32 v14, v14
	v_mul_f32_e32 v8, v13, v8
	v_mul_f32_e32 v13, 0xbfb8aa3b, v9
	v_exp_f32_e32 v13, v13
	v_add_f32_e32 v14, 1.0, v14
	v_rcp_f32_e32 v14, v14
	v_mul_f32_e32 v8, v8, v15
	v_add_f32_e32 v13, 1.0, v13
	v_rcp_f32_e32 v13, v13
	v_lshlrev_b32_e32 v15, 16, v10
	v_and_b32_e32 v10, 0xffff0000, v10
	v_mul_f32_e32 v6, v14, v6
	v_mul_f32_e32 v6, v6, v10
	v_lshlrev_b32_e32 v10, 16, v7
	v_and_b32_e32 v7, 0xffff0000, v7
	v_mul_f32_e32 v14, 0xbfb8aa3b, v7
	v_mul_f32_e32 v9, v13, v9
	v_mul_f32_e32 v13, 0xbfb8aa3b, v10
	v_exp_f32_e32 v14, v14
	v_exp_f32_e32 v13, v13
	v_mul_f32_e32 v9, v9, v15
	v_lshlrev_b32_e32 v15, 16, v11
	v_add_f32_e32 v14, 1.0, v14
	v_add_f32_e32 v13, 1.0, v13
	v_rcp_f32_e32 v14, v14
	v_rcp_f32_e32 v13, v13
	v_and_b32_e32 v11, 0xffff0000, v11
	v_cvt_pk_bf16_f32 v4, v12, v4
	v_mul_f32_e32 v7, v14, v7
	v_cvt_pk_bf16_f32 v5, v8, v5
	v_cvt_pk_bf16_f32 v6, v9, v6
	v_lshlrev_b64 v[8:9], 12, v[24:25]
	v_mul_f32_e32 v10, v13, v10
	v_mul_f32_e32 v7, v7, v11
	v_lshl_add_u64 v[8:9], v[22:23], 0, v[8:9]
	v_mul_f32_e32 v10, v10, v15
	v_cvt_pk_bf16_f32 v7, v10, v7
	global_store_dwordx4 v[8:9], v[4:7], off
	s_waitcnt vmcnt(7)
	v_lshlrev_b32_e32 v8, 16, v0
	v_and_b32_e32 v0, 0xffff0000, v0
	v_mul_f32_e32 v10, 0xbfb8aa3b, v0
	v_exp_f32_e32 v10, v10
	v_add_u32_e32 v4, v36, v212
	ds_read_b128 v[4:7], v4
	v_mul_f32_e32 v9, 0xbfb8aa3b, v8
	v_add_f32_e32 v10, 1.0, v10
	v_rcp_f32_e32 v10, v10
	v_exp_f32_e32 v9, v9
	s_waitcnt lgkmcnt(0)
	v_lshlrev_b32_e32 v11, 16, v4
	v_and_b32_e32 v4, 0xffff0000, v4
	v_mul_f32_e32 v0, v10, v0
	v_mul_f32_e32 v0, v0, v4
	v_lshlrev_b32_e32 v4, 16, v1
	v_and_b32_e32 v1, 0xffff0000, v1
	v_add_f32_e32 v9, 1.0, v9
	v_mul_f32_e32 v10, 0xbfb8aa3b, v1
	v_rcp_f32_e32 v9, v9
	v_exp_f32_e32 v10, v10
	v_mul_f32_e32 v8, v9, v8
	v_mul_f32_e32 v9, 0xbfb8aa3b, v4
	v_add_f32_e32 v10, 1.0, v10
	v_exp_f32_e32 v9, v9
	v_rcp_f32_e32 v10, v10
	v_mul_f32_e32 v8, v8, v11
	v_lshlrev_b32_e32 v11, 16, v5
	v_add_f32_e32 v9, 1.0, v9
	v_and_b32_e32 v5, 0xffff0000, v5
	v_mul_f32_e32 v1, v10, v1
	v_rcp_f32_e32 v9, v9
	v_mul_f32_e32 v1, v1, v5
	v_lshlrev_b32_e32 v5, 16, v2
	v_and_b32_e32 v2, 0xffff0000, v2
	v_mul_f32_e32 v10, 0xbfb8aa3b, v2
	v_exp_f32_e32 v10, v10
	v_mul_f32_e32 v4, v9, v4
	v_mul_f32_e32 v9, 0xbfb8aa3b, v5
	v_exp_f32_e32 v9, v9
	v_add_f32_e32 v10, 1.0, v10
	v_rcp_f32_e32 v10, v10
	v_mul_f32_e32 v4, v4, v11
	v_add_f32_e32 v9, 1.0, v9
	v_rcp_f32_e32 v9, v9
	v_lshlrev_b32_e32 v11, 16, v6
	v_and_b32_e32 v6, 0xffff0000, v6
	v_mul_f32_e32 v2, v10, v2
	v_mul_f32_e32 v2, v2, v6
	v_lshlrev_b32_e32 v6, 16, v3
	v_and_b32_e32 v3, 0xffff0000, v3
	v_mul_f32_e32 v10, 0xbfb8aa3b, v3
	v_mul_f32_e32 v5, v9, v5
	v_mul_f32_e32 v9, 0xbfb8aa3b, v6
	v_exp_f32_e32 v10, v10
	v_exp_f32_e32 v9, v9
	v_mul_f32_e32 v5, v5, v11
	v_lshlrev_b32_e32 v11, 16, v7
	v_add_f32_e32 v10, 1.0, v10
	v_add_f32_e32 v9, 1.0, v9
	v_rcp_f32_e32 v10, v10
	v_rcp_f32_e32 v9, v9
	v_and_b32_e32 v7, 0xffff0000, v7
	v_cvt_pk_bf16_f32 v0, v8, v0
	v_mul_f32_e32 v3, v10, v3
	v_cvt_pk_bf16_f32 v1, v4, v1
	v_cvt_pk_bf16_f32 v2, v5, v2
	v_lshlrev_b64 v[4:5], 12, v[20:21]
	v_mul_f32_e32 v6, v9, v6
	v_mul_f32_e32 v3, v3, v7
	v_lshl_add_u64 v[4:5], v[22:23], 0, v[4:5]
	v_mul_f32_e32 v6, v6, v11
	v_cvt_pk_bf16_f32 v3, v6, v3
	global_store_dwordx4 v[4:5], v[0:3], off
	s_barrier
; __device__ __forceinline__ int crow(int r, int hi) { return (r & 3) + 8 * (r >> 2) + 4 * hi; }
; __device__ __forceinline__ int v_st(int k, int c) { const int kk = (k & ~0xC) | ((k & 4) << 1) | ((k & 8) >> 1); return ((kk >> 3) * 4 + (c >> 5)) * 512 + ((kk & 7) * 32 + (c & 31)) * 2; }
; __device__ __forceinline__ int v_rd_base(int lane) { return ((lane & 3) << 3) | (((lane >> 2) & 3) << 6) | (((lane >> 4) & 1) << 5) | (((lane >> 5) & 1) << 8); }
; template <int MODE, bool SAMPLE>
; __device__ __forceinline__ void attn_unit(const Params& p, char* lds, int b, int h, int qb) {
;     ...
;     const bf16_t* Qw = P1q + qrow * 128 + hi * 8;
;     char* Qs = lds + AL_Q + wid * 8192;
; #pragma unroll
;     for (int d0 = 0; d0 < 8; ++d0) *reinterpret_cast<bf16x8*>(Qs + KSWZ(r32, (d0 * 16 + hi * 8) * 2)) = *reinterpret_cast<const bf16x8*>(Qw + d0 * 16);
;     const int qw0 = SAMPLE ? PAST : qb * 256 + wid * 32;
;     const int qpos = SAMPLE ? PAST + (r32 & 15) : qw0 + r32;
;     const int jd = SAMPLE ? 16 : (qw0 >> 6);
;     const int jfirst = SAMPLE ? 16 : qb * 4 + 3;
;     const bool wact = SAMPLE ? (wid == 0) : true;
;     const int sr = tid >> 4, sc = (tid & 15) * 8;
;     const int vst0 = v_st(sr, sc), vst1 = v_st(32 + sr, sc), kst0 = KSWZ(sr, sc * 2), kst1 = KSWZ(32 + sr, sc * 2);
;     const int vb0 = (int)(uintptr_t)V_lds + v_rd_base(lane);
;     struct StgT { bf16x8 k0, k1, v0, v1; f32x8 fk0, fk1, fv0, fv1; } stg2[SAMPLE ? 1 : NSP];
;     ...
;     f32x16 o[4] = {};
;     float m_reg = -1e30f, l_reg = 0.f, carry = 1.f;
;     constexpr int NS = SAMPLE ? 1 : NSP;
;     constexpr int PAR0 = SAMPLE ? 0 : 1;
;     LOADT(jfirst, stg2[NS == 2 ? PAR0 : 0]); if (NS == 2) LOADT(jfirst - 1, stg2[NS == 2 ? (PAR0 ^ 1) : 0]);
;     ...
;                 if (j == jd) {
; #pragma unroll
;                     for (int r = 0; r < 16; ++r) { const int kp = j * 64 + crow(r, hi); if (kp >= qpos) p0[r] = -1e30f; if (kp + 32 >= qpos) p1[r] = -1e30f; } }
	s_nop 0
	v_or_b32_e32 v0, s11, v131
	v_mov_b32_e32 v1, v129
	v_lshlrev_b64 v[0:1], 8, v[0:1]
	v_lshl_add_u64 v[0:1], s[82:83], 0, v[0:1]
	v_lshl_add_u64 v[4:5], v[0:1], 0, v[146:147]
	v_add_co_u32_e32 v0, vcc, s0, v4
	s_nop 1
	v_addc_co_u32_e32 v1, vcc, 0, v5, vcc
	global_load_dwordx4 v[0:3], v[0:1], off
	s_mov_b64 s[0:1], 0xcf00000
	v_lshl_add_u64 v[28:29], v[4:5], 0, s[0:1]
	global_load_dwordx4 v[4:7], v[28:29], off offset:32
	global_load_dwordx4 v[8:11], v[28:29], off offset:64
	global_load_dwordx4 v[12:15], v[28:29], off offset:96
	global_load_dwordx4 v[16:19], v[28:29], off offset:128
	global_load_dwordx4 v[20:23], v[28:29], off offset:160
	global_load_dwordx4 v[24:27], v[28:29], off offset:192
	s_nop 0
	global_load_dwordx4 v[28:31], v[28:29], off offset:224
	s_lshl_b32 s0, s6, 13
	s_add_i32 s12, s0, 0
	s_add_i32 s12, s12, 0x13000
	v_add_u32_e32 v32, s12, v135
	v_add_u32_e32 v33, v32, v139
	s_lshl_b32 s0, s4, 2
	s_or_b32 s16, s0, 3
	s_add_u32 s0, s82, 0xe000000
	s_addc_u32 s1, s83, 0
	s_lshl_b32 s4, s16, 6
	s_add_i32 s4, s4, s22
	s_lshl_b64 s[18:19], s[4:5], 8
	s_add_u32 s18, s0, s18
	s_addc_u32 s19, s1, s19
	s_add_i32 s4, s25, s17
	v_lshl_add_u64 v[164:165], s[0:1], 0, v[144:145]
	s_waitcnt vmcnt(7)
	ds_write_b128 v33, v[0:3]
	v_add_u32_e32 v0, v32, v141
	s_waitcnt vmcnt(6)
	ds_write_b128 v0, v[4:7]
	v_add_u32_e32 v0, v32, v149
	s_waitcnt vmcnt(5)
	ds_write_b128 v0, v[8:11]
	v_add_u32_e32 v0, v32, v151
	s_waitcnt vmcnt(4)
	ds_write_b128 v0, v[12:15]
	v_add_u32_e32 v0, v32, v153
	s_waitcnt vmcnt(3)
	ds_write_b128 v0, v[16:19]
	v_add_u32_e32 v0, v32, v155
	s_waitcnt vmcnt(2)
	ds_write_b128 v0, v[20:23]
	v_add_u32_e32 v0, v32, v172
	s_waitcnt vmcnt(1)
	ds_write_b128 v0, v[24:27]
	v_add_u32_e32 v0, v32, v173
	s_waitcnt vmcnt(0)
	ds_write_b128 v0, v[28:31]
	v_lshl_add_u64 v[0:1], s[18:19], 0, v[144:145]
	s_lshl_b64 s[18:19], s[4:5], 8
	v_lshl_add_u64 v[2:3], v[0:1], 0, v[128:129]
	v_lshl_add_u64 v[4:5], v[0:1], 0, v[160:161]
	v_lshl_add_u64 v[0:1], v[0:1], 0, s[96:97]
	s_add_u32 s18, s0, s18
	global_load_dwordx4 v[96:99], v[2:3], off
	global_load_dwordx4 v[100:103], v[4:5], off
	v_lshl_add_u64 v[2:3], v[0:1], 0, v[128:129]
	v_lshl_add_u64 v[0:1], v[0:1], 0, v[160:161]
	s_addc_u32 s19, s1, s19
	global_load_dwordx4 v[104:107], v[2:3], off
	global_load_dwordx4 v[108:111], v[0:1], off
	v_lshl_add_u64 v[0:1], s[18:19], 0, v[144:145]
	v_lshl_add_u64 v[2:3], v[0:1], 0, v[128:129]
	v_lshl_add_u64 v[4:5], v[0:1], 0, v[160:161]
	v_lshl_add_u64 v[0:1], v[0:1], 0, s[96:97]
	global_load_dwordx4 v[112:115], v[2:3], off
	global_load_dwordx4 v[116:119], v[4:5], off
	v_lshl_add_u64 v[2:3], v[0:1], 0, v[128:129]
	v_lshl_add_u64 v[0:1], v[0:1], 0, v[160:161]
	global_load_dwordx4 v[120:123], v[2:3], off
	global_load_dwordx4 v[124:127], v[0:1], off
	v_or_b32_e32 v6, s20, v131
	s_andn2_b32 s20, s20, 63
	v_or_b32_e32 v0, s20, v181
	v_or_b32_e32 v1, 32, v0
	v_cmp_lt_i32_e64 s[0:1], v1, v6
	v_or_b32_e32 v1, 1, v0
	v_cmp_lt_i32_e64 s[18:19], v1, v6
	v_or_b32_e32 v1, 33, v0
	v_cmp_lt_i32_e64 s[20:21], v1, v6
	v_or_b32_e32 v1, 2, v0
	v_cmp_lt_i32_e64 s[22:23], v1, v6
	v_or_b32_e32 v1, 34, v0
	v_cmp_lt_i32_e64 s[24:25], v1, v6
	v_or_b32_e32 v1, 3, v0
	v_cmp_lt_i32_e64 s[26:27], v1, v6
	v_or_b32_e32 v1, 35, v0
	v_cmp_lt_i32_e64 s[28:29], v1, v6
	v_or_b32_e32 v1, 8, v0
	v_cmp_lt_i32_e64 s[30:31], v1, v6
	v_or_b32_e32 v1, 40, v0
	v_cmp_lt_i32_e64 s[34:35], v1, v6
	v_or_b32_e32 v1, 9, v0
	v_cmp_lt_i32_e64 s[36:37], v1, v6
	v_or_b32_e32 v1, 41, v0
	v_cmp_lt_i32_e64 s[38:39], v1, v6
	v_or_b32_e32 v1, 10, v0
	v_cmp_lt_i32_e64 s[40:41], v1, v6
	v_or_b32_e32 v1, 42, v0
	v_cmp_lt_i32_e64 s[42:43], v1, v6
	v_or_b32_e32 v1, 11, v0
	v_cmp_lt_i32_e64 s[44:45], v1, v6
	v_or_b32_e32 v1, 43, v0
	v_cmp_lt_i32_e64 s[46:47], v1, v6
	v_or_b32_e32 v1, 16, v0
	v_cmp_lt_i32_e64 s[48:49], v1, v6
	v_or_b32_e32 v1, 48, v0
	v_cmp_lt_i32_e64 s[50:51], v1, v6
	v_or_b32_e32 v1, 17, v0
	v_cmp_lt_i32_e64 s[52:53], v1, v6
	v_or_b32_e32 v1, 49, v0
	v_cmp_lt_i32_e64 s[54:55], v1, v6
	v_or_b32_e32 v1, 18, v0
	v_cmp_lt_i32_e64 s[56:57], v1, v6
	v_or_b32_e32 v1, 50, v0
	v_cmp_lt_i32_e64 s[58:59], v1, v6
	v_or_b32_e32 v1, 19, v0
	v_cmp_lt_i32_e64 s[60:61], v1, v6
	v_or_b32_e32 v1, 51, v0
	v_cmp_lt_i32_e64 s[62:63], v1, v6
	v_or_b32_e32 v1, 24, v0
	v_cmp_lt_i32_e64 s[64:65], v1, v6
	v_or_b32_e32 v1, 56, v0
	v_cmp_lt_i32_e64 s[66:67], v1, v6
	v_or_b32_e32 v1, 25, v0
	v_cmp_lt_i32_e64 s[68:69], v1, v6
	v_or_b32_e32 v1, 57, v0
	v_cmp_lt_i32_e64 s[70:71], v1, v6
	v_or_b32_e32 v1, 26, v0
	s_lshr_b32 s4, s16, 1
	v_cmp_lt_i32_e64 s[72:73], v1, v6
	v_or_b32_e32 v1, 58, v0
	v_cmp_lt_i32_e32 vcc, v0, v6
	v_cmp_lt_i32_e64 s[74:75], v1, v6
	v_or_b32_e32 v1, 27, v0
	v_or_b32_e32 v0, 59, v0
	s_lshl_b32 s6, s4, 7
	v_mov_b32_e32 v14, v129
	v_mov_b32_e32 v15, v129
	v_cmp_lt_i32_e64 s[76:77], v1, v6
	v_cmp_lt_i32_e64 s[78:79], v0, v6
	s_add_i32 s6, s33, s6
	v_mov_b32_e32 v0, v129
	v_mov_b32_e32 v1, v129
	v_mov_b32_e32 v2, v129
	v_mov_b32_e32 v3, v129
	v_mov_b32_e32 v4, v129
	v_mov_b32_e32 v5, v129
	v_mov_b32_e32 v6, v129
	v_mov_b32_e32 v7, v129
	v_mov_b32_e32 v8, v129
	v_mov_b32_e32 v9, v129
	v_mov_b32_e32 v10, v129
	v_mov_b32_e32 v11, v129
	v_mov_b32_e32 v12, v129
	v_mov_b32_e32 v13, v129
	v_mov_b64_e32 v[30:31], v[14:15]
	v_mov_b64_e32 v[46:47], v[14:15]
	v_mov_b64_e32 v[62:63], v[14:15]
	s_add_i32 s86, s6, 0xffffff80
	s_sub_i32 s17, 0, s4
	s_and_b32 s33, s16, 0x7ffffffe
	s_add_i32 s6, s13, -1
	v_mov_b32_e32 v145, 1.0
	v_mov_b64_e32 v[28:29], v[12:13]
	v_mov_b64_e32 v[26:27], v[10:11]
	v_mov_b64_e32 v[24:25], v[8:9]
	v_mov_b64_e32 v[22:23], v[6:7]
	v_mov_b64_e32 v[20:21], v[4:5]
	v_mov_b64_e32 v[18:19], v[2:3]
	v_mov_b64_e32 v[16:17], v[0:1]
	v_mov_b64_e32 v[44:45], v[12:13]
	v_mov_b64_e32 v[42:43], v[10:11]
	v_mov_b64_e32 v[40:41], v[8:9]
	v_mov_b64_e32 v[38:39], v[6:7]
	v_mov_b64_e32 v[36:37], v[4:5]
	v_mov_b64_e32 v[34:35], v[2:3]
	v_mov_b64_e32 v[32:33], v[0:1]
	v_mov_b64_e32 v[60:61], v[12:13]
	v_mov_b64_e32 v[58:59], v[10:11]
	v_mov_b64_e32 v[56:57], v[8:9]
	v_mov_b64_e32 v[54:55], v[6:7]
	v_mov_b64_e32 v[52:53], v[4:5]
	v_mov_b64_e32 v[50:51], v[2:3]
	v_mov_b64_e32 v[48:49], v[0:1]
	s_branch .LBB0_708

; __device__ __forceinline__ unsigned cvtpk(float lo, float hi) { unsigned r; asm volatile("v_cvt_pk_bf16_f32 %0, %1, %2" : "=v"(r) : "v"(lo), "v"(hi)); return r; }
; __device__ __forceinline__ int crow(int r, int hi) { return (r & 3) + 8 * (r >> 2) + 4 * hi; }
; template <int MODE, bool SAMPLE>
; __device__ __forceinline__ void attn_unit(const Params& p, char* lds, int b, int h, int qb) {
;     ...
;     if (wact && var < 1) {
;         bf16_t* MIX = (bf16_t*)(p.ws + (var == 0 ? WS_MIX : WS_ACT));
;         const size_t rbase = SAMPLE ? (size_t)(MP + b * TS) : (size_t)(b * SEQ + qb * 256 + wid * 32);
;         constexpr int NIT = SAMPLE ? 4 : 8; const int er = lane >> 4, ec = (lane & 15) * 8;
;         float rli[16];
;         if (MODE == 0) { if (hi == 0) wsc[32 + r32] = l_reg; asm volatile("s_waitcnt lgkmcnt(0)" ::: "memory");
; #pragma unroll
;             for (int r = 0; r < 16; ++r) rli[r] = __builtin_amdgcn_rcpf(wsc[32 + crow(r, hi)]); }
; #pragma unroll
;         for (int r = 0; r < 16; ++r) { const int orow = crow(r, hi);
;             if (!SAMPLE || orow < TS) {
; #pragma unroll
;                 for (int d0 = 0; d0 < 4; ++d0) { float ov = o[d0][r]; if (MODE == 0) ov *= rli[r];
;                     const unsigned pk = cvtpk(ov, 0.f); *(bf16_t*)(Qs + orow * 256 + (d0 * 32 + r32) * 2) = (bf16_t)(pk & 0xffffu); } } }
;         asm volatile("s_waitcnt lgkmcnt(0)" ::: "memory");
;         bf16x8 gt[NIT];
; #pragma unroll
;         for (int it = 0; it < NIT; ++it) gt[it] = __builtin_nontemporal_load((const bf16x8*)(P1q + 24 * HB + (rbase + it * 4 + er) * 128 + ec));
.LBB0_725:
	s_waitcnt vmcnt(0)
	s_setprio 0
	v_add3_u32 v64, s10, v191, v192
	v_cvt_pk_bf16_f32 v48, v48, v129
	ds_write_b16 v64, v48
	v_cvt_pk_bf16_f32 v32, v32, v129
	ds_write_b16 v64, v32 offset:64
	v_cvt_pk_bf16_f32 v16, v16, v129
	ds_write_b16 v64, v16 offset:128
	v_cvt_pk_bf16_f32 v0, v0, v129
	s_nop 2
	ds_write_b16 v64, v0 offset:192
	v_cvt_pk_bf16_f32 v0, v49, v129
	ds_write_b16 v64, v0 offset:256
	v_cvt_pk_bf16_f32 v0, v33, v129
	ds_write_b16 v64, v0 offset:320
	v_cvt_pk_bf16_f32 v0, v17, v129
	ds_write_b16 v64, v0 offset:384
	v_cvt_pk_bf16_f32 v0, v1, v129
	ds_write_b16 v64, v0 offset:448
	v_cvt_pk_bf16_f32 v0, v50, v129
	ds_write_b16 v64, v0 offset:512
	v_cvt_pk_bf16_f32 v0, v34, v129
	ds_write_b16 v64, v0 offset:576
	v_cvt_pk_bf16_f32 v0, v18, v129
	ds_write_b16 v64, v0 offset:640
	v_cvt_pk_bf16_f32 v0, v2, v129
	ds_write_b16 v64, v0 offset:704
	v_cvt_pk_bf16_f32 v0, v51, v129
	ds_write_b16 v64, v0 offset:768
	v_cvt_pk_bf16_f32 v0, v35, v129
	ds_write_b16 v64, v0 offset:832
	v_cvt_pk_bf16_f32 v0, v19, v129
	ds_write_b16 v64, v0 offset:896
	v_cvt_pk_bf16_f32 v0, v3, v129
	ds_write_b16 v64, v0 offset:960
	v_cvt_pk_bf16_f32 v0, v52, v129
	ds_write_b16 v64, v0 offset:2048
	v_cvt_pk_bf16_f32 v0, v36, v129
	ds_write_b16 v64, v0 offset:2112
	v_cvt_pk_bf16_f32 v0, v20, v129
	ds_write_b16 v64, v0 offset:2176
	v_cvt_pk_bf16_f32 v0, v4, v129
	ds_write_b16 v64, v0 offset:2240
	v_cvt_pk_bf16_f32 v0, v53, v129
	ds_write_b16 v64, v0 offset:2304
	v_cvt_pk_bf16_f32 v0, v37, v129
	ds_write_b16 v64, v0 offset:2368
	v_cvt_pk_bf16_f32 v0, v21, v129
	ds_write_b16 v64, v0 offset:2432
	v_cvt_pk_bf16_f32 v0, v5, v129
	ds_write_b16 v64, v0 offset:2496
	v_cvt_pk_bf16_f32 v0, v54, v129
	ds_write_b16 v64, v0 offset:2560
	v_cvt_pk_bf16_f32 v0, v38, v129
	ds_write_b16 v64, v0 offset:2624
	v_cvt_pk_bf16_f32 v0, v22, v129
	ds_write_b16 v64, v0 offset:2688
	v_cvt_pk_bf16_f32 v0, v6, v129
	ds_write_b16 v64, v0 offset:2752
	v_cvt_pk_bf16_f32 v0, v55, v129
	ds_write_b16 v64, v0 offset:2816
	v_cvt_pk_bf16_f32 v0, v39, v129
	ds_write_b16 v64, v0 offset:2880
	v_cvt_pk_bf16_f32 v0, v23, v129
	ds_write_b16 v64, v0 offset:2944
	v_cvt_pk_bf16_f32 v0, v7, v129
	ds_write_b16 v64, v0 offset:3008
	v_cvt_pk_bf16_f32 v0, v56, v129
	ds_write_b16 v64, v0 offset:4096
	v_cvt_pk_bf16_f32 v0, v40, v129
	ds_write_b16 v64, v0 offset:4160
	v_cvt_pk_bf16_f32 v0, v24, v129
	ds_write_b16 v64, v0 offset:4224
	v_cvt_pk_bf16_f32 v0, v8, v129
	ds_write_b16 v64, v0 offset:4288
	v_cvt_pk_bf16_f32 v0, v57, v129
	ds_write_b16 v64, v0 offset:4352
	v_cvt_pk_bf16_f32 v0, v41, v129
	ds_write_b16 v64, v0 offset:4416
	v_cvt_pk_bf16_f32 v0, v25, v129
	ds_write_b16 v64, v0 offset:4480
	v_cvt_pk_bf16_f32 v0, v9, v129
	ds_write_b16 v64, v0 offset:4544
	v_cvt_pk_bf16_f32 v0, v58, v129
	ds_write_b16 v64, v0 offset:4608
	v_cvt_pk_bf16_f32 v0, v42, v129
	ds_write_b16 v64, v0 offset:4672
	v_cvt_pk_bf16_f32 v0, v26, v129
	ds_write_b16 v64, v0 offset:4736
	v_cvt_pk_bf16_f32 v0, v10, v129
	ds_write_b16 v64, v0 offset:4800
	v_cvt_pk_bf16_f32 v0, v59, v129
	ds_write_b16 v64, v0 offset:4864
	v_cvt_pk_bf16_f32 v0, v43, v129
	ds_write_b16 v64, v0 offset:4928
	v_cvt_pk_bf16_f32 v0, v27, v129
	ds_write_b16 v64, v0 offset:4992
	v_cvt_pk_bf16_f32 v0, v11, v129
	ds_write_b16 v64, v0 offset:5056
	v_cvt_pk_bf16_f32 v0, v60, v129
	ds_write_b16 v64, v0 offset:6144
	v_cvt_pk_bf16_f32 v0, v44, v129
	ds_write_b16 v64, v0 offset:6208
	v_cvt_pk_bf16_f32 v0, v28, v129
	ds_write_b16 v64, v0 offset:6272
	v_cvt_pk_bf16_f32 v0, v12, v129
	ds_write_b16 v64, v0 offset:6336
	v_cvt_pk_bf16_f32 v0, v61, v129
	ds_write_b16 v64, v0 offset:6400
	v_cvt_pk_bf16_f32 v0, v45, v129
	ds_write_b16 v64, v0 offset:6464
	v_cvt_pk_bf16_f32 v0, v29, v129
	ds_write_b16 v64, v0 offset:6528
	v_cvt_pk_bf16_f32 v0, v13, v129
	ds_write_b16 v64, v0 offset:6592
	v_cvt_pk_bf16_f32 v0, v62, v129
	ds_write_b16 v64, v0 offset:6656
	v_cvt_pk_bf16_f32 v0, v46, v129
	ds_write_b16 v64, v0 offset:6720
	v_cvt_pk_bf16_f32 v0, v30, v129
	ds_write_b16 v64, v0 offset:6784
	v_cvt_pk_bf16_f32 v0, v14, v129
	ds_write_b16 v64, v0 offset:6848
	v_cvt_pk_bf16_f32 v0, v63, v129
	ds_write_b16 v64, v0 offset:6912
	v_cvt_pk_bf16_f32 v0, v47, v129
	ds_write_b16 v64, v0 offset:6976
	v_cvt_pk_bf16_f32 v0, v31, v129
	ds_write_b16 v64, v0 offset:7040
	v_cvt_pk_bf16_f32 v0, v15, v129
	v_mov_b32_e32 v147, v129
	ds_write_b16 v64, v0 offset:7104
	v_or_b32_e32 v34, s9, v132
	v_lshl_add_u64 v[0:1], s[82:83], 0, v[146:147]
	s_mov_b64 s[0:1], 0x10200000
	v_mov_b32_e32 v35, v129
	v_lshl_add_u64 v[4:5], v[0:1], 0, s[0:1]
	v_lshlrev_b64 v[0:1], 8, v[34:35]
	s_waitcnt lgkmcnt(0)
	v_lshl_add_u64 v[0:1], v[4:5], 0, v[0:1]
	global_load_dwordx4 v[0:3], v[0:1], off nt
	v_or_b32_e32 v6, 4, v34
	v_mov_b32_e32 v7, v129
	v_lshlrev_b64 v[6:7], 8, v[6:7]
	v_lshl_add_u64 v[8:9], v[4:5], 0, v[6:7]
	v_or_b32_e32 v6, 8, v34
	v_mov_b32_e32 v7, v129
	v_lshlrev_b64 v[6:7], 8, v[6:7]
	v_lshl_add_u64 v[10:11], v[4:5], 0, v[6:7]
	v_or_b32_e32 v6, 12, v34
	v_mov_b32_e32 v7, v129
	v_lshlrev_b64 v[6:7], 8, v[6:7]
	global_load_dwordx4 v[22:25], v[8:9], off nt
	v_lshl_add_u64 v[12:13], v[4:5], 0, v[6:7]
	v_or_b32_e32 v6, 16, v34
	v_mov_b32_e32 v7, v129
	v_lshlrev_b64 v[6:7], 8, v[6:7]
	v_lshl_add_u64 v[14:15], v[4:5], 0, v[6:7]
	v_or_b32_e32 v6, 20, v34
	v_mov_b32_e32 v7, v129
	v_lshlrev_b64 v[6:7], 8, v[6:7]
	v_lshl_add_u64 v[30:31], v[4:5], 0, v[6:7]
	v_or_b32_e32 v6, 24, v34
	v_mov_b32_e32 v7, v129
	v_lshlrev_b64 v[6:7], 8, v[6:7]
	v_lshl_add_u64 v[32:33], v[4:5], 0, v[6:7]
	v_or_b32_e32 v6, 28, v34
	v_mov_b32_e32 v7, v129
	v_lshlrev_b64 v[6:7], 8, v[6:7]
	v_add_u32_e32 v20, s10, v134
	v_lshl_add_u64 v[36:37], v[4:5], 0, v[6:7]
	v_add_u32_e32 v4, v20, v193
	ds_read_b128 v[4:7], v4
	v_lshlrev_b64 v[34:35], 12, v[34:35]
	v_lshl_add_u64 v[34:35], s[92:93], 0, v[34:35]
	s_lshl_b32 s2, s8, 1
	v_lshl_add_u64 v[34:35], v[34:35], 0, s[2:3]
	s_waitcnt lgkmcnt(0)
; __device__ __forceinline__ float bf2f(short s) { return __uint_as_float(((unsigned)(unsigned short)s) << 16); }
; __device__ __forceinline__ float silu_fast(float g) { return g * __builtin_amdgcn_rcpf(1.f + __builtin_amdgcn_exp2f(-g * LOG2E)); }
; __device__ __forceinline__ bf16x8 tobf8(f32x8 x) { u32x4 w = {cvtpk(x[0], x[1]), cvtpk(x[2], x[3]), cvtpk(x[4], x[5]), cvtpk(x[6], x[7])}; return *reinterpret_cast<bf16x8*>(&w); }
; template <int MODE, bool SAMPLE>
; __device__ __forceinline__ void attn_unit(const Params& p, char* lds, int b, int h, int qb) {
;     ...
;         for (int it = 0; it < NIT; ++it) gt[it] = __builtin_nontemporal_load((const bf16x8*)(P1q + 24 * HB + (rbase + it * 4 + er) * 128 + ec));
; #pragma unroll
;         for (int it = 0; it < NIT; ++it) { const int row = it * 4 + er; const bf16x8 mx = *(const bf16x8*)(Qs + row * 256 + ec * 2); f32x8 y;
; #pragma unroll
;             for (int i = 0; i < 8; ++i) y[i] = bf2f(mx[i]) * silu_fast(bf2f(gt[it][i]));
;             *(bf16x8*)(MIX + (rbase + row) * DM + MODE * 1024 + h * HD + ec) = tobf8(y); }
	v_lshlrev_b32_e32 v17, 16, v4
	v_and_b32_e32 v4, 0xffff0000, v4
	v_lshl_add_u64 v[34:35], v[34:35], 0, v[146:147]
	v_add_co_u32_e32 v34, vcc, s6, v34
	v_readlane_b32 s0, v253, 9
	s_nop 0
	v_addc_co_u32_e32 v35, vcc, 0, v35, vcc
	s_add_i32 s7, s7, s0
	s_cmpk_gt_i32 s7, 0xff
	v_readlane_b32 s1, v253, 10
	s_waitcnt vmcnt(1)
	v_lshlrev_b32_e32 v8, 16, v0
	v_and_b32_e32 v0, 0xffff0000, v0
	v_mul_f32_e32 v16, 0xbfb8aa3b, v0
	v_exp_f32_e32 v16, v16
	v_mul_f32_e32 v9, 0xbfb8aa3b, v8
	v_exp_f32_e32 v9, v9
	v_add_f32_e32 v16, 1.0, v16
	v_rcp_f32_e32 v16, v16
	v_add_f32_e32 v9, 1.0, v9
	v_rcp_f32_e32 v9, v9
	v_mul_f32_e32 v0, v16, v0
	v_mul_f32_e32 v38, v0, v4
	v_lshlrev_b32_e32 v0, 16, v1
	v_mul_f32_e32 v8, v9, v8
	v_mul_f32_e32 v4, 0xbfb8aa3b, v0
	v_and_b32_e32 v1, 0xffff0000, v1
	v_mul_f32_e32 v21, v8, v17
	v_exp_f32_e32 v4, v4
	v_mul_f32_e32 v8, 0xbfb8aa3b, v1
	v_exp_f32_e32 v8, v8
	v_lshlrev_b32_e32 v9, 16, v5
	v_add_f32_e32 v4, 1.0, v4
	v_rcp_f32_e32 v4, v4
	v_add_f32_e32 v8, 1.0, v8
	v_rcp_f32_e32 v8, v8
	v_mul_f32_e32 v0, v4, v0
	v_mul_f32_e32 v39, v0, v9
	v_and_b32_e32 v0, 0xffff0000, v5
	v_mul_f32_e32 v1, v8, v1
	v_mul_f32_e32 v40, v1, v0
	v_lshlrev_b32_e32 v0, 16, v2
	v_mul_f32_e32 v1, 0xbfb8aa3b, v0
	v_and_b32_e32 v2, 0xffff0000, v2
	v_exp_f32_e32 v1, v1
	v_mul_f32_e32 v4, 0xbfb8aa3b, v2
	v_exp_f32_e32 v4, v4
	v_lshlrev_b32_e32 v5, 16, v6
	v_add_f32_e32 v1, 1.0, v1
	v_rcp_f32_e32 v1, v1
	v_add_f32_e32 v4, 1.0, v4
	v_rcp_f32_e32 v4, v4
	v_mul_f32_e32 v0, v1, v0
	v_mul_f32_e32 v41, v0, v5
	v_and_b32_e32 v0, 0xffff0000, v6
	v_mul_f32_e32 v1, v4, v2
	v_mul_f32_e32 v42, v1, v0
	v_lshlrev_b32_e32 v0, 16, v3
	v_mul_f32_e32 v1, 0xbfb8aa3b, v0
	v_and_b32_e32 v2, 0xffff0000, v3
	v_exp_f32_e32 v1, v1
	v_mul_f32_e32 v3, 0xbfb8aa3b, v2
	v_exp_f32_e32 v3, v3
	v_lshlrev_b32_e32 v4, 16, v7
	v_add_f32_e32 v1, 1.0, v1
	v_rcp_f32_e32 v1, v1
	v_add_f32_e32 v3, 1.0, v3
	v_rcp_f32_e32 v3, v3
	v_mul_f32_e32 v0, v1, v0
	v_mul_f32_e32 v43, v0, v4
	v_and_b32_e32 v0, 0xffff0000, v7
	v_mul_f32_e32 v1, v3, v2
	v_mul_f32_e32 v44, v1, v0
	global_load_dwordx4 v[26:29], v[10:11], off nt
	global_load_dwordx4 v[16:19], v[12:13], off nt
	s_nop 0
	global_load_dwordx4 v[12:15], v[14:15], off nt
	s_nop 0
	global_load_dwordx4 v[8:11], v[30:31], off nt
	global_load_dwordx4 v[4:7], v[32:33], off nt
	global_load_dwordx4 v[0:3], v[36:37], off nt
	v_cvt_pk_bf16_f32 v30, v21, v38
	v_cvt_pk_bf16_f32 v31, v39, v40
	v_cvt_pk_bf16_f32 v32, v41, v42
	v_cvt_pk_bf16_f32 v33, v43, v44
	v_add_u32_e32 v21, v20, v194
	global_store_dwordx4 v[34:35], v[30:33], off offset:2048
	ds_read_b128 v[30:33], v21
	s_waitcnt vmcnt(7)
	v_lshlrev_b32_e32 v21, 16, v22
	v_and_b32_e32 v22, 0xffff0000, v22
	v_mul_f32_e32 v35, 0xbfb8aa3b, v22
	v_exp_f32_e32 v35, v35
	v_mul_f32_e32 v34, 0xbfb8aa3b, v21
	v_exp_f32_e32 v34, v34
	s_waitcnt lgkmcnt(0)
	v_lshlrev_b32_e32 v36, 16, v30
	v_add_f32_e32 v35, 1.0, v35
	v_rcp_f32_e32 v35, v35
	v_and_b32_e32 v30, 0xffff0000, v30
	v_add_f32_e32 v34, 1.0, v34
	v_rcp_f32_e32 v34, v34
	v_mul_f32_e32 v22, v35, v22
	v_mul_f32_e32 v22, v22, v30
	v_lshlrev_b32_e32 v30, 16, v23
	v_and_b32_e32 v23, 0xffff0000, v23
	v_mul_f32_e32 v35, 0xbfb8aa3b, v23
	v_exp_f32_e32 v35, v35
	v_mul_f32_e32 v21, v34, v21
	v_mul_f32_e32 v34, 0xbfb8aa3b, v30
	v_exp_f32_e32 v34, v34
	v_add_f32_e32 v35, 1.0, v35
	v_rcp_f32_e32 v35, v35
	v_mul_f32_e32 v21, v21, v36
	v_add_f32_e32 v34, 1.0, v34
	v_lshlrev_b32_e32 v36, 16, v31
	v_and_b32_e32 v31, 0xffff0000, v31
	v_mul_f32_e32 v23, v35, v23
	v_rcp_f32_e32 v34, v34
	v_mul_f32_e32 v23, v23, v31
	v_lshlrev_b32_e32 v31, 16, v24
	v_and_b32_e32 v24, 0xffff0000, v24
	v_mul_f32_e32 v35, 0xbfb8aa3b, v24
	v_exp_f32_e32 v35, v35
	v_mul_f32_e32 v30, v34, v30
	v_mul_f32_e32 v34, 0xbfb8aa3b, v31
	v_exp_f32_e32 v34, v34
	v_add_f32_e32 v35, 1.0, v35
	v_rcp_f32_e32 v35, v35
	v_mul_f32_e32 v30, v30, v36
	v_add_f32_e32 v34, 1.0, v34
	v_rcp_f32_e32 v34, v34
	v_lshlrev_b32_e32 v36, 16, v32
	v_and_b32_e32 v32, 0xffff0000, v32
	v_mul_f32_e32 v24, v35, v24
	v_mul_f32_e32 v24, v24, v32
	v_lshlrev_b32_e32 v32, 16, v25
	v_and_b32_e32 v25, 0xffff0000, v25
	v_mul_f32_e32 v35, 0xbfb8aa3b, v25
	v_mul_f32_e32 v31, v34, v31
	v_mul_f32_e32 v34, 0xbfb8aa3b, v32
	v_exp_f32_e32 v35, v35
	v_exp_f32_e32 v34, v34
	v_mul_f32_e32 v31, v31, v36
	v_cvt_pk_bf16_f32 v22, v21, v22
	v_add_f32_e32 v35, 1.0, v35
	v_add_f32_e32 v34, 1.0, v34
	v_rcp_f32_e32 v35, v35
	v_cvt_pk_bf16_f32 v23, v30, v23
	v_cvt_pk_bf16_f32 v24, v31, v24
	v_or_b32_e32 v30, s9, v138
	v_mov_b32_e32 v31, v129
	v_rcp_f32_e32 v34, v34
	v_lshlrev_b64 v[30:31], 12, v[30:31]
	v_lshl_add_u64 v[30:31], s[92:93], 0, v[30:31]
	v_lshl_add_u64 v[30:31], v[30:31], 0, s[2:3]
	v_lshlrev_b32_e32 v36, 16, v33
	v_and_b32_e32 v33, 0xffff0000, v33
	v_mul_f32_e32 v25, v35, v25
	v_lshl_add_u64 v[30:31], v[30:31], 0, v[146:147]
	v_mul_f32_e32 v32, v34, v32
	v_mul_f32_e32 v25, v25, v33
	v_add_co_u32_e32 v30, vcc, s6, v30
	v_mul_f32_e32 v32, v32, v36
	v_cvt_pk_bf16_f32 v25, v32, v25
	s_nop 0
	v_addc_co_u32_e32 v31, vcc, 0, v31, vcc
	v_add_u32_e32 v21, v20, v195
	global_store_dwordx4 v[30:31], v[22:25], off offset:2048
	ds_read_b128 v[22:25], v21
	s_waitcnt vmcnt(7)
	v_lshlrev_b32_e32 v21, 16, v26
	v_and_b32_e32 v26, 0xffff0000, v26
	v_mul_f32_e32 v31, 0xbfb8aa3b, v26
	v_exp_f32_e32 v31, v31
	v_mul_f32_e32 v30, 0xbfb8aa3b, v21
	v_exp_f32_e32 v30, v30
	s_waitcnt lgkmcnt(0)
; __device__ __forceinline__ float bf2f(short s) { return __uint_as_float(((unsigned)(unsigned short)s) << 16); }
; __device__ __forceinline__ float silu_fast(float g) { return g * __builtin_amdgcn_rcpf(1.f + __builtin_amdgcn_exp2f(-g * LOG2E)); }
; __device__ __forceinline__ bf16x8 tobf8(f32x8 x) { u32x4 w = {cvtpk(x[0], x[1]), cvtpk(x[2], x[3]), cvtpk(x[4], x[5]), cvtpk(x[6], x[7])}; return *reinterpret_cast<bf16x8*>(&w); }
; template <int MODE, bool SAMPLE>
; __device__ __forceinline__ void attn_unit(const Params& p, char* lds, int b, int h, int qb) {
;     ...
;         for (int it = 0; it < NIT; ++it) { const int row = it * 4 + er; const bf16x8 mx = *(const bf16x8*)(Qs + row * 256 + ec * 2); f32x8 y;
; #pragma unroll
;             for (int i = 0; i < 8; ++i) y[i] = bf2f(mx[i]) * silu_fast(bf2f(gt[it][i]));
;             *(bf16x8*)(MIX + (rbase + row) * DM + MODE * 1024 + h * HD + ec) = tobf8(y); }
	v_lshlrev_b32_e32 v32, 16, v22
	v_add_f32_e32 v31, 1.0, v31
	v_rcp_f32_e32 v31, v31
	v_and_b32_e32 v22, 0xffff0000, v22
	v_add_f32_e32 v30, 1.0, v30
	v_rcp_f32_e32 v30, v30
	v_mul_f32_e32 v26, v31, v26
	v_mul_f32_e32 v22, v26, v22
	v_lshlrev_b32_e32 v26, 16, v27
	v_and_b32_e32 v27, 0xffff0000, v27
	v_mul_f32_e32 v31, 0xbfb8aa3b, v27
	v_exp_f32_e32 v31, v31
	v_mul_f32_e32 v21, v30, v21
	v_mul_f32_e32 v30, 0xbfb8aa3b, v26
	v_exp_f32_e32 v30, v30
	v_add_f32_e32 v31, 1.0, v31
	v_rcp_f32_e32 v31, v31
	v_mul_f32_e32 v21, v21, v32
	v_add_f32_e32 v30, 1.0, v30
	v_lshlrev_b32_e32 v32, 16, v23
	v_and_b32_e32 v23, 0xffff0000, v23
	v_mul_f32_e32 v27, v31, v27
	v_rcp_f32_e32 v30, v30
	v_mul_f32_e32 v23, v27, v23
	v_lshlrev_b32_e32 v27, 16, v28
	v_and_b32_e32 v28, 0xffff0000, v28
	v_mul_f32_e32 v31, 0xbfb8aa3b, v28
	v_exp_f32_e32 v31, v31
	v_mul_f32_e32 v26, v30, v26
	v_mul_f32_e32 v30, 0xbfb8aa3b, v27
	v_exp_f32_e32 v30, v30
	v_add_f32_e32 v31, 1.0, v31
	v_rcp_f32_e32 v31, v31
	v_mul_f32_e32 v26, v26, v32
	v_add_f32_e32 v30, 1.0, v30
	v_rcp_f32_e32 v30, v30
	v_lshlrev_b32_e32 v32, 16, v24
	v_and_b32_e32 v24, 0xffff0000, v24
	v_mul_f32_e32 v28, v31, v28
	v_mul_f32_e32 v24, v28, v24
	v_lshlrev_b32_e32 v28, 16, v29
	v_and_b32_e32 v29, 0xffff0000, v29
	v_mul_f32_e32 v31, 0xbfb8aa3b, v29
	v_mul_f32_e32 v27, v30, v27
	v_mul_f32_e32 v30, 0xbfb8aa3b, v28
	v_exp_f32_e32 v31, v31
	v_exp_f32_e32 v30, v30
	v_mul_f32_e32 v27, v27, v32
	v_cvt_pk_bf16_f32 v22, v21, v22
	v_add_f32_e32 v31, 1.0, v31
	v_add_f32_e32 v30, 1.0, v30
	v_rcp_f32_e32 v31, v31
	v_cvt_pk_bf16_f32 v23, v26, v23
	v_cvt_pk_bf16_f32 v24, v27, v24
	v_or_b32_e32 v26, s9, v140
	v_mov_b32_e32 v27, v129
	v_rcp_f32_e32 v30, v30
	v_lshlrev_b64 v[26:27], 12, v[26:27]
	v_lshl_add_u64 v[26:27], s[92:93], 0, v[26:27]
	v_lshl_add_u64 v[26:27], v[26:27], 0, s[2:3]
	v_lshlrev_b32_e32 v32, 16, v25
	v_and_b32_e32 v25, 0xffff0000, v25
	v_mul_f32_e32 v29, v31, v29
	v_lshl_add_u64 v[26:27], v[26:27], 0, v[146:147]
	v_mul_f32_e32 v28, v30, v28
	v_mul_f32_e32 v25, v29, v25
	v_add_co_u32_e32 v26, vcc, s6, v26
	v_mul_f32_e32 v28, v28, v32
	v_cvt_pk_bf16_f32 v25, v28, v25
	s_nop 0
	v_addc_co_u32_e32 v27, vcc, 0, v27, vcc
	v_add_u32_e32 v21, v20, v196
	global_store_dwordx4 v[26:27], v[22:25], off offset:2048
	ds_read_b128 v[22:25], v21
	s_waitcnt vmcnt(7)
	v_lshlrev_b32_e32 v21, 16, v16
	v_and_b32_e32 v16, 0xffff0000, v16
	v_mul_f32_e32 v27, 0xbfb8aa3b, v16
	v_exp_f32_e32 v27, v27
	v_mul_f32_e32 v26, 0xbfb8aa3b, v21
	v_exp_f32_e32 v26, v26
	s_waitcnt lgkmcnt(0)
	v_lshlrev_b32_e32 v28, 16, v22
	v_add_f32_e32 v27, 1.0, v27
	v_rcp_f32_e32 v27, v27
	v_and_b32_e32 v22, 0xffff0000, v22
	v_add_f32_e32 v26, 1.0, v26
	v_rcp_f32_e32 v26, v26
	v_mul_f32_e32 v16, v27, v16
	v_mul_f32_e32 v16, v16, v22
	v_lshlrev_b32_e32 v22, 16, v17
	v_and_b32_e32 v17, 0xffff0000, v17
	v_mul_f32_e32 v27, 0xbfb8aa3b, v17
	v_exp_f32_e32 v27, v27
	v_mul_f32_e32 v21, v26, v21
	v_mul_f32_e32 v26, 0xbfb8aa3b, v22
	v_exp_f32_e32 v26, v26
	v_add_f32_e32 v27, 1.0, v27
	v_rcp_f32_e32 v27, v27
	v_mul_f32_e32 v21, v21, v28
	v_add_f32_e32 v26, 1.0, v26
	v_lshlrev_b32_e32 v28, 16, v23
	v_and_b32_e32 v23, 0xffff0000, v23
	v_mul_f32_e32 v17, v27, v17
	v_rcp_f32_e32 v26, v26
	v_mul_f32_e32 v17, v17, v23
	v_lshlrev_b32_e32 v23, 16, v18
	v_and_b32_e32 v18, 0xffff0000, v18
	v_mul_f32_e32 v27, 0xbfb8aa3b, v18
	v_exp_f32_e32 v27, v27
	v_mul_f32_e32 v22, v26, v22
	v_mul_f32_e32 v26, 0xbfb8aa3b, v23
	v_exp_f32_e32 v26, v26
	v_add_f32_e32 v27, 1.0, v27
	v_rcp_f32_e32 v27, v27
	v_mul_f32_e32 v22, v22, v28
	v_add_f32_e32 v26, 1.0, v26
	v_rcp_f32_e32 v26, v26
	v_lshlrev_b32_e32 v28, 16, v24
	v_and_b32_e32 v24, 0xffff0000, v24
	v_mul_f32_e32 v18, v27, v18
	v_mul_f32_e32 v18, v18, v24
	v_lshlrev_b32_e32 v24, 16, v19
	v_and_b32_e32 v19, 0xffff0000, v19
	v_mul_f32_e32 v27, 0xbfb8aa3b, v19
	v_mul_f32_e32 v23, v26, v23
	v_mul_f32_e32 v26, 0xbfb8aa3b, v24
	v_exp_f32_e32 v27, v27
	v_exp_f32_e32 v26, v26
	v_mul_f32_e32 v23, v23, v28
	v_cvt_pk_bf16_f32 v16, v21, v16
	v_add_f32_e32 v27, 1.0, v27
	v_cvt_pk_bf16_f32 v17, v22, v17
	v_cvt_pk_bf16_f32 v18, v23, v18
	v_or_b32_e32 v22, s9, v142
	v_mov_b32_e32 v23, v129
	v_add_f32_e32 v26, 1.0, v26
	v_rcp_f32_e32 v27, v27
	v_lshlrev_b64 v[22:23], 12, v[22:23]
	v_rcp_f32_e32 v26, v26
	v_lshl_add_u64 v[22:23], s[92:93], 0, v[22:23]
	v_lshl_add_u64 v[22:23], v[22:23], 0, s[2:3]
	v_lshl_add_u64 v[22:23], v[22:23], 0, v[146:147]
	v_lshlrev_b32_e32 v28, 16, v25
	v_and_b32_e32 v25, 0xffff0000, v25
	v_mul_f32_e32 v19, v27, v19
	v_add_co_u32_e32 v22, vcc, s6, v22
	v_mul_f32_e32 v24, v26, v24
	v_mul_f32_e32 v19, v19, v25
	v_addc_co_u32_e32 v23, vcc, 0, v23, vcc
	s_waitcnt vmcnt(6)
	v_lshlrev_b32_e32 v21, 16, v12
	v_and_b32_e32 v12, 0xffff0000, v12
	v_mul_f32_e32 v24, v24, v28
	v_cvt_pk_bf16_f32 v19, v24, v19
	global_store_dwordx4 v[22:23], v[16:19], off offset:2048
	v_mul_f32_e32 v23, 0xbfb8aa3b, v12
	v_exp_f32_e32 v23, v23
	v_add_u32_e32 v16, v20, v208
	ds_read_b128 v[16:19], v16
	v_mul_f32_e32 v22, 0xbfb8aa3b, v21
	v_add_f32_e32 v23, 1.0, v23
	v_rcp_f32_e32 v23, v23
	v_exp_f32_e32 v22, v22
	s_waitcnt lgkmcnt(0)
; __device__ __forceinline__ float bf2f(short s) { return __uint_as_float(((unsigned)(unsigned short)s) << 16); }
; __device__ __forceinline__ float silu_fast(float g) { return g * __builtin_amdgcn_rcpf(1.f + __builtin_amdgcn_exp2f(-g * LOG2E)); }
; __device__ __forceinline__ bf16x8 tobf8(f32x8 x) { u32x4 w = {cvtpk(x[0], x[1]), cvtpk(x[2], x[3]), cvtpk(x[4], x[5]), cvtpk(x[6], x[7])}; return *reinterpret_cast<bf16x8*>(&w); }
; template <int MODE, bool SAMPLE>
; __device__ __forceinline__ void attn_unit(const Params& p, char* lds, int b, int h, int qb) {
;     ...
; #pragma unroll
;         for (int it = 0; it < NIT; ++it) gt[it] = __builtin_nontemporal_load((const bf16x8*)(P1q + 24 * HB + (rbase + it * 4 + er) * 128 + ec));
; #pragma unroll
;         for (int it = 0; it < NIT; ++it) { const int row = it * 4 + er; const bf16x8 mx = *(const bf16x8*)(Qs + row * 256 + ec * 2); f32x8 y;
; #pragma unroll
;             for (int i = 0; i < 8; ++i) y[i] = bf2f(mx[i]) * silu_fast(bf2f(gt[it][i]));
;             *(bf16x8*)(MIX + (rbase + row) * DM + MODE * 1024 + h * HD + ec) = tobf8(y); }
	v_lshlrev_b32_e32 v24, 16, v16
	v_and_b32_e32 v16, 0xffff0000, v16
	v_mul_f32_e32 v12, v23, v12
	v_mul_f32_e32 v12, v12, v16
	v_lshlrev_b32_e32 v16, 16, v13
	v_and_b32_e32 v13, 0xffff0000, v13
	v_add_f32_e32 v22, 1.0, v22
	v_mul_f32_e32 v23, 0xbfb8aa3b, v13
	v_rcp_f32_e32 v22, v22
	v_exp_f32_e32 v23, v23
	v_mul_f32_e32 v21, v22, v21
	v_mul_f32_e32 v22, 0xbfb8aa3b, v16
	v_add_f32_e32 v23, 1.0, v23
	v_exp_f32_e32 v22, v22
	v_rcp_f32_e32 v23, v23
	v_mul_f32_e32 v21, v21, v24
	v_lshlrev_b32_e32 v24, 16, v17
	v_add_f32_e32 v22, 1.0, v22
	v_and_b32_e32 v17, 0xffff0000, v17
	v_mul_f32_e32 v13, v23, v13
	v_rcp_f32_e32 v22, v22
	v_mul_f32_e32 v13, v13, v17
	v_lshlrev_b32_e32 v17, 16, v14
	v_and_b32_e32 v14, 0xffff0000, v14
	v_mul_f32_e32 v23, 0xbfb8aa3b, v14
	v_exp_f32_e32 v23, v23
	v_mul_f32_e32 v16, v22, v16
	v_mul_f32_e32 v22, 0xbfb8aa3b, v17
	v_exp_f32_e32 v22, v22
	v_add_f32_e32 v23, 1.0, v23
	v_rcp_f32_e32 v23, v23
	v_mul_f32_e32 v16, v16, v24
	v_add_f32_e32 v22, 1.0, v22
	v_rcp_f32_e32 v22, v22
	v_lshlrev_b32_e32 v24, 16, v18
	v_and_b32_e32 v18, 0xffff0000, v18
	v_mul_f32_e32 v14, v23, v14
	v_mul_f32_e32 v14, v14, v18
	v_lshlrev_b32_e32 v18, 16, v15
	v_and_b32_e32 v15, 0xffff0000, v15
	v_mul_f32_e32 v23, 0xbfb8aa3b, v15
	v_mul_f32_e32 v17, v22, v17
	v_mul_f32_e32 v22, 0xbfb8aa3b, v18
	v_exp_f32_e32 v23, v23
	v_exp_f32_e32 v22, v22
	v_mul_f32_e32 v17, v17, v24
	v_cvt_pk_bf16_f32 v12, v21, v12
	v_add_f32_e32 v23, 1.0, v23
	v_cvt_pk_bf16_f32 v13, v16, v13
	v_cvt_pk_bf16_f32 v14, v17, v14
	v_or_b32_e32 v16, s9, v150
	v_mov_b32_e32 v17, v129
	v_add_f32_e32 v22, 1.0, v22
	v_rcp_f32_e32 v23, v23
	v_lshlrev_b64 v[16:17], 12, v[16:17]
	v_rcp_f32_e32 v22, v22
	v_lshl_add_u64 v[16:17], s[92:93], 0, v[16:17]
	v_lshl_add_u64 v[16:17], v[16:17], 0, s[2:3]
	v_lshl_add_u64 v[16:17], v[16:17], 0, v[146:147]
	v_lshlrev_b32_e32 v24, 16, v19
	v_and_b32_e32 v19, 0xffff0000, v19
	v_mul_f32_e32 v15, v23, v15
	v_add_co_u32_e32 v16, vcc, s6, v16
	v_mul_f32_e32 v18, v22, v18
	v_mul_f32_e32 v15, v15, v19
	v_addc_co_u32_e32 v17, vcc, 0, v17, vcc
	v_mul_f32_e32 v18, v18, v24
	v_cvt_pk_bf16_f32 v15, v18, v15
	global_store_dwordx4 v[16:17], v[12:15], off offset:2048
	s_waitcnt vmcnt(7)
	v_lshlrev_b32_e32 v16, 16, v8
	v_and_b32_e32 v8, 0xffff0000, v8
	v_mul_f32_e32 v18, 0xbfb8aa3b, v8
	v_exp_f32_e32 v18, v18
	v_add_u32_e32 v12, v20, v209
	ds_read_b128 v[12:15], v12
	v_mul_f32_e32 v17, 0xbfb8aa3b, v16
	v_add_f32_e32 v18, 1.0, v18
	v_rcp_f32_e32 v18, v18
	v_exp_f32_e32 v17, v17
	s_waitcnt lgkmcnt(0)
	v_lshlrev_b32_e32 v19, 16, v12
	v_and_b32_e32 v12, 0xffff0000, v12
	v_mul_f32_e32 v8, v18, v8
	v_mul_f32_e32 v8, v8, v12
	v_lshlrev_b32_e32 v12, 16, v9
	v_and_b32_e32 v9, 0xffff0000, v9
	v_add_f32_e32 v17, 1.0, v17
	v_mul_f32_e32 v18, 0xbfb8aa3b, v9
	v_rcp_f32_e32 v17, v17
	v_exp_f32_e32 v18, v18
	v_mul_f32_e32 v16, v17, v16
	v_mul_f32_e32 v17, 0xbfb8aa3b, v12
	v_add_f32_e32 v18, 1.0, v18
	v_exp_f32_e32 v17, v17
	v_rcp_f32_e32 v18, v18
	v_mul_f32_e32 v16, v16, v19
	v_lshlrev_b32_e32 v19, 16, v13
	v_add_f32_e32 v17, 1.0, v17
	v_and_b32_e32 v13, 0xffff0000, v13
	v_mul_f32_e32 v9, v18, v9
	v_rcp_f32_e32 v17, v17
	v_mul_f32_e32 v9, v9, v13
	v_lshlrev_b32_e32 v13, 16, v10
	v_and_b32_e32 v10, 0xffff0000, v10
	v_mul_f32_e32 v18, 0xbfb8aa3b, v10
	v_exp_f32_e32 v18, v18
	v_mul_f32_e32 v12, v17, v12
	v_mul_f32_e32 v17, 0xbfb8aa3b, v13
	v_exp_f32_e32 v17, v17
	v_add_f32_e32 v18, 1.0, v18
	v_rcp_f32_e32 v18, v18
	v_mul_f32_e32 v12, v12, v19
	v_add_f32_e32 v17, 1.0, v17
	v_rcp_f32_e32 v17, v17
	v_lshlrev_b32_e32 v19, 16, v14
	v_and_b32_e32 v14, 0xffff0000, v14
	v_mul_f32_e32 v10, v18, v10
	v_mul_f32_e32 v10, v10, v14
	v_lshlrev_b32_e32 v14, 16, v11
	v_and_b32_e32 v11, 0xffff0000, v11
	v_mul_f32_e32 v18, 0xbfb8aa3b, v11
	v_mul_f32_e32 v13, v17, v13
	v_mul_f32_e32 v17, 0xbfb8aa3b, v14
	v_exp_f32_e32 v18, v18
	v_exp_f32_e32 v17, v17
	v_mul_f32_e32 v13, v13, v19
	v_cvt_pk_bf16_f32 v8, v16, v8
	v_add_f32_e32 v18, 1.0, v18
	v_cvt_pk_bf16_f32 v9, v12, v9
	v_cvt_pk_bf16_f32 v10, v13, v10
	v_or_b32_e32 v12, s9, v152
	v_mov_b32_e32 v13, v129
	v_add_f32_e32 v17, 1.0, v17
	v_rcp_f32_e32 v18, v18
	v_lshlrev_b64 v[12:13], 12, v[12:13]
	v_rcp_f32_e32 v17, v17
	v_lshl_add_u64 v[12:13], s[92:93], 0, v[12:13]
	v_lshl_add_u64 v[12:13], v[12:13], 0, s[2:3]
	v_lshl_add_u64 v[12:13], v[12:13], 0, v[146:147]
	v_lshlrev_b32_e32 v19, 16, v15
	v_and_b32_e32 v15, 0xffff0000, v15
	v_mul_f32_e32 v11, v18, v11
	v_add_co_u32_e32 v12, vcc, s6, v12
	v_mul_f32_e32 v14, v17, v14
	v_mul_f32_e32 v11, v11, v15
	v_addc_co_u32_e32 v13, vcc, 0, v13, vcc
	v_mul_f32_e32 v14, v14, v19
	v_cvt_pk_bf16_f32 v11, v14, v11
	global_store_dwordx4 v[12:13], v[8:11], off offset:2048
	s_waitcnt vmcnt(7)
; __device__ __forceinline__ float bf2f(short s) { return __uint_as_float(((unsigned)(unsigned short)s) << 16); }
; __device__ __forceinline__ float silu_fast(float g) { return g * __builtin_amdgcn_rcpf(1.f + __builtin_amdgcn_exp2f(-g * LOG2E)); }
; __device__ __forceinline__ bf16x8 tobf8(f32x8 x) { u32x4 w = {cvtpk(x[0], x[1]), cvtpk(x[2], x[3]), cvtpk(x[4], x[5]), cvtpk(x[6], x[7])}; return *reinterpret_cast<bf16x8*>(&w); }
; template <int MODE, bool SAMPLE>
; __device__ __forceinline__ void attn_unit(const Params& p, char* lds, int b, int h, int qb) {
;     ...
; #pragma unroll
;         for (int it = 0; it < NIT; ++it) gt[it] = __builtin_nontemporal_load((const bf16x8*)(P1q + 24 * HB + (rbase + it * 4 + er) * 128 + ec));
; #pragma unroll
;         for (int it = 0; it < NIT; ++it) { const int row = it * 4 + er; const bf16x8 mx = *(const bf16x8*)(Qs + row * 256 + ec * 2); f32x8 y;
; #pragma unroll
;             for (int i = 0; i < 8; ++i) y[i] = bf2f(mx[i]) * silu_fast(bf2f(gt[it][i]));
;             *(bf16x8*)(MIX + (rbase + row) * DM + MODE * 1024 + h * HD + ec) = tobf8(y); }
;     }
;     __syncthreads();
	v_lshlrev_b32_e32 v12, 16, v4
	v_and_b32_e32 v4, 0xffff0000, v4
	v_mul_f32_e32 v14, 0xbfb8aa3b, v4
	v_exp_f32_e32 v14, v14
	v_add_u32_e32 v8, v20, v210
	ds_read_b128 v[8:11], v8
	v_mul_f32_e32 v13, 0xbfb8aa3b, v12
	v_add_f32_e32 v14, 1.0, v14
	v_rcp_f32_e32 v14, v14
	v_exp_f32_e32 v13, v13
	s_waitcnt lgkmcnt(0)
	v_lshlrev_b32_e32 v15, 16, v8
	v_and_b32_e32 v8, 0xffff0000, v8
	v_mul_f32_e32 v4, v14, v4
	v_mul_f32_e32 v4, v4, v8
	v_lshlrev_b32_e32 v8, 16, v5
	v_and_b32_e32 v5, 0xffff0000, v5
	v_add_f32_e32 v13, 1.0, v13
	v_mul_f32_e32 v14, 0xbfb8aa3b, v5
	v_rcp_f32_e32 v13, v13
	v_exp_f32_e32 v14, v14
	v_mul_f32_e32 v12, v13, v12
	v_mul_f32_e32 v13, 0xbfb8aa3b, v8
	v_add_f32_e32 v14, 1.0, v14
	v_exp_f32_e32 v13, v13
	v_rcp_f32_e32 v14, v14
	v_mul_f32_e32 v12, v12, v15
	v_lshlrev_b32_e32 v15, 16, v9
	v_add_f32_e32 v13, 1.0, v13
	v_and_b32_e32 v9, 0xffff0000, v9
	v_mul_f32_e32 v5, v14, v5
	v_rcp_f32_e32 v13, v13
	v_mul_f32_e32 v5, v5, v9
	v_lshlrev_b32_e32 v9, 16, v6
	v_and_b32_e32 v6, 0xffff0000, v6
	v_mul_f32_e32 v14, 0xbfb8aa3b, v6
	v_exp_f32_e32 v14, v14
	v_mul_f32_e32 v8, v13, v8
	v_mul_f32_e32 v13, 0xbfb8aa3b, v9
	v_exp_f32_e32 v13, v13
	v_add_f32_e32 v14, 1.0, v14
	v_rcp_f32_e32 v14, v14
	v_mul_f32_e32 v8, v8, v15
	v_add_f32_e32 v13, 1.0, v13
	v_rcp_f32_e32 v13, v13
	v_lshlrev_b32_e32 v15, 16, v10
	v_and_b32_e32 v10, 0xffff0000, v10
	v_mul_f32_e32 v6, v14, v6
	v_mul_f32_e32 v6, v6, v10
	v_lshlrev_b32_e32 v10, 16, v7
	v_and_b32_e32 v7, 0xffff0000, v7
	v_mul_f32_e32 v14, 0xbfb8aa3b, v7
	v_mul_f32_e32 v9, v13, v9
	v_mul_f32_e32 v13, 0xbfb8aa3b, v10
	v_exp_f32_e32 v14, v14
	v_exp_f32_e32 v13, v13
	v_mul_f32_e32 v9, v9, v15
	v_cvt_pk_bf16_f32 v4, v12, v4
	v_add_f32_e32 v14, 1.0, v14
	v_cvt_pk_bf16_f32 v5, v8, v5
	v_cvt_pk_bf16_f32 v6, v9, v6
	v_or_b32_e32 v8, s9, v154
	v_mov_b32_e32 v9, v129
	v_add_f32_e32 v13, 1.0, v13
	v_rcp_f32_e32 v14, v14
	v_lshlrev_b64 v[8:9], 12, v[8:9]
	v_rcp_f32_e32 v13, v13
	v_lshl_add_u64 v[8:9], s[92:93], 0, v[8:9]
	v_lshl_add_u64 v[8:9], v[8:9], 0, s[2:3]
	v_lshl_add_u64 v[8:9], v[8:9], 0, v[146:147]
	v_lshlrev_b32_e32 v15, 16, v11
	v_and_b32_e32 v11, 0xffff0000, v11
	v_mul_f32_e32 v7, v14, v7
	v_add_co_u32_e32 v8, vcc, s6, v8
	v_mul_f32_e32 v10, v13, v10
	v_mul_f32_e32 v7, v7, v11
	v_addc_co_u32_e32 v9, vcc, 0, v9, vcc
	v_mul_f32_e32 v10, v10, v15
	v_cvt_pk_bf16_f32 v7, v10, v7
	global_store_dwordx4 v[8:9], v[4:7], off offset:2048
	s_waitcnt vmcnt(7)
	v_lshlrev_b32_e32 v8, 16, v0
	v_and_b32_e32 v0, 0xffff0000, v0
	v_mul_f32_e32 v10, 0xbfb8aa3b, v0
	v_exp_f32_e32 v10, v10
	v_add_u32_e32 v4, v20, v211
	ds_read_b128 v[4:7], v4
	v_mul_f32_e32 v9, 0xbfb8aa3b, v8
	v_add_f32_e32 v10, 1.0, v10
	v_rcp_f32_e32 v10, v10
	v_exp_f32_e32 v9, v9
	s_waitcnt lgkmcnt(0)
	v_lshlrev_b32_e32 v11, 16, v4
	v_and_b32_e32 v4, 0xffff0000, v4
	v_mul_f32_e32 v0, v10, v0
	v_mul_f32_e32 v0, v0, v4
	v_lshlrev_b32_e32 v4, 16, v1
	v_and_b32_e32 v1, 0xffff0000, v1
	v_add_f32_e32 v9, 1.0, v9
	v_mul_f32_e32 v10, 0xbfb8aa3b, v1
	v_rcp_f32_e32 v9, v9
	v_exp_f32_e32 v10, v10
	v_mul_f32_e32 v8, v9, v8
	v_mul_f32_e32 v9, 0xbfb8aa3b, v4
	v_add_f32_e32 v10, 1.0, v10
	v_exp_f32_e32 v9, v9
	v_rcp_f32_e32 v10, v10
	v_mul_f32_e32 v8, v8, v11
	v_lshlrev_b32_e32 v11, 16, v5
	v_add_f32_e32 v9, 1.0, v9
	v_and_b32_e32 v5, 0xffff0000, v5
	v_mul_f32_e32 v1, v10, v1
	v_rcp_f32_e32 v9, v9
	v_mul_f32_e32 v1, v1, v5
	v_lshlrev_b32_e32 v5, 16, v2
	v_and_b32_e32 v2, 0xffff0000, v2
	v_mul_f32_e32 v10, 0xbfb8aa3b, v2
	v_exp_f32_e32 v10, v10
	v_mul_f32_e32 v4, v9, v4
	v_mul_f32_e32 v9, 0xbfb8aa3b, v5
	v_exp_f32_e32 v9, v9
	v_add_f32_e32 v10, 1.0, v10
	v_rcp_f32_e32 v10, v10
	v_mul_f32_e32 v4, v4, v11
	v_add_f32_e32 v9, 1.0, v9
	v_rcp_f32_e32 v9, v9
	v_lshlrev_b32_e32 v11, 16, v6
	v_and_b32_e32 v6, 0xffff0000, v6
	v_mul_f32_e32 v2, v10, v2
	v_mul_f32_e32 v2, v2, v6
	v_lshlrev_b32_e32 v6, 16, v3
	v_and_b32_e32 v3, 0xffff0000, v3
	v_mul_f32_e32 v10, 0xbfb8aa3b, v3
	v_mul_f32_e32 v5, v9, v5
	v_mul_f32_e32 v9, 0xbfb8aa3b, v6
	v_exp_f32_e32 v10, v10
	v_exp_f32_e32 v9, v9
	v_mul_f32_e32 v5, v5, v11
	v_cvt_pk_bf16_f32 v0, v8, v0
	v_add_f32_e32 v10, 1.0, v10
	v_cvt_pk_bf16_f32 v1, v4, v1
	v_cvt_pk_bf16_f32 v2, v5, v2
	v_or_b32_e32 v4, s9, v156
	v_mov_b32_e32 v5, v129
	v_add_f32_e32 v9, 1.0, v9
	v_rcp_f32_e32 v10, v10
	v_lshlrev_b64 v[4:5], 12, v[4:5]
	v_rcp_f32_e32 v9, v9
	v_lshl_add_u64 v[4:5], s[92:93], 0, v[4:5]
	v_lshl_add_u64 v[4:5], v[4:5], 0, s[2:3]
	v_lshl_add_u64 v[4:5], v[4:5], 0, v[146:147]
	v_lshlrev_b32_e32 v11, 16, v7
	v_and_b32_e32 v7, 0xffff0000, v7
	v_mul_f32_e32 v3, v10, v3
	v_add_co_u32_e32 v4, vcc, 0x11300000, v4
	v_mul_f32_e32 v6, v9, v6
	v_mul_f32_e32 v3, v3, v7
	v_addc_co_u32_e32 v5, vcc, 0, v5, vcc
	v_mul_f32_e32 v6, v6, v11
	v_cvt_pk_bf16_f32 v3, v6, v3
	global_store_dwordx4 v[4:5], v[0:3], off offset:2048
	s_barrier
	s_cbranch_scc1 .LBB0_796

; __device__ __forceinline__ unsigned cvtpk(float lo, float hi) { unsigned r; asm volatile("v_cvt_pk_bf16_f32 %0, %1, %2" : "=v"(r) : "v"(lo), "v"(hi)); return r; }
; __device__ __forceinline__ int crow(int r, int hi) { return (r & 3) + 8 * (r >> 2) + 4 * hi; }
; template <int MODE, bool SAMPLE>
; __device__ __forceinline__ void attn_unit(const Params& p, char* lds, int b, int h, int qb) {
;     ...
;     if (wact && var < 1) {
;         bf16_t* MIX = (bf16_t*)(p.ws + (var == 0 ? WS_MIX : WS_ACT));
;         const size_t rbase = SAMPLE ? (size_t)(MP + b * TS) : (size_t)(b * SEQ + qb * 256 + wid * 32);
;         constexpr int NIT = SAMPLE ? 4 : 8; const int er = lane >> 4, ec = (lane & 15) * 8;
;         float rli[16];
;         if (MODE == 0) { if (hi == 0) wsc[32 + r32] = l_reg; asm volatile("s_waitcnt lgkmcnt(0)" ::: "memory");
; #pragma unroll
;             for (int r = 0; r < 16; ++r) rli[r] = __builtin_amdgcn_rcpf(wsc[32 + crow(r, hi)]); }
; #pragma unroll
;         for (int r = 0; r < 16; ++r) { const int orow = crow(r, hi);
;             if (!SAMPLE || orow < TS) {
; #pragma unroll
;                 for (int d0 = 0; d0 < 4; ++d0) { float ov = o[d0][r]; if (MODE == 0) ov *= rli[r];
;                     const unsigned pk = cvtpk(ov, 0.f); *(bf16_t*)(Qs + orow * 256 + (d0 * 32 + r32) * 2) = (bf16_t)(pk & 0xffffu); } } }
.LBB0_778:
	s_waitcnt vmcnt(0)
	s_setprio 0
	s_and_saveexec_b64 s[16:17], s[12:13]
	ds_write_b32 v149, v214 offset:128
	s_or_b64 exec, exec, s[16:17]
	s_waitcnt lgkmcnt(0)
	v_add_u32_e32 v72, s10, v137
	ds_read_b128 v[64:67], v72 offset:128
	ds_read_b128 v[68:71], v72 offset:160
	s_ashr_i32 s2, s8, 31
	v_mov_b32_e32 v147, v129
	v_mov_b32_e32 v149, v129
	s_waitcnt lgkmcnt(1)
	v_rcp_f32_e32 v73, v64
	v_rcp_f32_e32 v74, v65
	v_rcp_f32_e32 v75, v66
	v_rcp_f32_e32 v76, v67
	v_mul_f32_e32 v16, v16, v73
	s_waitcnt lgkmcnt(0)
	v_rcp_f32_e32 v77, v68
	ds_read_b128 v[64:67], v72 offset:192
	v_rcp_f32_e32 v78, v69
	v_rcp_f32_e32 v79, v70
	v_rcp_f32_e32 v80, v71
	ds_read_b128 v[68:71], v72 offset:224
	v_add3_u32 v72, s24, v191, v192
	v_cvt_pk_bf16_f32 v16, v16, v129
	ds_write_b16 v72, v16
	v_mul_f32_e32 v16, v48, v73
	v_cvt_pk_bf16_f32 v16, v16, v129
	ds_write_b16 v72, v16 offset:64
	v_mul_f32_e32 v16, v32, v73
	v_mul_f32_e32 v0, v0, v73
	v_cvt_pk_bf16_f32 v16, v16, v129
	ds_write_b16 v72, v16 offset:128
	v_cvt_pk_bf16_f32 v0, v0, v129
	ds_write_b16 v72, v0 offset:192
	v_mul_f32_e32 v0, v17, v74
	v_cvt_pk_bf16_f32 v0, v0, v129
	ds_write_b16 v72, v0 offset:256
	v_mul_f32_e32 v0, v49, v74
	v_cvt_pk_bf16_f32 v0, v0, v129
	ds_write_b16 v72, v0 offset:320
	v_mul_f32_e32 v0, v33, v74
	v_cvt_pk_bf16_f32 v0, v0, v129
	ds_write_b16 v72, v0 offset:384
	v_mul_f32_e32 v0, v1, v74
	v_cvt_pk_bf16_f32 v0, v0, v129
	ds_write_b16 v72, v0 offset:448
	v_mul_f32_e32 v0, v18, v75
	v_cvt_pk_bf16_f32 v0, v0, v129
	ds_write_b16 v72, v0 offset:512
	v_mul_f32_e32 v0, v50, v75
	v_cvt_pk_bf16_f32 v0, v0, v129
	ds_write_b16 v72, v0 offset:576
	v_mul_f32_e32 v0, v34, v75
	v_cvt_pk_bf16_f32 v0, v0, v129
	ds_write_b16 v72, v0 offset:640
	v_mul_f32_e32 v0, v2, v75
	v_cvt_pk_bf16_f32 v0, v0, v129
	ds_write_b16 v72, v0 offset:704
	v_mul_f32_e32 v0, v19, v76
	v_cvt_pk_bf16_f32 v0, v0, v129
	ds_write_b16 v72, v0 offset:768
	v_mul_f32_e32 v0, v51, v76
	v_cvt_pk_bf16_f32 v0, v0, v129
	ds_write_b16 v72, v0 offset:832
	v_mul_f32_e32 v0, v35, v76
	v_cvt_pk_bf16_f32 v0, v0, v129
	ds_write_b16 v72, v0 offset:896
	v_mul_f32_e32 v0, v3, v76
	v_cvt_pk_bf16_f32 v0, v0, v129
	ds_write_b16 v72, v0 offset:960
	v_mul_f32_e32 v0, v20, v77
	v_cvt_pk_bf16_f32 v0, v0, v129
	ds_write_b16 v72, v0 offset:2048
	v_mul_f32_e32 v0, v52, v77
	v_cvt_pk_bf16_f32 v0, v0, v129
	ds_write_b16 v72, v0 offset:2112
	v_mul_f32_e32 v0, v36, v77
	v_cvt_pk_bf16_f32 v0, v0, v129
	ds_write_b16 v72, v0 offset:2176
	v_mul_f32_e32 v0, v4, v77
	v_cvt_pk_bf16_f32 v0, v0, v129
	ds_write_b16 v72, v0 offset:2240
	v_mul_f32_e32 v0, v21, v78
	v_cvt_pk_bf16_f32 v0, v0, v129
	ds_write_b16 v72, v0 offset:2304
	v_mul_f32_e32 v0, v53, v78
	v_cvt_pk_bf16_f32 v0, v0, v129
	ds_write_b16 v72, v0 offset:2368
	v_mul_f32_e32 v0, v37, v78
	v_cvt_pk_bf16_f32 v0, v0, v129
	ds_write_b16 v72, v0 offset:2432
	v_mul_f32_e32 v0, v5, v78
	v_cvt_pk_bf16_f32 v0, v0, v129
	ds_write_b16 v72, v0 offset:2496
	v_mul_f32_e32 v0, v22, v79
	v_cvt_pk_bf16_f32 v0, v0, v129
	ds_write_b16 v72, v0 offset:2560
	v_mul_f32_e32 v0, v54, v79
	v_cvt_pk_bf16_f32 v0, v0, v129
	ds_write_b16 v72, v0 offset:2624
	v_mul_f32_e32 v0, v38, v79
	v_cvt_pk_bf16_f32 v0, v0, v129
	ds_write_b16 v72, v0 offset:2688
	v_mul_f32_e32 v0, v6, v79
	v_cvt_pk_bf16_f32 v0, v0, v129
	ds_write_b16 v72, v0 offset:2752
	v_mul_f32_e32 v0, v23, v80
	v_cvt_pk_bf16_f32 v0, v0, v129
	ds_write_b16 v72, v0 offset:2816
	v_mul_f32_e32 v0, v55, v80
	v_cvt_pk_bf16_f32 v0, v0, v129
	s_waitcnt lgkmcnt(14)
	v_rcp_f32_e32 v64, v64
	ds_write_b16 v72, v0 offset:2880
	v_mul_f32_e32 v0, v39, v80
	v_cvt_pk_bf16_f32 v0, v0, v129
	ds_write_b16 v72, v0 offset:2944
	v_mul_f32_e32 v0, v7, v80
	v_cvt_pk_bf16_f32 v0, v0, v129
	ds_write_b16 v72, v0 offset:3008
	v_mul_f32_e32 v0, v24, v64
	v_cvt_pk_bf16_f32 v0, v0, v129
	ds_write_b16 v72, v0 offset:4096
	v_mul_f32_e32 v0, v56, v64
	v_cvt_pk_bf16_f32 v0, v0, v129
	v_rcp_f32_e32 v65, v65
	ds_write_b16 v72, v0 offset:4160
	v_mul_f32_e32 v0, v40, v64
	v_cvt_pk_bf16_f32 v0, v0, v129
	ds_write_b16 v72, v0 offset:4224
	v_mul_f32_e32 v0, v8, v64
	v_cvt_pk_bf16_f32 v0, v0, v129
	ds_write_b16 v72, v0 offset:4288
	v_mul_f32_e32 v0, v25, v65
	v_cvt_pk_bf16_f32 v0, v0, v129
	ds_write_b16 v72, v0 offset:4352
	v_mul_f32_e32 v0, v57, v65
	v_cvt_pk_bf16_f32 v0, v0, v129
	v_rcp_f32_e32 v66, v66
	ds_write_b16 v72, v0 offset:4416
	v_mul_f32_e32 v0, v41, v65
	v_cvt_pk_bf16_f32 v0, v0, v129
	ds_write_b16 v72, v0 offset:4480
	v_mul_f32_e32 v0, v9, v65
	v_cvt_pk_bf16_f32 v0, v0, v129
	ds_write_b16 v72, v0 offset:4544
	v_mul_f32_e32 v0, v26, v66
	v_cvt_pk_bf16_f32 v0, v0, v129
	ds_write_b16 v72, v0 offset:4608
	v_mul_f32_e32 v0, v58, v66
	v_cvt_pk_bf16_f32 v0, v0, v129
	v_rcp_f32_e32 v67, v67
	ds_write_b16 v72, v0 offset:4672
	v_mul_f32_e32 v0, v42, v66
	v_cvt_pk_bf16_f32 v0, v0, v129
	ds_write_b16 v72, v0 offset:4736
	v_mul_f32_e32 v0, v10, v66
	v_cvt_pk_bf16_f32 v0, v0, v129
	ds_write_b16 v72, v0 offset:4800
	v_mul_f32_e32 v0, v27, v67
	v_cvt_pk_bf16_f32 v0, v0, v129
	ds_write_b16 v72, v0 offset:4864
	v_mul_f32_e32 v0, v59, v67
	v_cvt_pk_bf16_f32 v0, v0, v129
	v_rcp_f32_e32 v68, v68
	ds_write_b16 v72, v0 offset:4928
	v_mul_f32_e32 v0, v43, v67
	v_cvt_pk_bf16_f32 v0, v0, v129
	ds_write_b16 v72, v0 offset:4992
	v_mul_f32_e32 v0, v11, v67
	v_cvt_pk_bf16_f32 v0, v0, v129
	ds_write_b16 v72, v0 offset:5056
	v_mul_f32_e32 v0, v28, v68
	v_cvt_pk_bf16_f32 v0, v0, v129
	ds_write_b16 v72, v0 offset:6144
	v_mul_f32_e32 v0, v60, v68
	v_cvt_pk_bf16_f32 v0, v0, v129
	v_rcp_f32_e32 v69, v69
	ds_write_b16 v72, v0 offset:6208
	v_mul_f32_e32 v0, v44, v68
	v_cvt_pk_bf16_f32 v0, v0, v129
	ds_write_b16 v72, v0 offset:6272
; __device__ __forceinline__ unsigned cvtpk(float lo, float hi) { unsigned r; asm volatile("v_cvt_pk_bf16_f32 %0, %1, %2" : "=v"(r) : "v"(lo), "v"(hi)); return r; }
; __device__ __forceinline__ float bf2f(short s) { return __uint_as_float(((unsigned)(unsigned short)s) << 16); }
; __device__ __forceinline__ float silu_fast(float g) { return g * __builtin_amdgcn_rcpf(1.f + __builtin_amdgcn_exp2f(-g * LOG2E)); }
; __device__ __forceinline__ int crow(int r, int hi) { return (r & 3) + 8 * (r >> 2) + 4 * hi; }
; __device__ __forceinline__ bf16x8 tobf8(f32x8 x) { u32x4 w = {cvtpk(x[0], x[1]), cvtpk(x[2], x[3]), cvtpk(x[4], x[5]), cvtpk(x[6], x[7])}; return *reinterpret_cast<bf16x8*>(&w); }
; template <int MODE, bool SAMPLE>
; __device__ __forceinline__ void attn_unit(const Params& p, char* lds, int b, int h, int qb) {
;     ...
;         for (int r = 0; r < 16; ++r) { const int orow = crow(r, hi);
;             if (!SAMPLE || orow < TS) {
; #pragma unroll
;                 for (int d0 = 0; d0 < 4; ++d0) { float ov = o[d0][r]; if (MODE == 0) ov *= rli[r];
;                     const unsigned pk = cvtpk(ov, 0.f); *(bf16_t*)(Qs + orow * 256 + (d0 * 32 + r32) * 2) = (bf16_t)(pk & 0xffffu); } } }
;         asm volatile("s_waitcnt lgkmcnt(0)" ::: "memory");
;         bf16x8 gt[NIT];
; #pragma unroll
;         for (int it = 0; it < NIT; ++it) gt[it] = __builtin_nontemporal_load((const bf16x8*)(P1q + 24 * HB + (rbase + it * 4 + er) * 128 + ec));
; #pragma unroll
;         for (int it = 0; it < NIT; ++it) { const int row = it * 4 + er; const bf16x8 mx = *(const bf16x8*)(Qs + row * 256 + ec * 2); f32x8 y;
; #pragma unroll
;             for (int i = 0; i < 8; ++i) y[i] = bf2f(mx[i]) * silu_fast(bf2f(gt[it][i]));
;             *(bf16x8*)(MIX + (rbase + row) * DM + MODE * 1024 + h * HD + ec) = tobf8(y); }
	v_mul_f32_e32 v0, v12, v68
	v_cvt_pk_bf16_f32 v0, v0, v129
	ds_write_b16 v72, v0 offset:6336
	v_mul_f32_e32 v0, v29, v69
	v_cvt_pk_bf16_f32 v0, v0, v129
	ds_write_b16 v72, v0 offset:6400
	v_mul_f32_e32 v0, v61, v69
	v_cvt_pk_bf16_f32 v0, v0, v129
	v_rcp_f32_e32 v70, v70
	ds_write_b16 v72, v0 offset:6464
	v_mul_f32_e32 v0, v45, v69
	v_cvt_pk_bf16_f32 v0, v0, v129
	ds_write_b16 v72, v0 offset:6528
	v_mul_f32_e32 v0, v13, v69
	v_cvt_pk_bf16_f32 v0, v0, v129
	ds_write_b16 v72, v0 offset:6592
	v_mul_f32_e32 v0, v30, v70
	v_cvt_pk_bf16_f32 v0, v0, v129
	ds_write_b16 v72, v0 offset:6656
	v_mul_f32_e32 v0, v62, v70
	v_cvt_pk_bf16_f32 v0, v0, v129
	v_rcp_f32_e32 v71, v71
	ds_write_b16 v72, v0 offset:6720
	v_mul_f32_e32 v0, v46, v70
	v_cvt_pk_bf16_f32 v0, v0, v129
	ds_write_b16 v72, v0 offset:6784
	v_mul_f32_e32 v0, v14, v70
	v_cvt_pk_bf16_f32 v0, v0, v129
	ds_write_b16 v72, v0 offset:6848
	v_mul_f32_e32 v0, v31, v71
	v_cvt_pk_bf16_f32 v0, v0, v129
	ds_write_b16 v72, v0 offset:6912
	v_mul_f32_e32 v0, v63, v71
	v_cvt_pk_bf16_f32 v0, v0, v129
	ds_write_b16 v72, v0 offset:6976
	v_mul_f32_e32 v0, v47, v71
	v_cvt_pk_bf16_f32 v0, v0, v129
	ds_write_b16 v72, v0 offset:7040
	v_mul_f32_e32 v0, v15, v71
	v_cvt_pk_bf16_f32 v0, v0, v129
	ds_write_b16 v72, v0 offset:7104
	v_lshl_add_u64 v[0:1], s[0:1], 0, v[146:147]
	s_mov_b64 s[0:1], 0x3300000
	v_mov_b32_e32 v51, s2
	v_or_b32_e32 v50, s8, v132
	v_lshl_add_u64 v[4:5], v[0:1], 0, s[0:1]
	v_lshlrev_b64 v[0:1], 8, v[50:51]
	s_waitcnt lgkmcnt(0)
	v_lshl_add_u64 v[0:1], v[4:5], 0, v[0:1]
	global_load_dwordx4 v[0:3], v[0:1], off nt
	v_mov_b32_e32 v35, s2
	v_or_b32_e32 v34, s8, v138
	v_lshlrev_b64 v[6:7], 8, v[34:35]
	v_lshl_add_u64 v[8:9], v[4:5], 0, v[6:7]
	global_load_dwordx4 v[38:41], v[8:9], off nt
	v_mov_b32_e32 v33, s2
	v_or_b32_e32 v32, s8, v140
	v_lshlrev_b64 v[6:7], 8, v[32:33]
	v_mov_b32_e32 v31, s2
	v_or_b32_e32 v30, s8, v142
	v_lshl_add_u64 v[10:11], v[4:5], 0, v[6:7]
	v_lshlrev_b64 v[6:7], 8, v[30:31]
	v_mov_b32_e32 v29, s2
	v_or_b32_e32 v28, s8, v150
	v_lshl_add_u64 v[12:13], v[4:5], 0, v[6:7]
	v_lshlrev_b64 v[6:7], 8, v[28:29]
	v_mov_b32_e32 v27, s2
	v_or_b32_e32 v26, s8, v152
	v_lshl_add_u64 v[14:15], v[4:5], 0, v[6:7]
	v_lshlrev_b64 v[6:7], 8, v[26:27]
	v_mov_b32_e32 v25, s2
	v_or_b32_e32 v24, s8, v154
	v_lshl_add_u64 v[46:47], v[4:5], 0, v[6:7]
	v_lshlrev_b64 v[6:7], 8, v[24:25]
	v_mov_b32_e32 v21, s2
	v_or_b32_e32 v20, s8, v156
	v_lshl_add_u64 v[48:49], v[4:5], 0, v[6:7]
	v_lshlrev_b64 v[6:7], 8, v[20:21]
	v_add_u32_e32 v36, s24, v134
	v_lshl_add_u64 v[52:53], v[4:5], 0, v[6:7]
	v_add_u32_e32 v4, v36, v193
	ds_read_b128 v[4:7], v4
	s_lshl_b32 s2, s9, 8
	v_lshl_add_u64 v[22:23], v[144:145], 0, s[2:3]
	v_lshlrev_b64 v[50:51], 12, v[50:51]
	v_lshl_add_u64 v[50:51], v[22:23], 0, v[50:51]
	s_waitcnt lgkmcnt(0)
	v_lshlrev_b32_e32 v17, 16, v4
	v_and_b32_e32 v4, 0xffff0000, v4
	v_lshlrev_b64 v[34:35], 12, v[34:35]
	v_lshl_add_u64 v[34:35], v[22:23], 0, v[34:35]
	v_lshlrev_b64 v[32:33], 12, v[32:33]
	v_lshl_add_u64 v[32:33], v[22:23], 0, v[32:33]
	v_lshlrev_b64 v[30:31], 12, v[30:31]
	v_lshl_add_u64 v[30:31], v[22:23], 0, v[30:31]
	v_readfirstlane_b32 s0, v183
	s_lshl_b32 s8, s9, 7
	s_sub_i32 s2, 7, s22
	s_lshr_b32 s10, s0, 6
	s_add_u32 s82, s92, s23
	s_addc_u32 s83, s93, 0
	s_lshl_b32 s15, s2, 8
	s_lshl_b32 s0, s10, 5
	s_add_i32 s18, s0, s15
	s_add_i32 s9, s18, s20
	s_mov_b32 s0, 0xcf00000
	s_lshr_b32 s11, s18, 6
	v_mov_b32_e32 v159, v129
	s_waitcnt vmcnt(1)
	v_lshlrev_b32_e32 v8, 16, v0
	v_and_b32_e32 v0, 0xffff0000, v0
	v_mul_f32_e32 v16, 0xbfb8aa3b, v0
	v_exp_f32_e32 v16, v16
	v_mul_f32_e32 v9, 0xbfb8aa3b, v8
	v_exp_f32_e32 v9, v9
	v_add_f32_e32 v16, 1.0, v16
	v_rcp_f32_e32 v16, v16
	v_add_f32_e32 v9, 1.0, v9
	v_rcp_f32_e32 v9, v9
	v_mul_f32_e32 v0, v16, v0
	v_mul_f32_e32 v54, v0, v4
	v_lshlrev_b32_e32 v0, 16, v1
	v_mul_f32_e32 v8, v9, v8
	v_mul_f32_e32 v4, 0xbfb8aa3b, v0
	v_and_b32_e32 v1, 0xffff0000, v1
	v_mul_f32_e32 v37, v8, v17
	v_exp_f32_e32 v4, v4
	v_mul_f32_e32 v8, 0xbfb8aa3b, v1
	v_exp_f32_e32 v8, v8
	v_lshlrev_b32_e32 v9, 16, v5
	v_add_f32_e32 v4, 1.0, v4
	v_rcp_f32_e32 v4, v4
	v_add_f32_e32 v8, 1.0, v8
	v_rcp_f32_e32 v8, v8
	v_mul_f32_e32 v0, v4, v0
	v_mul_f32_e32 v55, v0, v9
	v_and_b32_e32 v0, 0xffff0000, v5
	v_mul_f32_e32 v1, v8, v1
	v_mul_f32_e32 v56, v1, v0
	v_lshlrev_b32_e32 v0, 16, v2
	v_mul_f32_e32 v1, 0xbfb8aa3b, v0
	v_and_b32_e32 v2, 0xffff0000, v2
	v_exp_f32_e32 v1, v1
	v_mul_f32_e32 v4, 0xbfb8aa3b, v2
	v_exp_f32_e32 v4, v4
	v_lshlrev_b32_e32 v5, 16, v6
	v_add_f32_e32 v1, 1.0, v1
	v_rcp_f32_e32 v1, v1
	v_add_f32_e32 v4, 1.0, v4
	v_rcp_f32_e32 v4, v4
	v_mul_f32_e32 v0, v1, v0
	v_mul_f32_e32 v57, v0, v5
	v_and_b32_e32 v0, 0xffff0000, v6
	v_mul_f32_e32 v1, v4, v2
	v_mul_f32_e32 v58, v1, v0
	v_lshlrev_b32_e32 v0, 16, v3
	v_mul_f32_e32 v1, 0xbfb8aa3b, v0
	v_and_b32_e32 v2, 0xffff0000, v3
	v_exp_f32_e32 v1, v1
	v_mul_f32_e32 v3, 0xbfb8aa3b, v2
	v_exp_f32_e32 v3, v3
	v_lshlrev_b32_e32 v4, 16, v7
	v_add_f32_e32 v1, 1.0, v1
	v_rcp_f32_e32 v1, v1
	v_add_f32_e32 v3, 1.0, v3
	v_rcp_f32_e32 v3, v3
	v_mul_f32_e32 v0, v1, v0
	v_mul_f32_e32 v59, v0, v4
	v_and_b32_e32 v0, 0xffff0000, v7
	v_mul_f32_e32 v1, v3, v2
	v_mul_f32_e32 v60, v1, v0
	global_load_dwordx4 v[42:45], v[10:11], off nt
	global_load_dwordx4 v[16:19], v[12:13], off nt
	s_nop 0
	global_load_dwordx4 v[12:15], v[14:15], off nt
	s_nop 0
	global_load_dwordx4 v[8:11], v[46:47], off nt
	global_load_dwordx4 v[4:7], v[48:49], off nt
	global_load_dwordx4 v[0:3], v[52:53], off nt
	v_cvt_pk_bf16_f32 v46, v37, v54
	v_cvt_pk_bf16_f32 v47, v55, v56
	v_cvt_pk_bf16_f32 v48, v57, v58
	v_cvt_pk_bf16_f32 v49, v59, v60
	v_add_u32_e32 v37, v36, v194
	global_store_dwordx4 v[50:51], v[46:49], off
	ds_read_b128 v[46:49], v37
	s_waitcnt vmcnt(7)
; __device__ __forceinline__ float bf2f(short s) { return __uint_as_float(((unsigned)(unsigned short)s) << 16); }
; __device__ __forceinline__ float silu_fast(float g) { return g * __builtin_amdgcn_rcpf(1.f + __builtin_amdgcn_exp2f(-g * LOG2E)); }
; __device__ __forceinline__ bf16x8 tobf8(f32x8 x) { u32x4 w = {cvtpk(x[0], x[1]), cvtpk(x[2], x[3]), cvtpk(x[4], x[5]), cvtpk(x[6], x[7])}; return *reinterpret_cast<bf16x8*>(&w); }
; template <int MODE, bool SAMPLE>
; __device__ __forceinline__ void attn_unit(const Params& p, char* lds, int b, int h, int qb) {
;     ...
;         for (int it = 0; it < NIT; ++it) { const int row = it * 4 + er; const bf16x8 mx = *(const bf16x8*)(Qs + row * 256 + ec * 2); f32x8 y;
; #pragma unroll
;             for (int i = 0; i < 8; ++i) y[i] = bf2f(mx[i]) * silu_fast(bf2f(gt[it][i]));
;             *(bf16x8*)(MIX + (rbase + row) * DM + MODE * 1024 + h * HD + ec) = tobf8(y); }
	v_lshlrev_b32_e32 v37, 16, v38
	v_and_b32_e32 v38, 0xffff0000, v38
	v_mul_f32_e32 v51, 0xbfb8aa3b, v38
	v_exp_f32_e32 v51, v51
	v_mul_f32_e32 v50, 0xbfb8aa3b, v37
	v_exp_f32_e32 v50, v50
	s_waitcnt lgkmcnt(0)
	v_lshlrev_b32_e32 v52, 16, v46
	v_add_f32_e32 v51, 1.0, v51
	v_rcp_f32_e32 v51, v51
	v_and_b32_e32 v46, 0xffff0000, v46
	v_add_f32_e32 v50, 1.0, v50
	v_rcp_f32_e32 v50, v50
	v_mul_f32_e32 v38, v51, v38
	v_mul_f32_e32 v38, v38, v46
	v_lshlrev_b32_e32 v46, 16, v39
	v_and_b32_e32 v39, 0xffff0000, v39
	v_mul_f32_e32 v51, 0xbfb8aa3b, v39
	v_exp_f32_e32 v51, v51
	v_mul_f32_e32 v37, v50, v37
	v_mul_f32_e32 v50, 0xbfb8aa3b, v46
	v_exp_f32_e32 v50, v50
	v_add_f32_e32 v51, 1.0, v51
	v_rcp_f32_e32 v51, v51
	v_mul_f32_e32 v37, v37, v52
	v_add_f32_e32 v50, 1.0, v50
	v_lshlrev_b32_e32 v52, 16, v47
	v_and_b32_e32 v47, 0xffff0000, v47
	v_mul_f32_e32 v39, v51, v39
	v_rcp_f32_e32 v50, v50
	v_mul_f32_e32 v39, v39, v47
	v_lshlrev_b32_e32 v47, 16, v40
	v_and_b32_e32 v40, 0xffff0000, v40
	v_mul_f32_e32 v51, 0xbfb8aa3b, v40
	v_exp_f32_e32 v51, v51
	v_mul_f32_e32 v46, v50, v46
	v_mul_f32_e32 v50, 0xbfb8aa3b, v47
	v_exp_f32_e32 v50, v50
	v_add_f32_e32 v51, 1.0, v51
	v_rcp_f32_e32 v51, v51
	v_mul_f32_e32 v46, v46, v52
	v_add_f32_e32 v50, 1.0, v50
	v_rcp_f32_e32 v50, v50
	v_lshlrev_b32_e32 v52, 16, v48
	v_and_b32_e32 v48, 0xffff0000, v48
	v_mul_f32_e32 v40, v51, v40
	v_mul_f32_e32 v40, v40, v48
	v_lshlrev_b32_e32 v48, 16, v41
	v_and_b32_e32 v41, 0xffff0000, v41
	v_mul_f32_e32 v51, 0xbfb8aa3b, v41
	v_mul_f32_e32 v47, v50, v47
	v_mul_f32_e32 v50, 0xbfb8aa3b, v48
	v_exp_f32_e32 v51, v51
	v_exp_f32_e32 v50, v50
	v_mul_f32_e32 v47, v47, v52
	v_lshlrev_b32_e32 v52, 16, v49
	v_add_f32_e32 v51, 1.0, v51
	v_add_f32_e32 v50, 1.0, v50
	v_rcp_f32_e32 v51, v51
	v_rcp_f32_e32 v50, v50
	v_and_b32_e32 v49, 0xffff0000, v49
	v_cvt_pk_bf16_f32 v38, v37, v38
	v_mul_f32_e32 v41, v51, v41
	v_mul_f32_e32 v48, v50, v48
	v_mul_f32_e32 v41, v41, v49
	v_mul_f32_e32 v48, v48, v52
	v_cvt_pk_bf16_f32 v39, v46, v39
	v_cvt_pk_bf16_f32 v40, v47, v40
	v_cvt_pk_bf16_f32 v41, v48, v41
	global_store_dwordx4 v[34:35], v[38:41], off
	v_add_u32_e32 v34, v36, v195
	ds_read_b128 v[38:41], v34
	s_waitcnt vmcnt(7)
	v_lshlrev_b32_e32 v34, 16, v42
	v_and_b32_e32 v37, 0xffff0000, v42
	v_mul_f32_e32 v35, 0xbfb8aa3b, v34
	v_mul_f32_e32 v42, 0xbfb8aa3b, v37
	v_exp_f32_e32 v35, v35
	v_exp_f32_e32 v42, v42
	s_waitcnt lgkmcnt(0)
	v_lshlrev_b32_e32 v46, 16, v38
	v_add_f32_e32 v35, 1.0, v35
	v_add_f32_e32 v42, 1.0, v42
	v_rcp_f32_e32 v35, v35
	v_rcp_f32_e32 v42, v42
	v_mul_f32_e32 v34, v35, v34
	v_and_b32_e32 v35, 0xffff0000, v38
	v_mul_f32_e32 v37, v42, v37
	v_mul_f32_e32 v35, v37, v35
	v_lshlrev_b32_e32 v37, 16, v43
	v_and_b32_e32 v42, 0xffff0000, v43
	v_mul_f32_e32 v38, 0xbfb8aa3b, v37
	v_mul_f32_e32 v43, 0xbfb8aa3b, v42
	v_exp_f32_e32 v38, v38
	v_exp_f32_e32 v43, v43
	v_mul_f32_e32 v34, v34, v46
	v_lshlrev_b32_e32 v46, 16, v39
	v_add_f32_e32 v38, 1.0, v38
	v_add_f32_e32 v43, 1.0, v43
	v_rcp_f32_e32 v38, v38
	v_rcp_f32_e32 v43, v43
	v_mul_f32_e32 v37, v38, v37
	v_and_b32_e32 v38, 0xffff0000, v39
	v_mul_f32_e32 v39, v43, v42
	v_mul_f32_e32 v39, v39, v38
	v_lshlrev_b32_e32 v38, 16, v44
	v_mul_f32_e32 v42, 0xbfb8aa3b, v38
	v_and_b32_e32 v43, 0xffff0000, v44
	v_exp_f32_e32 v42, v42
	v_mul_f32_e32 v44, 0xbfb8aa3b, v43
	v_exp_f32_e32 v44, v44
	v_mul_f32_e32 v37, v37, v46
	v_add_f32_e32 v42, 1.0, v42
	v_rcp_f32_e32 v42, v42
	v_add_f32_e32 v44, 1.0, v44
	v_rcp_f32_e32 v44, v44
	v_lshlrev_b32_e32 v46, 16, v40
	v_mul_f32_e32 v38, v42, v38
	v_mul_f32_e32 v42, v38, v46
	v_and_b32_e32 v38, 0xffff0000, v40
	v_mul_f32_e32 v40, v44, v43
	v_mul_f32_e32 v40, v40, v38
	v_lshlrev_b32_e32 v38, 16, v45
	v_mul_f32_e32 v43, 0xbfb8aa3b, v38
	v_and_b32_e32 v44, 0xffff0000, v45
	v_exp_f32_e32 v43, v43
	v_mul_f32_e32 v45, 0xbfb8aa3b, v44
	v_exp_f32_e32 v45, v45
	v_lshlrev_b32_e32 v46, 16, v41
	v_add_f32_e32 v43, 1.0, v43
	v_rcp_f32_e32 v43, v43
	v_add_f32_e32 v45, 1.0, v45
	v_rcp_f32_e32 v45, v45
	v_mul_f32_e32 v38, v43, v38
	v_mul_f32_e32 v43, v38, v46
	v_and_b32_e32 v38, 0xffff0000, v41
	v_mul_f32_e32 v41, v45, v44
	v_mul_f32_e32 v41, v41, v38
	v_cvt_pk_bf16_f32 v38, v34, v35
	v_cvt_pk_bf16_f32 v39, v37, v39
	s_waitcnt vmcnt(6)
	v_lshlrev_b32_e32 v37, 16, v16
	v_and_b32_e32 v16, 0xffff0000, v16
	v_cvt_pk_bf16_f32 v40, v42, v40
	v_cvt_pk_bf16_f32 v41, v43, v41
	global_store_dwordx4 v[32:33], v[38:41], off
	v_add_u32_e32 v32, v36, v196
	ds_read_b128 v[32:35], v32
	v_mul_f32_e32 v39, 0xbfb8aa3b, v16
	v_exp_f32_e32 v39, v39
	v_mul_f32_e32 v38, 0xbfb8aa3b, v37
	v_exp_f32_e32 v38, v38
	s_waitcnt lgkmcnt(0)
	v_lshlrev_b32_e32 v40, 16, v32
	v_add_f32_e32 v39, 1.0, v39
	v_rcp_f32_e32 v39, v39
	v_and_b32_e32 v32, 0xffff0000, v32
	v_add_f32_e32 v38, 1.0, v38
	v_rcp_f32_e32 v38, v38
	v_mul_f32_e32 v16, v39, v16
	v_mul_f32_e32 v16, v16, v32
	v_lshlrev_b32_e32 v32, 16, v17
	v_and_b32_e32 v17, 0xffff0000, v17
	v_mul_f32_e32 v39, 0xbfb8aa3b, v17
	v_exp_f32_e32 v39, v39
	v_mul_f32_e32 v37, v38, v37
	v_mul_f32_e32 v38, 0xbfb8aa3b, v32
	v_exp_f32_e32 v38, v38
	v_add_f32_e32 v39, 1.0, v39
	v_rcp_f32_e32 v39, v39
	v_mul_f32_e32 v37, v37, v40
	v_add_f32_e32 v38, 1.0, v38
	v_lshlrev_b32_e32 v40, 16, v33
	v_and_b32_e32 v33, 0xffff0000, v33
	v_mul_f32_e32 v17, v39, v17
	v_rcp_f32_e32 v38, v38
	v_mul_f32_e32 v17, v17, v33
	v_lshlrev_b32_e32 v33, 16, v18
	v_and_b32_e32 v18, 0xffff0000, v18
	v_mul_f32_e32 v39, 0xbfb8aa3b, v18
	v_exp_f32_e32 v39, v39
	v_mul_f32_e32 v32, v38, v32
	v_mul_f32_e32 v38, 0xbfb8aa3b, v33
	v_exp_f32_e32 v38, v38
	v_add_f32_e32 v39, 1.0, v39
	v_rcp_f32_e32 v39, v39
	v_mul_f32_e32 v32, v32, v40
	v_add_f32_e32 v38, 1.0, v38
	v_rcp_f32_e32 v38, v38
	v_lshlrev_b32_e32 v40, 16, v34
	v_and_b32_e32 v34, 0xffff0000, v34
	v_mul_f32_e32 v18, v39, v18
	v_mul_f32_e32 v18, v18, v34
	v_lshlrev_b32_e32 v34, 16, v19
	v_and_b32_e32 v19, 0xffff0000, v19
	v_mul_f32_e32 v39, 0xbfb8aa3b, v19
	v_mul_f32_e32 v33, v38, v33
	v_mul_f32_e32 v38, 0xbfb8aa3b, v34
	v_exp_f32_e32 v39, v39
	v_exp_f32_e32 v38, v38
	v_mul_f32_e32 v33, v33, v40
	v_lshlrev_b32_e32 v40, 16, v35
	v_add_f32_e32 v39, 1.0, v39
	v_add_f32_e32 v38, 1.0, v38
	v_rcp_f32_e32 v39, v39
	v_rcp_f32_e32 v38, v38
	v_and_b32_e32 v35, 0xffff0000, v35
	v_cvt_pk_bf16_f32 v16, v37, v16
	v_mul_f32_e32 v19, v39, v19
	v_mul_f32_e32 v34, v38, v34
	v_mul_f32_e32 v19, v19, v35
	v_mul_f32_e32 v34, v34, v40
	v_cvt_pk_bf16_f32 v17, v32, v17
	v_cvt_pk_bf16_f32 v18, v33, v18
	v_cvt_pk_bf16_f32 v19, v34, v19
	global_store_dwordx4 v[30:31], v[16:19], off
	s_waitcnt vmcnt(7)
; __device__ __forceinline__ float bf2f(short s) { return __uint_as_float(((unsigned)(unsigned short)s) << 16); }
; __device__ __forceinline__ float silu_fast(float g) { return g * __builtin_amdgcn_rcpf(1.f + __builtin_amdgcn_exp2f(-g * LOG2E)); }
; __device__ __forceinline__ bf16x8 tobf8(f32x8 x) { u32x4 w = {cvtpk(x[0], x[1]), cvtpk(x[2], x[3]), cvtpk(x[4], x[5]), cvtpk(x[6], x[7])}; return *reinterpret_cast<bf16x8*>(&w); }
; template <int MODE, bool SAMPLE>
; __device__ __forceinline__ void attn_unit(const Params& p, char* lds, int b, int h, int qb) {
;     ...
;         for (int it = 0; it < NIT; ++it) { const int row = it * 4 + er; const bf16x8 mx = *(const bf16x8*)(Qs + row * 256 + ec * 2); f32x8 y;
; #pragma unroll
;             for (int i = 0; i < 8; ++i) y[i] = bf2f(mx[i]) * silu_fast(bf2f(gt[it][i]));
;             *(bf16x8*)(MIX + (rbase + row) * DM + MODE * 1024 + h * HD + ec) = tobf8(y); }
	v_lshlrev_b32_e32 v30, 16, v12
	v_and_b32_e32 v12, 0xffff0000, v12
	v_mul_f32_e32 v32, 0xbfb8aa3b, v12
	v_exp_f32_e32 v32, v32
	v_add_u32_e32 v16, v36, v208
	ds_read_b128 v[16:19], v16
	v_mul_f32_e32 v31, 0xbfb8aa3b, v30
	v_add_f32_e32 v32, 1.0, v32
	v_rcp_f32_e32 v32, v32
	v_exp_f32_e32 v31, v31
	s_waitcnt lgkmcnt(0)
	v_lshlrev_b32_e32 v33, 16, v16
	v_and_b32_e32 v16, 0xffff0000, v16
	v_mul_f32_e32 v12, v32, v12
	v_mul_f32_e32 v12, v12, v16
	v_lshlrev_b32_e32 v16, 16, v13
	v_and_b32_e32 v13, 0xffff0000, v13
	v_add_f32_e32 v31, 1.0, v31
	v_mul_f32_e32 v32, 0xbfb8aa3b, v13
	v_rcp_f32_e32 v31, v31
	v_exp_f32_e32 v32, v32
	v_mul_f32_e32 v30, v31, v30
	v_mul_f32_e32 v31, 0xbfb8aa3b, v16
	v_add_f32_e32 v32, 1.0, v32
	v_exp_f32_e32 v31, v31
	v_rcp_f32_e32 v32, v32
	v_mul_f32_e32 v30, v30, v33
	v_lshlrev_b32_e32 v33, 16, v17
	v_add_f32_e32 v31, 1.0, v31
	v_and_b32_e32 v17, 0xffff0000, v17
	v_mul_f32_e32 v13, v32, v13
	v_rcp_f32_e32 v31, v31
	v_mul_f32_e32 v13, v13, v17
	v_lshlrev_b32_e32 v17, 16, v14
	v_and_b32_e32 v14, 0xffff0000, v14
	v_mul_f32_e32 v32, 0xbfb8aa3b, v14
	v_exp_f32_e32 v32, v32
	v_mul_f32_e32 v16, v31, v16
	v_mul_f32_e32 v31, 0xbfb8aa3b, v17
	v_exp_f32_e32 v31, v31
	v_add_f32_e32 v32, 1.0, v32
	v_rcp_f32_e32 v32, v32
	v_mul_f32_e32 v16, v16, v33
	v_add_f32_e32 v31, 1.0, v31
	v_rcp_f32_e32 v31, v31
	v_lshlrev_b32_e32 v33, 16, v18
	v_and_b32_e32 v18, 0xffff0000, v18
	v_mul_f32_e32 v14, v32, v14
	v_mul_f32_e32 v14, v14, v18
	v_lshlrev_b32_e32 v18, 16, v15
	v_and_b32_e32 v15, 0xffff0000, v15
	v_mul_f32_e32 v32, 0xbfb8aa3b, v15
	v_mul_f32_e32 v17, v31, v17
	v_mul_f32_e32 v31, 0xbfb8aa3b, v18
	v_exp_f32_e32 v32, v32
	v_exp_f32_e32 v31, v31
	v_mul_f32_e32 v17, v17, v33
	v_lshlrev_b32_e32 v33, 16, v19
	v_add_f32_e32 v32, 1.0, v32
	v_add_f32_e32 v31, 1.0, v31
	v_rcp_f32_e32 v32, v32
	v_rcp_f32_e32 v31, v31
	v_and_b32_e32 v19, 0xffff0000, v19
	v_cvt_pk_bf16_f32 v12, v30, v12
	v_mul_f32_e32 v15, v32, v15
	v_cvt_pk_bf16_f32 v13, v16, v13
	v_cvt_pk_bf16_f32 v14, v17, v14
	v_lshlrev_b64 v[16:17], 12, v[28:29]
	v_mul_f32_e32 v18, v31, v18
	v_mul_f32_e32 v15, v15, v19
	v_lshl_add_u64 v[16:17], v[22:23], 0, v[16:17]
	v_mul_f32_e32 v18, v18, v33
	v_cvt_pk_bf16_f32 v15, v18, v15
	global_store_dwordx4 v[16:17], v[12:15], off
	s_waitcnt vmcnt(7)
	v_lshlrev_b32_e32 v16, 16, v8
	v_and_b32_e32 v8, 0xffff0000, v8
	v_mul_f32_e32 v18, 0xbfb8aa3b, v8
	v_exp_f32_e32 v18, v18
	v_add_u32_e32 v12, v36, v209
	ds_read_b128 v[12:15], v12
	v_mul_f32_e32 v17, 0xbfb8aa3b, v16
	v_add_f32_e32 v18, 1.0, v18
	v_rcp_f32_e32 v18, v18
	v_exp_f32_e32 v17, v17
	s_waitcnt lgkmcnt(0)
	v_lshlrev_b32_e32 v19, 16, v12
	v_and_b32_e32 v12, 0xffff0000, v12
	v_mul_f32_e32 v8, v18, v8
	v_mul_f32_e32 v8, v8, v12
	v_lshlrev_b32_e32 v12, 16, v9
	v_and_b32_e32 v9, 0xffff0000, v9
	v_add_f32_e32 v17, 1.0, v17
	v_mul_f32_e32 v18, 0xbfb8aa3b, v9
	v_rcp_f32_e32 v17, v17
	v_exp_f32_e32 v18, v18
	v_mul_f32_e32 v16, v17, v16
	v_mul_f32_e32 v17, 0xbfb8aa3b, v12
	v_add_f32_e32 v18, 1.0, v18
	v_exp_f32_e32 v17, v17
	v_rcp_f32_e32 v18, v18
	v_mul_f32_e32 v16, v16, v19
	v_lshlrev_b32_e32 v19, 16, v13
	v_add_f32_e32 v17, 1.0, v17
	v_and_b32_e32 v13, 0xffff0000, v13
	v_mul_f32_e32 v9, v18, v9
	v_rcp_f32_e32 v17, v17
	v_mul_f32_e32 v9, v9, v13
	v_lshlrev_b32_e32 v13, 16, v10
	v_and_b32_e32 v10, 0xffff0000, v10
	v_mul_f32_e32 v18, 0xbfb8aa3b, v10
	v_exp_f32_e32 v18, v18
	v_mul_f32_e32 v12, v17, v12
	v_mul_f32_e32 v17, 0xbfb8aa3b, v13
	v_exp_f32_e32 v17, v17
	v_add_f32_e32 v18, 1.0, v18
	v_rcp_f32_e32 v18, v18
	v_mul_f32_e32 v12, v12, v19
	v_add_f32_e32 v17, 1.0, v17
	v_rcp_f32_e32 v17, v17
	v_lshlrev_b32_e32 v19, 16, v14
	v_and_b32_e32 v14, 0xffff0000, v14
	v_mul_f32_e32 v10, v18, v10
	v_mul_f32_e32 v10, v10, v14
	v_lshlrev_b32_e32 v14, 16, v11
	v_and_b32_e32 v11, 0xffff0000, v11
	v_mul_f32_e32 v18, 0xbfb8aa3b, v11
	v_mul_f32_e32 v13, v17, v13
	v_mul_f32_e32 v17, 0xbfb8aa3b, v14
	v_exp_f32_e32 v18, v18
	v_exp_f32_e32 v17, v17
	v_mul_f32_e32 v13, v13, v19
	v_lshlrev_b32_e32 v19, 16, v15
	v_add_f32_e32 v18, 1.0, v18
	v_add_f32_e32 v17, 1.0, v17
	v_rcp_f32_e32 v18, v18
	v_rcp_f32_e32 v17, v17
	v_and_b32_e32 v15, 0xffff0000, v15
	v_cvt_pk_bf16_f32 v8, v16, v8
	v_mul_f32_e32 v11, v18, v11
	v_cvt_pk_bf16_f32 v9, v12, v9
	v_cvt_pk_bf16_f32 v10, v13, v10
	v_lshlrev_b64 v[12:13], 12, v[26:27]
	v_mul_f32_e32 v14, v17, v14
	v_mul_f32_e32 v11, v11, v15
	v_lshl_add_u64 v[12:13], v[22:23], 0, v[12:13]
	v_mul_f32_e32 v14, v14, v19
	v_cvt_pk_bf16_f32 v11, v14, v11
	global_store_dwordx4 v[12:13], v[8:11], off
	s_waitcnt vmcnt(7)
	v_lshlrev_b32_e32 v12, 16, v4
	v_and_b32_e32 v4, 0xffff0000, v4
	v_mul_f32_e32 v14, 0xbfb8aa3b, v4
	v_exp_f32_e32 v14, v14
	v_add_u32_e32 v8, v36, v210
	ds_read_b128 v[8:11], v8
	v_mul_f32_e32 v13, 0xbfb8aa3b, v12
	v_add_f32_e32 v14, 1.0, v14
	v_rcp_f32_e32 v14, v14
	v_exp_f32_e32 v13, v13
	s_waitcnt lgkmcnt(0)
; __device__ __forceinline__ float bf2f(short s) { return __uint_as_float(((unsigned)(unsigned short)s) << 16); }
; __device__ __forceinline__ float silu_fast(float g) { return g * __builtin_amdgcn_rcpf(1.f + __builtin_amdgcn_exp2f(-g * LOG2E)); }
; __device__ __forceinline__ bf16x8 tobf8(f32x8 x) { u32x4 w = {cvtpk(x[0], x[1]), cvtpk(x[2], x[3]), cvtpk(x[4], x[5]), cvtpk(x[6], x[7])}; return *reinterpret_cast<bf16x8*>(&w); }
; template <int MODE, bool SAMPLE>
; __device__ __forceinline__ void attn_unit(const Params& p, char* lds, int b, int h, int qb) {
;     ...
;         for (int it = 0; it < NIT; ++it) { const int row = it * 4 + er; const bf16x8 mx = *(const bf16x8*)(Qs + row * 256 + ec * 2); f32x8 y;
; #pragma unroll
;             for (int i = 0; i < 8; ++i) y[i] = bf2f(mx[i]) * silu_fast(bf2f(gt[it][i]));
;             *(bf16x8*)(MIX + (rbase + row) * DM + MODE * 1024 + h * HD + ec) = tobf8(y); }
;     }
;     __syncthreads();
	v_lshlrev_b32_e32 v15, 16, v8
	v_and_b32_e32 v8, 0xffff0000, v8
	v_mul_f32_e32 v4, v14, v4
	v_mul_f32_e32 v4, v4, v8
	v_lshlrev_b32_e32 v8, 16, v5
	v_and_b32_e32 v5, 0xffff0000, v5
	v_add_f32_e32 v13, 1.0, v13
	v_mul_f32_e32 v14, 0xbfb8aa3b, v5
	v_rcp_f32_e32 v13, v13
	v_exp_f32_e32 v14, v14
	v_mul_f32_e32 v12, v13, v12
	v_mul_f32_e32 v13, 0xbfb8aa3b, v8
	v_add_f32_e32 v14, 1.0, v14
	v_exp_f32_e32 v13, v13
	v_rcp_f32_e32 v14, v14
	v_mul_f32_e32 v12, v12, v15
	v_lshlrev_b32_e32 v15, 16, v9
	v_add_f32_e32 v13, 1.0, v13
	v_and_b32_e32 v9, 0xffff0000, v9
	v_mul_f32_e32 v5, v14, v5
	v_rcp_f32_e32 v13, v13
	v_mul_f32_e32 v5, v5, v9
	v_lshlrev_b32_e32 v9, 16, v6
	v_and_b32_e32 v6, 0xffff0000, v6
	v_mul_f32_e32 v14, 0xbfb8aa3b, v6
	v_exp_f32_e32 v14, v14
	v_mul_f32_e32 v8, v13, v8
	v_mul_f32_e32 v13, 0xbfb8aa3b, v9
	v_exp_f32_e32 v13, v13
	v_add_f32_e32 v14, 1.0, v14
	v_rcp_f32_e32 v14, v14
	v_mul_f32_e32 v8, v8, v15
	v_add_f32_e32 v13, 1.0, v13
	v_rcp_f32_e32 v13, v13
	v_lshlrev_b32_e32 v15, 16, v10
	v_and_b32_e32 v10, 0xffff0000, v10
	v_mul_f32_e32 v6, v14, v6
	v_mul_f32_e32 v6, v6, v10
	v_lshlrev_b32_e32 v10, 16, v7
	v_and_b32_e32 v7, 0xffff0000, v7
	v_mul_f32_e32 v14, 0xbfb8aa3b, v7
	v_mul_f32_e32 v9, v13, v9
	v_mul_f32_e32 v13, 0xbfb8aa3b, v10
	v_exp_f32_e32 v14, v14
	v_exp_f32_e32 v13, v13
	v_mul_f32_e32 v9, v9, v15
	v_lshlrev_b32_e32 v15, 16, v11
	v_add_f32_e32 v14, 1.0, v14
	v_add_f32_e32 v13, 1.0, v13
	v_rcp_f32_e32 v14, v14
	v_rcp_f32_e32 v13, v13
	v_and_b32_e32 v11, 0xffff0000, v11
	v_cvt_pk_bf16_f32 v4, v12, v4
	v_mul_f32_e32 v7, v14, v7
	v_cvt_pk_bf16_f32 v5, v8, v5
	v_cvt_pk_bf16_f32 v6, v9, v6
	v_lshlrev_b64 v[8:9], 12, v[24:25]
	v_mul_f32_e32 v10, v13, v10
	v_mul_f32_e32 v7, v7, v11
	v_lshl_add_u64 v[8:9], v[22:23], 0, v[8:9]
	v_mul_f32_e32 v10, v10, v15
	v_cvt_pk_bf16_f32 v7, v10, v7
	global_store_dwordx4 v[8:9], v[4:7], off
	s_waitcnt vmcnt(7)
	v_lshlrev_b32_e32 v8, 16, v0
	v_and_b32_e32 v0, 0xffff0000, v0
	v_mul_f32_e32 v10, 0xbfb8aa3b, v0
	v_exp_f32_e32 v10, v10
	v_add_u32_e32 v4, v36, v211
	ds_read_b128 v[4:7], v4
	v_mul_f32_e32 v9, 0xbfb8aa3b, v8
	v_add_f32_e32 v10, 1.0, v10
	v_rcp_f32_e32 v10, v10
	v_exp_f32_e32 v9, v9
	s_waitcnt lgkmcnt(0)
	v_lshlrev_b32_e32 v11, 16, v4
	v_and_b32_e32 v4, 0xffff0000, v4
	v_mul_f32_e32 v0, v10, v0
	v_mul_f32_e32 v0, v0, v4
	v_lshlrev_b32_e32 v4, 16, v1
	v_and_b32_e32 v1, 0xffff0000, v1
	v_add_f32_e32 v9, 1.0, v9
	v_mul_f32_e32 v10, 0xbfb8aa3b, v1
	v_rcp_f32_e32 v9, v9
	v_exp_f32_e32 v10, v10
	v_mul_f32_e32 v8, v9, v8
	v_mul_f32_e32 v9, 0xbfb8aa3b, v4
	v_add_f32_e32 v10, 1.0, v10
	v_exp_f32_e32 v9, v9
	v_rcp_f32_e32 v10, v10
	v_mul_f32_e32 v8, v8, v11
	v_lshlrev_b32_e32 v11, 16, v5
	v_add_f32_e32 v9, 1.0, v9
	v_and_b32_e32 v5, 0xffff0000, v5
	v_mul_f32_e32 v1, v10, v1
	v_rcp_f32_e32 v9, v9
	v_mul_f32_e32 v1, v1, v5
	v_lshlrev_b32_e32 v5, 16, v2
	v_and_b32_e32 v2, 0xffff0000, v2
	v_mul_f32_e32 v10, 0xbfb8aa3b, v2
	v_exp_f32_e32 v10, v10
	v_mul_f32_e32 v4, v9, v4
	v_mul_f32_e32 v9, 0xbfb8aa3b, v5
	v_exp_f32_e32 v9, v9
	v_add_f32_e32 v10, 1.0, v10
	v_rcp_f32_e32 v10, v10
	v_mul_f32_e32 v4, v4, v11
	v_add_f32_e32 v9, 1.0, v9
	v_rcp_f32_e32 v9, v9
	v_lshlrev_b32_e32 v11, 16, v6
	v_and_b32_e32 v6, 0xffff0000, v6
	v_mul_f32_e32 v2, v10, v2
	v_mul_f32_e32 v2, v2, v6
	v_lshlrev_b32_e32 v6, 16, v3
	v_and_b32_e32 v3, 0xffff0000, v3
	v_mul_f32_e32 v10, 0xbfb8aa3b, v3
	v_mul_f32_e32 v5, v9, v5
	v_mul_f32_e32 v9, 0xbfb8aa3b, v6
	v_exp_f32_e32 v10, v10
	v_exp_f32_e32 v9, v9
	v_mul_f32_e32 v5, v5, v11
	v_lshlrev_b32_e32 v11, 16, v7
	v_add_f32_e32 v10, 1.0, v10
	v_add_f32_e32 v9, 1.0, v9
	v_rcp_f32_e32 v10, v10
	v_rcp_f32_e32 v9, v9
	v_and_b32_e32 v7, 0xffff0000, v7
	v_cvt_pk_bf16_f32 v0, v8, v0
	v_mul_f32_e32 v3, v10, v3
	v_cvt_pk_bf16_f32 v1, v4, v1
	v_cvt_pk_bf16_f32 v2, v5, v2
	v_lshlrev_b64 v[4:5], 12, v[20:21]
	v_mul_f32_e32 v6, v9, v6
	v_mul_f32_e32 v3, v3, v7
	v_lshl_add_u64 v[4:5], v[22:23], 0, v[4:5]
	v_mul_f32_e32 v6, v6, v11
	v_cvt_pk_bf16_f32 v3, v6, v3
	global_store_dwordx4 v[4:5], v[0:3], off
	s_barrier
; __device__ __forceinline__ int crow(int r, int hi) { return (r & 3) + 8 * (r >> 2) + 4 * hi; }
; __device__ __forceinline__ int v_st(int k, int c) { const int kk = (k & ~0xC) | ((k & 4) << 1) | ((k & 8) >> 1); return ((kk >> 3) * 4 + (c >> 5)) * 512 + ((kk & 7) * 32 + (c & 31)) * 2; }
; __device__ __forceinline__ int v_rd_base(int lane) { return ((lane & 3) << 3) | (((lane >> 2) & 3) << 6) | (((lane >> 4) & 1) << 5) | (((lane >> 5) & 1) << 8); }
; template <int MODE, bool SAMPLE>
; __device__ __forceinline__ void attn_unit(const Params& p, char* lds, int b, int h, int qb) {
;     ...
;     const bf16_t* P1q = P1 + (size_t)((MODE ? 32 : 0) + h) * HB;
;     const size_t qrow = SAMPLE ? (size_t)(MP + b * TS + (r32 & 15)) : (size_t)(b * SEQ + qb * 256 + wid * 32 + r32);
;     const bf16_t* Qw = P1q + qrow * 128 + hi * 8;
;     char* Qs = lds + AL_Q + wid * 8192;
; #pragma unroll
;     for (int d0 = 0; d0 < 8; ++d0) *reinterpret_cast<bf16x8*>(Qs + KSWZ(r32, (d0 * 16 + hi * 8) * 2)) = *reinterpret_cast<const bf16x8*>(Qw + d0 * 16);
;     const int qw0 = SAMPLE ? PAST : qb * 256 + wid * 32;
;     const int qpos = SAMPLE ? PAST + (r32 & 15) : qw0 + r32;
;     const int jd = SAMPLE ? 16 : (qw0 >> 6);
;     const int jfirst = SAMPLE ? 16 : qb * 4 + 3;
;     const bool wact = SAMPLE ? (wid == 0) : true;
;     const int sr = tid >> 4, sc = (tid & 15) * 8;
;     const int vst0 = v_st(sr, sc), vst1 = v_st(32 + sr, sc), kst0 = KSWZ(sr, sc * 2), kst1 = KSWZ(32 + sr, sc * 2);
;     const int vb0 = (int)(uintptr_t)V_lds + v_rd_base(lane);
;     struct StgT { bf16x8 k0, k1, v0, v1; f32x8 fk0, fk1, fv0, fv1; } stg2[SAMPLE ? 1 : NSP];
;     ...
;     f32x16 o[4] = {};
;     float m_reg = -1e30f, l_reg = 0.f, carry = 1.f;
;     constexpr int NS = SAMPLE ? 1 : NSP;
;     constexpr int PAR0 = SAMPLE ? 0 : 1;
;     LOADT(jfirst, stg2[NS == 2 ? PAR0 : 0]); if (NS == 2) LOADT(jfirst - 1, stg2[NS == 2 ? (PAR0 ^ 1) : 0]);
;     ...
;                 p0 = f32x16{}; p1 = f32x16{};
;                 qkt(p0, p1, Kt, Qs, r32, hi);
;                 if (j == jd) {
; #pragma unroll
;                     for (int r = 0; r < 16; ++r) { const int kp = j * 64 + crow(r, hi); if (kp >= qpos) p0[r] = -1e30f; if (kp + 32 >= qpos) p1[r] = -1e30f; } }
	s_nop 0
	v_or_b32_e32 v0, s9, v131
	v_mov_b32_e32 v1, v129
	v_lshlrev_b64 v[0:1], 8, v[0:1]
	v_lshl_add_u64 v[0:1], s[82:83], 0, v[0:1]
	v_lshl_add_u64 v[4:5], v[0:1], 0, v[148:149]
	v_add_co_u32_e32 v0, vcc, s0, v4
	s_nop 1
	v_addc_co_u32_e32 v1, vcc, 0, v5, vcc
	global_load_dwordx4 v[0:3], v[0:1], off
	s_mov_b64 s[0:1], 0xcf00000
	v_lshl_add_u64 v[28:29], v[4:5], 0, s[0:1]
	global_load_dwordx4 v[4:7], v[28:29], off offset:32
	global_load_dwordx4 v[8:11], v[28:29], off offset:64
	global_load_dwordx4 v[12:15], v[28:29], off offset:96
	global_load_dwordx4 v[16:19], v[28:29], off offset:128
	global_load_dwordx4 v[20:23], v[28:29], off offset:160
	global_load_dwordx4 v[24:27], v[28:29], off offset:192
	s_nop 0
	global_load_dwordx4 v[28:31], v[28:29], off offset:224
	s_lshl_b32 s0, s10, 13
	s_add_i32 s10, s0, 0
	s_add_i32 s10, s10, 0x13000
	v_add_u32_e32 v32, s10, v133
	v_add_u32_e32 v33, v32, v139
	s_lshl_b32 s0, s2, 2
	s_or_b32 s14, s0, 3
	s_add_u32 s0, s82, 0xe000000
	s_addc_u32 s1, s83, 0
	s_lshl_b32 s2, s14, 6
	s_add_i32 s2, s2, s20
	s_lshl_b64 s[16:17], s[2:3], 8
	s_add_u32 s16, s0, s16
	s_addc_u32 s17, s1, s17
	s_add_i32 s2, s21, s15
	v_lshl_add_u64 v[160:161], s[0:1], 0, v[146:147]
	s_waitcnt vmcnt(7)
	ds_write_b128 v33, v[0:3]
	v_add_u32_e32 v0, v32, v141
	s_waitcnt vmcnt(6)
	ds_write_b128 v0, v[4:7]
	v_add_u32_e32 v0, v32, v143
	s_waitcnt vmcnt(5)
	ds_write_b128 v0, v[8:11]
	v_add_u32_e32 v0, v32, v151
	s_waitcnt vmcnt(4)
	ds_write_b128 v0, v[12:15]
	v_add_u32_e32 v0, v32, v153
	s_waitcnt vmcnt(3)
	ds_write_b128 v0, v[16:19]
	v_add_u32_e32 v0, v32, v170
	s_waitcnt vmcnt(2)
	ds_write_b128 v0, v[20:23]
	v_add_u32_e32 v0, v32, v171
	s_waitcnt vmcnt(1)
	ds_write_b128 v0, v[24:27]
	v_add_u32_e32 v0, v32, v172
	s_waitcnt vmcnt(0)
	ds_write_b128 v0, v[28:31]
	v_lshl_add_u64 v[0:1], s[16:17], 0, v[146:147]
	s_lshl_b64 s[16:17], s[2:3], 8
	v_lshl_add_u64 v[2:3], v[0:1], 0, v[128:129]
	v_lshl_add_u64 v[4:5], v[0:1], 0, v[158:159]
	v_lshl_add_u64 v[0:1], v[0:1], 0, s[86:87]
	s_add_u32 s16, s0, s16
	global_load_dwordx4 v[96:99], v[2:3], off
	global_load_dwordx4 v[100:103], v[4:5], off
	v_lshl_add_u64 v[2:3], v[0:1], 0, v[128:129]
	v_lshl_add_u64 v[0:1], v[0:1], 0, v[158:159]
	s_addc_u32 s17, s1, s17
	global_load_dwordx4 v[104:107], v[2:3], off
	global_load_dwordx4 v[108:111], v[0:1], off
	v_lshl_add_u64 v[0:1], s[16:17], 0, v[146:147]
	v_lshl_add_u64 v[2:3], v[0:1], 0, v[128:129]
	v_lshl_add_u64 v[4:5], v[0:1], 0, v[158:159]
	v_lshl_add_u64 v[0:1], v[0:1], 0, s[86:87]
	global_load_dwordx4 v[112:115], v[2:3], off
	global_load_dwordx4 v[116:119], v[4:5], off
	v_lshl_add_u64 v[2:3], v[0:1], 0, v[128:129]
	v_lshl_add_u64 v[0:1], v[0:1], 0, v[158:159]
	global_load_dwordx4 v[120:123], v[2:3], off
	global_load_dwordx4 v[124:127], v[0:1], off
	v_or_b32_e32 v6, s18, v131
	s_andn2_b32 s18, s18, 63
	v_or_b32_e32 v0, s18, v180
	v_or_b32_e32 v1, 32, v0
	v_cmp_lt_i32_e64 s[0:1], v1, v6
	v_or_b32_e32 v1, 1, v0
	v_cmp_lt_i32_e64 s[16:17], v1, v6
	v_or_b32_e32 v1, 33, v0
	v_cmp_lt_i32_e64 s[18:19], v1, v6
	v_or_b32_e32 v1, 2, v0
	v_cmp_lt_i32_e64 s[20:21], v1, v6
	v_or_b32_e32 v1, 34, v0
	v_cmp_lt_i32_e64 s[22:23], v1, v6
	v_or_b32_e32 v1, 3, v0
	v_cmp_lt_i32_e64 s[24:25], v1, v6
	v_or_b32_e32 v1, 35, v0
	v_cmp_lt_i32_e64 s[26:27], v1, v6
	v_or_b32_e32 v1, 8, v0
	v_cmp_lt_i32_e64 s[28:29], v1, v6
	v_or_b32_e32 v1, 40, v0
	v_cmp_lt_i32_e64 s[30:31], v1, v6
	v_or_b32_e32 v1, 9, v0
	v_cmp_lt_i32_e64 s[34:35], v1, v6
	v_or_b32_e32 v1, 41, v0
	v_cmp_lt_i32_e64 s[36:37], v1, v6
	v_or_b32_e32 v1, 10, v0
	v_cmp_lt_i32_e64 s[38:39], v1, v6
	v_or_b32_e32 v1, 42, v0
	v_cmp_lt_i32_e64 s[40:41], v1, v6
	v_or_b32_e32 v1, 11, v0
	v_cmp_lt_i32_e64 s[42:43], v1, v6
	v_or_b32_e32 v1, 43, v0
	v_cmp_lt_i32_e64 s[44:45], v1, v6
	v_or_b32_e32 v1, 16, v0
	v_cmp_lt_i32_e64 s[46:47], v1, v6
	v_or_b32_e32 v1, 48, v0
	v_cmp_lt_i32_e64 s[48:49], v1, v6
	v_or_b32_e32 v1, 17, v0
	v_cmp_lt_i32_e64 s[50:51], v1, v6
	v_or_b32_e32 v1, 49, v0
	v_cmp_lt_i32_e64 s[52:53], v1, v6
	v_or_b32_e32 v1, 18, v0
	v_cmp_lt_i32_e64 s[54:55], v1, v6
	v_or_b32_e32 v1, 50, v0
	v_cmp_lt_i32_e64 s[56:57], v1, v6
	v_or_b32_e32 v1, 19, v0
	v_cmp_lt_i32_e64 s[58:59], v1, v6
	v_or_b32_e32 v1, 51, v0
	v_cmp_lt_i32_e64 s[60:61], v1, v6
	v_or_b32_e32 v1, 24, v0
	v_cmp_lt_i32_e64 s[62:63], v1, v6
	v_or_b32_e32 v1, 56, v0
	v_cmp_lt_i32_e64 s[64:65], v1, v6
	v_or_b32_e32 v1, 25, v0
	v_cmp_lt_i32_e64 s[66:67], v1, v6
	v_or_b32_e32 v1, 57, v0
	v_cmp_lt_i32_e64 s[68:69], v1, v6
	v_or_b32_e32 v1, 26, v0
	s_lshr_b32 s2, s14, 1
	v_cmp_lt_i32_e64 s[70:71], v1, v6
	v_or_b32_e32 v1, 58, v0
	v_cmp_lt_i32_e32 vcc, v0, v6
	v_cmp_lt_i32_e64 s[72:73], v1, v6
	v_or_b32_e32 v1, 27, v0
	v_or_b32_e32 v0, 59, v0
	s_lshl_b32 s15, s2, 7
	v_mov_b32_e32 v14, v129
	v_mov_b32_e32 v15, v129
	v_cmp_lt_i32_e64 s[74:75], v1, v6
	v_cmp_lt_i32_e64 s[76:77], v0, v6
	s_add_i32 s15, s33, s15
	v_mov_b32_e32 v0, v129
	v_mov_b32_e32 v1, v129
	v_mov_b32_e32 v2, v129
	v_mov_b32_e32 v3, v129
	v_mov_b32_e32 v4, v129
	v_mov_b32_e32 v5, v129
	v_mov_b32_e32 v6, v129
	v_mov_b32_e32 v7, v129
	v_mov_b32_e32 v8, v129
	v_mov_b32_e32 v9, v129
	v_mov_b32_e32 v10, v129
	v_mov_b32_e32 v11, v129
	v_mov_b32_e32 v12, v129
	v_mov_b32_e32 v13, v129
	v_mov_b64_e32 v[30:31], v[14:15]
	v_mov_b64_e32 v[46:47], v[14:15]
	v_mov_b64_e32 v[62:63], v[14:15]
	s_add_i32 s80, s15, 0xffffff80
	s_sub_i32 s15, 0, s2
	s_and_b32 s33, s14, 0x7ffffffe
	s_add_i32 s97, s11, -1
	v_mov_b32_e32 v147, 1.0
	v_mov_b64_e32 v[28:29], v[12:13]
	v_mov_b64_e32 v[26:27], v[10:11]
	v_mov_b64_e32 v[24:25], v[8:9]
	v_mov_b64_e32 v[22:23], v[6:7]
	v_mov_b64_e32 v[20:21], v[4:5]
	v_mov_b64_e32 v[18:19], v[2:3]
	v_mov_b64_e32 v[16:17], v[0:1]
	v_mov_b64_e32 v[44:45], v[12:13]
	v_mov_b64_e32 v[42:43], v[10:11]
	v_mov_b64_e32 v[40:41], v[8:9]
	v_mov_b64_e32 v[38:39], v[6:7]
	v_mov_b64_e32 v[36:37], v[4:5]
	v_mov_b64_e32 v[34:35], v[2:3]
	v_mov_b64_e32 v[32:33], v[0:1]
	v_mov_b64_e32 v[60:61], v[12:13]
	v_mov_b64_e32 v[58:59], v[10:11]
	v_mov_b64_e32 v[56:57], v[8:9]
	v_mov_b64_e32 v[54:55], v[6:7]
	v_mov_b64_e32 v[52:53], v[4:5]
	v_mov_b64_e32 v[50:51], v[2:3]
	v_mov_b64_e32 v[48:49], v[0:1]
	s_branch .LBB0_783
